# GEMM K-loops: one static priority raise for waves 4-7 instead of per-cluster setprio toggles; P8 prologue wait removed
# speedup vs baseline: 1.0072x; 1.0072x over previous
.LBB0_242:
	s_add_i32 m0, s26, 0x18000
	v_lshl_add_u64 v[2:3], v[2:3], 0, s[30:31]
	s_waitcnt vmcnt(4)
	s_barrier
	global_load_lds_dwordx4 v[2:3], off
	v_lshl_add_u64 v[2:3], v[4:5], 0, s[30:31]
	s_add_i32 m0, s26, 0x1a000
	s_add_i32 s44, s26, 0x8000
	global_load_lds_dwordx4 v[2:3], off
	v_lshl_add_u64 v[2:3], v[8:9], 0, s[30:31]
	s_mov_b32 m0, s44
	s_add_i32 s45, s26, 0xa000
	global_load_lds_dwordx4 v[2:3], off
	v_lshl_add_u64 v[2:3], v[6:7], 0, s[30:31]
	s_mov_b32 m0, s45
	v_bfe_u32 v173, v15, 4, 2
	global_load_lds_dwordx4 v[2:3], off
	v_lshl_add_u64 v[2:3], v[144:145], 0, s[34:35]
	s_add_i32 m0, s26, 0x1c000
	v_lshl_add_u64 v[4:5], v[2:3], 0, v[132:133]
	global_load_lds_dwordx4 v[4:5], off
	v_lshl_add_u64 v[2:3], v[2:3], 0, v[142:143]
	s_add_i32 m0, s26, 0x1e000
	s_lshl_b32 s4, s4, 5
	global_load_lds_dwordx4 v[2:3], off
	v_lshlrev_b32_e32 v2, 14, v10
	v_and_b32_e32 v2, 0xffff8000, v2
	v_lshl_add_u32 v2, v11, 11, v2
	v_and_b32_e32 v3, 1, v10
	v_lshl_or_b32 v2, v3, 6, v2
	v_lshl_add_u32 v2, v12, 1, v2
	v_mov_b32_e32 v3, v133
	v_lshl_add_u64 v[2:3], s[6:7], 0, v[2:3]
	v_lshl_add_u64 v[148:149], v[160:161], 0, v[2:3]
	v_lshlrev_b32_e32 v2, 14, v13
	v_and_b32_e32 v2, 0xffff8000, v2
	v_lshl_add_u32 v2, v14, 11, v2
	v_and_b32_e32 v3, 1, v13
	v_and_b32_e32 v17, 15, v15
	v_lshlrev_b32_e32 v18, 4, v173
	s_and_b32 s40, s4, 0x60
	v_lshlrev_b32_e32 v15, 2, v15
	v_lshl_or_b32 v2, v3, 6, v2
	v_lshl_or_b32 v172, s5, 6, v17
	v_lshl_or_b32 v17, v17, 6, v18
	s_lshl_b32 s4, s40, 7
	v_and_b32_e32 v15, 32, v15
	v_lshl_add_u32 v2, v16, 1, v2
	v_mov_b32_e32 v3, v133
	v_bitop3_b32 v174, v17, s4, v15 bitop3:0xde
	s_lshl_b32 s4, s5, 13
	s_waitcnt vmcnt(6)
	v_lshl_add_u64 v[2:3], s[6:7], 0, v[2:3]
	v_bitop3_b32 v15, v17, s4, v15 bitop3:0xde
	v_lshl_add_u64 v[150:151], v[160:161], 0, v[2:3]
	v_mov_b32_e32 v2, 0
	s_mov_b32 s39, s27
	s_mov_b32 s46, -2
	s_mov_b64 s[4:5], 0
	v_add_u32_e32 v175, 0, v15
	v_mov_b32_e32 v3, v2
	v_mov_b32_e32 v4, v2
	v_mov_b32_e32 v5, v2
	v_mov_b32_e32 v6, v2
	v_mov_b32_e32 v7, v2
	v_mov_b32_e32 v8, v2
	v_mov_b32_e32 v9, v2
	v_mov_b32_e32 v10, v2
	v_mov_b32_e32 v11, v2
	v_mov_b32_e32 v12, v2
	v_mov_b32_e32 v13, v2
	v_mov_b32_e32 v14, v2
	v_mov_b32_e32 v15, v2
	v_mov_b32_e32 v16, v2
	v_mov_b32_e32 v17, v2
	v_mov_b32_e32 v18, v2
	v_mov_b32_e32 v19, v2
	v_mov_b32_e32 v20, v2
	v_mov_b32_e32 v21, v2
	v_mov_b32_e32 v22, v2
	v_mov_b32_e32 v23, v2
	v_mov_b32_e32 v24, v2
	v_mov_b32_e32 v25, v2
	v_mov_b32_e32 v26, v2
	v_mov_b32_e32 v27, v2
	v_mov_b32_e32 v28, v2
	v_mov_b32_e32 v29, v2
	v_mov_b32_e32 v30, v2
	v_mov_b32_e32 v31, v2
	v_mov_b32_e32 v32, v2
	v_mov_b32_e32 v33, v2
	v_mov_b32_e32 v34, v2
	v_mov_b32_e32 v35, v2
	v_mov_b32_e32 v36, v2
	v_mov_b32_e32 v37, v2
	v_mov_b32_e32 v38, v2
	v_mov_b32_e32 v39, v2
	v_mov_b32_e32 v40, v2
	v_mov_b32_e32 v41, v2
	v_mov_b32_e32 v42, v2
	v_mov_b32_e32 v43, v2
	v_mov_b32_e32 v44, v2
	v_mov_b32_e32 v45, v2
	v_mov_b32_e32 v46, v2
	v_mov_b32_e32 v47, v2
	v_mov_b32_e32 v48, v2
	v_mov_b32_e32 v49, v2
	v_mov_b32_e32 v50, v2
	v_mov_b32_e32 v51, v2
	v_mov_b32_e32 v52, v2
	v_mov_b32_e32 v53, v2
	v_mov_b32_e32 v54, v2
	v_mov_b32_e32 v55, v2
	v_mov_b32_e32 v56, v2
	v_mov_b32_e32 v57, v2
	v_mov_b32_e32 v58, v2
	v_mov_b32_e32 v59, v2
	v_mov_b32_e32 v60, v2
	v_mov_b32_e32 v61, v2
	v_mov_b32_e32 v62, v2
	v_mov_b32_e32 v63, v2
	v_mov_b32_e32 v64, v2
	v_mov_b32_e32 v65, v2
	v_mov_b32_e32 v66, v2
	v_mov_b32_e32 v67, v2
	v_mov_b32_e32 v68, v2
	v_mov_b32_e32 v69, v2
	v_mov_b32_e32 v70, v2
	v_mov_b32_e32 v71, v2
	v_mov_b32_e32 v72, v2
	v_mov_b32_e32 v73, v2
	v_mov_b32_e32 v74, v2
	v_mov_b32_e32 v75, v2
	v_mov_b32_e32 v76, v2
	v_mov_b32_e32 v77, v2
	v_mov_b32_e32 v78, v2
	v_mov_b32_e32 v79, v2
	v_mov_b32_e32 v80, v2
	v_mov_b32_e32 v81, v2
	v_mov_b32_e32 v82, v2
	v_mov_b32_e32 v83, v2
	v_mov_b32_e32 v84, v2
	v_mov_b32_e32 v85, v2
	v_mov_b32_e32 v86, v2
	v_mov_b32_e32 v87, v2
	v_mov_b32_e32 v88, v2
	v_mov_b32_e32 v89, v2
	v_mov_b32_e32 v90, v2
	v_mov_b32_e32 v91, v2
	v_mov_b32_e32 v92, v2
	v_mov_b32_e32 v93, v2
	v_mov_b32_e32 v94, v2
	v_mov_b32_e32 v95, v2
	v_mov_b32_e32 v96, v2
	v_mov_b32_e32 v97, v2
	v_mov_b32_e32 v98, v2
	v_mov_b32_e32 v99, v2
	v_mov_b32_e32 v100, v2
	v_mov_b32_e32 v101, v2
	v_mov_b32_e32 v102, v2
	v_mov_b32_e32 v103, v2
	v_mov_b32_e32 v104, v2
	v_mov_b32_e32 v105, v2
	v_mov_b32_e32 v106, v2
	v_mov_b32_e32 v107, v2
	v_mov_b32_e32 v108, v2
	v_mov_b32_e32 v109, v2
	v_mov_b32_e32 v110, v2
	v_mov_b32_e32 v111, v2
	v_mov_b32_e32 v112, v2
	v_mov_b32_e32 v113, v2
	v_mov_b32_e32 v114, v2
	v_mov_b32_e32 v115, v2
	v_mov_b32_e32 v116, v2
	v_mov_b32_e32 v117, v2
	v_mov_b32_e32 v118, v2
	v_mov_b32_e32 v119, v2
	v_mov_b32_e32 v120, v2
	v_mov_b32_e32 v121, v2
	v_mov_b32_e32 v122, v2
	v_mov_b32_e32 v123, v2
	v_mov_b32_e32 v124, v2
	v_mov_b32_e32 v125, v2
	v_mov_b32_e32 v126, v2
	v_mov_b32_e32 v127, v2
	v_mov_b32_e32 v128, v2
	v_mov_b32_e32 v129, v2
	v_lshl_add_u64 v[152:153], v[154:155], 0, s[6:7]
	v_lshl_add_u64 v[168:169], v[136:137], 0, s[8:9]
	s_barrier
	v_readfirstlane_b32 s98, v0
	s_bitcmp1_b32 s98, 8
	s_cbranch_scc0 .Lkprio_0
	s_setprio 1
.Lkprio_0:
.LBB0_243:
	s_cmpk_eq_i32 s4, 0x700
	v_lshl_add_u64 v[170:171], v[152:153], 0, s[4:5]
	s_mov_b64 s[6:7], 0x4280100
	v_lshl_add_u64 v[170:171], v[170:171], 0, s[6:7]
	s_cselect_b64 vcc, -1, 0
	s_add_i32 s6, 0, 0x10000
	v_cndmask_b32_e32 v245, v171, v147, vcc
	v_add_u32_e32 v171, s6, v174
	ds_read_b128 v[176:179], v171
	ds_read_b128 v[180:183], v171 offset:1024
	ds_read_b128 v[184:187], v171 offset:2048
	ds_read_b128 v[188:191], v171 offset:3072
	v_cndmask_b32_e32 v244, v170, v146, vcc
	v_lshl_add_u64 v[170:171], v[168:169], 0, s[4:5]
	v_cndmask_b32_e32 v171, v171, v145, vcc
	v_cndmask_b32_e32 v170, v170, v144, vcc
	v_lshl_add_u64 v[228:229], v[148:149], 0, s[4:5]
	s_add_i32 m0, s26, 0xc000
	ds_read_b128 v[192:195], v175
	ds_read_b128 v[196:199], v175 offset:1024
	ds_read_b128 v[200:203], v175 offset:2048
	ds_read_b128 v[204:207], v175 offset:3072
	ds_read_b128 v[210:213], v175 offset:4096
	ds_read_b128 v[214:217], v175 offset:5120
	ds_read_b128 v[218:221], v175 offset:6144
	ds_read_b128 v[222:225], v175 offset:7168
	global_load_lds_dwordx4 v[228:229], off
	v_lshl_add_u64 v[228:229], v[150:151], 0, s[4:5]
	s_add_i32 m0, s26, 0xe000
	s_nop 0
	global_load_lds_dwordx4 v[228:229], off
	s_waitcnt lgkmcnt(8)
	s_barrier
	s_waitcnt lgkmcnt(7)
	v_mfma_f32_16x16x32_bf16 v[126:129], v[176:179], v[192:195], v[126:129]
	v_mfma_f32_16x16x32_bf16 v[122:125], v[184:187], v[192:195], v[122:125]
	s_waitcnt lgkmcnt(5)
	v_mfma_f32_16x16x32_bf16 v[118:121], v[176:179], v[200:203], v[118:121]
	v_mfma_f32_16x16x32_bf16 v[114:117], v[184:187], v[200:203], v[114:117]
	s_waitcnt lgkmcnt(3)
	v_mfma_f32_16x16x32_bf16 v[110:113], v[176:179], v[210:213], v[110:113]
	v_mfma_f32_16x16x32_bf16 v[106:109], v[184:187], v[210:213], v[106:109]
	s_waitcnt lgkmcnt(1)
	v_mfma_f32_16x16x32_bf16 v[102:105], v[176:179], v[218:221], v[102:105]
	v_mfma_f32_16x16x32_bf16 v[98:101], v[184:187], v[218:221], v[98:101]
	v_mfma_f32_16x16x32_bf16 v[126:129], v[180:183], v[196:199], v[126:129]
	v_mfma_f32_16x16x32_bf16 v[122:125], v[188:191], v[196:199], v[122:125]
	v_mfma_f32_16x16x32_bf16 v[118:121], v[180:183], v[204:207], v[118:121]
	v_mfma_f32_16x16x32_bf16 v[114:117], v[188:191], v[204:207], v[114:117]
	v_mfma_f32_16x16x32_bf16 v[110:113], v[180:183], v[214:217], v[110:113]
	v_mfma_f32_16x16x32_bf16 v[106:109], v[188:191], v[214:217], v[106:109]
	s_waitcnt lgkmcnt(0)
	v_mfma_f32_16x16x32_bf16 v[102:105], v[180:183], v[222:225], v[102:105]
	v_mfma_f32_16x16x32_bf16 v[98:101], v[188:191], v[222:225], v[98:101]
	s_barrier
	s_add_i32 s7, 0, 0x14000
	s_add_i32 s6, s6, s13
	v_add_u32_e32 v208, s7, v174
	v_lshl_add_u64 v[246:247], v[170:171], 0, v[132:133]
	s_mov_b32 m0, s6
	ds_read_b128 v[228:231], v208
	ds_read_b128 v[232:235], v208 offset:1024
	ds_read_b128 v[236:239], v208 offset:2048
	ds_read_b128 v[240:243], v208 offset:3072
	global_load_lds_dwordx4 v[246:247], off
	v_lshl_add_u64 v[248:249], v[170:171], 0, v[142:143]
	s_add_i32 m0, s6, 0x2000
	s_nop 0
	global_load_lds_dwordx4 v[248:249], off
	s_barrier
	s_waitcnt lgkmcnt(3)
	v_mfma_f32_16x16x32_bf16 v[94:97], v[228:231], v[192:195], v[94:97]
	s_waitcnt lgkmcnt(1)
	v_mfma_f32_16x16x32_bf16 v[90:93], v[236:239], v[192:195], v[90:93]
	v_mfma_f32_16x16x32_bf16 v[86:89], v[228:231], v[200:203], v[86:89]
	v_mfma_f32_16x16x32_bf16 v[82:85], v[236:239], v[200:203], v[82:85]
	v_mfma_f32_16x16x32_bf16 v[78:81], v[228:231], v[210:213], v[78:81]
	v_mfma_f32_16x16x32_bf16 v[74:77], v[236:239], v[210:213], v[74:77]
	v_mfma_f32_16x16x32_bf16 v[70:73], v[228:231], v[218:221], v[70:73]
	v_mfma_f32_16x16x32_bf16 v[66:69], v[236:239], v[218:221], v[66:69]
	v_mfma_f32_16x16x32_bf16 v[94:97], v[232:235], v[196:199], v[94:97]
	s_waitcnt lgkmcnt(0)
	v_mfma_f32_16x16x32_bf16 v[90:93], v[240:243], v[196:199], v[90:93]
	v_mfma_f32_16x16x32_bf16 v[86:89], v[232:235], v[204:207], v[86:89]
	v_mfma_f32_16x16x32_bf16 v[82:85], v[240:243], v[204:207], v[82:85]
	v_mfma_f32_16x16x32_bf16 v[78:81], v[232:235], v[214:217], v[78:81]
	v_mfma_f32_16x16x32_bf16 v[74:77], v[240:243], v[214:217], v[74:77]
	v_mfma_f32_16x16x32_bf16 v[70:73], v[232:235], v[222:225], v[70:73]
	v_mfma_f32_16x16x32_bf16 v[66:69], v[240:243], v[222:225], v[66:69]
	s_mov_b32 m0, s26
	v_lshl_add_u64 v[250:251], v[244:245], 0, v[132:133]
	s_barrier
	ds_read_b128 v[192:195], v175 offset:16384
	ds_read_b128 v[196:199], v175 offset:17408
	ds_read_b128 v[200:203], v175 offset:18432
	ds_read_b128 v[204:207], v175 offset:19456
	ds_read_b128 v[210:213], v175 offset:20480
	ds_read_b128 v[214:217], v175 offset:21504
	ds_read_b128 v[218:221], v175 offset:22528
	ds_read_b128 v[222:225], v175 offset:23552
	global_load_lds_dwordx4 v[250:251], off
	v_lshl_add_u64 v[252:253], v[244:245], 0, v[142:143]
	s_mov_b32 m0, s41
	s_nop 0
	global_load_lds_dwordx4 v[252:253], off
	s_barrier
	s_waitcnt lgkmcnt(7)
	v_mfma_f32_16x16x32_bf16 v[62:65], v[176:179], v[192:195], v[62:65]
	v_mfma_f32_16x16x32_bf16 v[58:61], v[184:187], v[192:195], v[58:61]
	s_waitcnt lgkmcnt(5)
	v_mfma_f32_16x16x32_bf16 v[54:57], v[176:179], v[200:203], v[54:57]
	v_mfma_f32_16x16x32_bf16 v[50:53], v[184:187], v[200:203], v[50:53]
	s_waitcnt lgkmcnt(3)
	v_mfma_f32_16x16x32_bf16 v[46:49], v[176:179], v[210:213], v[46:49]
	v_mfma_f32_16x16x32_bf16 v[42:45], v[184:187], v[210:213], v[42:45]
	s_waitcnt lgkmcnt(1)
	v_mfma_f32_16x16x32_bf16 v[38:41], v[176:179], v[218:221], v[38:41]
	v_mfma_f32_16x16x32_bf16 v[34:37], v[184:187], v[218:221], v[34:37]
	v_mfma_f32_16x16x32_bf16 v[62:65], v[180:183], v[196:199], v[62:65]
	v_mfma_f32_16x16x32_bf16 v[58:61], v[188:191], v[196:199], v[58:61]
	v_mfma_f32_16x16x32_bf16 v[54:57], v[180:183], v[204:207], v[54:57]
	v_mfma_f32_16x16x32_bf16 v[50:53], v[188:191], v[204:207], v[50:53]
	v_mfma_f32_16x16x32_bf16 v[46:49], v[180:183], v[214:217], v[46:49]
	v_mfma_f32_16x16x32_bf16 v[42:45], v[188:191], v[214:217], v[42:45]
	s_waitcnt lgkmcnt(0)
	v_mfma_f32_16x16x32_bf16 v[38:41], v[180:183], v[222:225], v[38:41]
	v_mfma_f32_16x16x32_bf16 v[34:37], v[188:191], v[222:225], v[34:37]
	s_barrier
	v_lshl_add_u64 v[176:177], v[170:171], 0, s[28:29]
	s_add_i32 s6, s7, s13
	v_lshl_add_u64 v[178:179], v[176:177], 0, v[132:133]
	s_mov_b32 m0, s6
	v_lshl_add_u64 v[176:177], v[176:177], 0, v[142:143]
	global_load_lds_dwordx4 v[178:179], off
	s_add_i32 m0, s6, 0x2000
	s_nop 0
	global_load_lds_dwordx4 v[176:177], off
	s_waitcnt vmcnt(6)
	s_barrier
	v_mfma_f32_16x16x32_bf16 v[30:33], v[228:231], v[192:195], v[30:33]
	v_mfma_f32_16x16x32_bf16 v[26:29], v[236:239], v[192:195], v[26:29]
	v_mfma_f32_16x16x32_bf16 v[22:25], v[228:231], v[200:203], v[22:25]
	v_mfma_f32_16x16x32_bf16 v[18:21], v[236:239], v[200:203], v[18:21]
	v_mfma_f32_16x16x32_bf16 v[14:17], v[228:231], v[210:213], v[14:17]
	v_mfma_f32_16x16x32_bf16 v[10:13], v[236:239], v[210:213], v[10:13]
	v_mfma_f32_16x16x32_bf16 v[6:9], v[228:231], v[218:221], v[6:9]
	v_mfma_f32_16x16x32_bf16 v[2:5], v[236:239], v[218:221], v[2:5]
	v_mfma_f32_16x16x32_bf16 v[30:33], v[232:235], v[196:199], v[30:33]
	v_mfma_f32_16x16x32_bf16 v[26:29], v[240:243], v[196:199], v[26:29]
	v_mfma_f32_16x16x32_bf16 v[22:25], v[232:235], v[204:207], v[22:25]
	v_mfma_f32_16x16x32_bf16 v[18:21], v[240:243], v[204:207], v[18:21]
	v_mfma_f32_16x16x32_bf16 v[14:17], v[232:235], v[214:217], v[14:17]
	v_mfma_f32_16x16x32_bf16 v[10:13], v[240:243], v[214:217], v[10:13]
	v_mfma_f32_16x16x32_bf16 v[6:9], v[232:235], v[222:225], v[6:9]
	v_mfma_f32_16x16x32_bf16 v[2:5], v[240:243], v[222:225], v[2:5]
	s_add_i32 s6, 0, 0x18000
	v_add_u32_e32 v188, s6, v174
	s_barrier
	ds_read_b128 v[176:179], v188
	ds_read_b128 v[180:183], v188 offset:1024
	ds_read_b128 v[184:187], v188 offset:2048
	ds_read_b128 v[188:191], v188 offset:3072
	v_lshl_add_u64 v[228:229], v[244:245], 0, s[28:29]
	s_mov_b32 m0, s42
	v_lshl_add_u64 v[230:231], v[228:229], 0, v[132:133]
	ds_read_b128 v[192:195], v175 offset:32768
	ds_read_b128 v[196:199], v175 offset:33792
	ds_read_b128 v[200:203], v175 offset:34816
	ds_read_b128 v[204:207], v175 offset:35840
	ds_read_b128 v[210:213], v175 offset:36864
	ds_read_b128 v[214:217], v175 offset:37888
	ds_read_b128 v[218:221], v175 offset:38912
	ds_read_b128 v[222:225], v175 offset:39936
	global_load_lds_dwordx4 v[230:231], off
	v_lshl_add_u64 v[228:229], v[228:229], 0, v[142:143]
	s_mov_b32 m0, s43
	s_nop 0
	global_load_lds_dwordx4 v[228:229], off
	s_waitcnt lgkmcnt(8)
	s_barrier
	s_waitcnt lgkmcnt(7)
	v_mfma_f32_16x16x32_bf16 v[126:129], v[176:179], v[192:195], v[126:129]
	v_mfma_f32_16x16x32_bf16 v[122:125], v[184:187], v[192:195], v[122:125]
	s_waitcnt lgkmcnt(5)
	v_mfma_f32_16x16x32_bf16 v[118:121], v[176:179], v[200:203], v[118:121]
	v_mfma_f32_16x16x32_bf16 v[114:117], v[184:187], v[200:203], v[114:117]
	s_waitcnt lgkmcnt(3)
	v_mfma_f32_16x16x32_bf16 v[110:113], v[176:179], v[210:213], v[110:113]
	v_mfma_f32_16x16x32_bf16 v[106:109], v[184:187], v[210:213], v[106:109]
	s_waitcnt lgkmcnt(1)
	v_mfma_f32_16x16x32_bf16 v[102:105], v[176:179], v[218:221], v[102:105]
	v_mfma_f32_16x16x32_bf16 v[98:101], v[184:187], v[218:221], v[98:101]
	v_mfma_f32_16x16x32_bf16 v[126:129], v[180:183], v[196:199], v[126:129]
	v_mfma_f32_16x16x32_bf16 v[122:125], v[188:191], v[196:199], v[122:125]
	v_mfma_f32_16x16x32_bf16 v[118:121], v[180:183], v[204:207], v[118:121]
	v_mfma_f32_16x16x32_bf16 v[114:117], v[188:191], v[204:207], v[114:117]
	v_mfma_f32_16x16x32_bf16 v[110:113], v[180:183], v[214:217], v[110:113]
	v_mfma_f32_16x16x32_bf16 v[106:109], v[188:191], v[214:217], v[106:109]
	s_waitcnt lgkmcnt(0)
	v_mfma_f32_16x16x32_bf16 v[102:105], v[180:183], v[222:225], v[102:105]
	v_mfma_f32_16x16x32_bf16 v[98:101], v[188:191], v[222:225], v[98:101]
	s_barrier
	s_add_i32 s7, 0, 0x1c000
	s_add_i32 s6, s6, s13
	v_add_u32_e32 v208, s7, v174
	v_lshl_add_u64 v[244:245], v[246:247], 0, s[30:31]
	s_mov_b32 m0, s6
	ds_read_b128 v[228:231], v208
	ds_read_b128 v[232:235], v208 offset:1024
	ds_read_b128 v[236:239], v208 offset:2048
	ds_read_b128 v[240:243], v208 offset:3072
	global_load_lds_dwordx4 v[244:245], off
	v_lshl_add_u64 v[244:245], v[248:249], 0, s[30:31]
	s_add_i32 m0, s6, 0x2000
	s_nop 0
	global_load_lds_dwordx4 v[244:245], off
	s_barrier
	s_waitcnt lgkmcnt(3)
	v_mfma_f32_16x16x32_bf16 v[94:97], v[228:231], v[192:195], v[94:97]
	s_waitcnt lgkmcnt(1)
	v_mfma_f32_16x16x32_bf16 v[90:93], v[236:239], v[192:195], v[90:93]
	v_mfma_f32_16x16x32_bf16 v[86:89], v[228:231], v[200:203], v[86:89]
	v_mfma_f32_16x16x32_bf16 v[82:85], v[236:239], v[200:203], v[82:85]
	v_mfma_f32_16x16x32_bf16 v[78:81], v[228:231], v[210:213], v[78:81]
	v_mfma_f32_16x16x32_bf16 v[74:77], v[236:239], v[210:213], v[74:77]
	v_mfma_f32_16x16x32_bf16 v[70:73], v[228:231], v[218:221], v[70:73]
	v_mfma_f32_16x16x32_bf16 v[66:69], v[236:239], v[218:221], v[66:69]
	v_mfma_f32_16x16x32_bf16 v[94:97], v[232:235], v[196:199], v[94:97]
	s_waitcnt lgkmcnt(0)
	v_mfma_f32_16x16x32_bf16 v[90:93], v[240:243], v[196:199], v[90:93]
	v_mfma_f32_16x16x32_bf16 v[86:89], v[232:235], v[204:207], v[86:89]
	v_mfma_f32_16x16x32_bf16 v[82:85], v[240:243], v[204:207], v[82:85]
	v_mfma_f32_16x16x32_bf16 v[78:81], v[232:235], v[214:217], v[78:81]
	v_mfma_f32_16x16x32_bf16 v[74:77], v[240:243], v[214:217], v[74:77]
	v_mfma_f32_16x16x32_bf16 v[70:73], v[232:235], v[222:225], v[70:73]
	v_mfma_f32_16x16x32_bf16 v[66:69], v[240:243], v[222:225], v[66:69]
	s_mov_b32 m0, s44
	v_lshl_add_u64 v[244:245], v[250:251], 0, s[30:31]
	s_barrier
	ds_read_b128 v[192:195], v175 offset:49152
	ds_read_b128 v[196:199], v175 offset:50176
	ds_read_b128 v[200:203], v175 offset:51200
	ds_read_b128 v[204:207], v175 offset:52224
	ds_read_b128 v[210:213], v175 offset:53248
	ds_read_b128 v[214:217], v175 offset:54272
	ds_read_b128 v[218:221], v175 offset:55296
	ds_read_b128 v[222:225], v175 offset:56320
	global_load_lds_dwordx4 v[244:245], off
	v_lshl_add_u64 v[244:245], v[252:253], 0, s[30:31]
	s_mov_b32 m0, s45
	s_nop 0
	global_load_lds_dwordx4 v[244:245], off
	s_barrier
	s_waitcnt lgkmcnt(7)
	v_mfma_f32_16x16x32_bf16 v[62:65], v[176:179], v[192:195], v[62:65]
	v_mfma_f32_16x16x32_bf16 v[58:61], v[184:187], v[192:195], v[58:61]
	s_waitcnt lgkmcnt(5)
	v_mfma_f32_16x16x32_bf16 v[54:57], v[176:179], v[200:203], v[54:57]
	v_mfma_f32_16x16x32_bf16 v[50:53], v[184:187], v[200:203], v[50:53]
	s_waitcnt lgkmcnt(3)
	v_mfma_f32_16x16x32_bf16 v[46:49], v[176:179], v[210:213], v[46:49]
	v_mfma_f32_16x16x32_bf16 v[42:45], v[184:187], v[210:213], v[42:45]
	s_waitcnt lgkmcnt(1)
	v_mfma_f32_16x16x32_bf16 v[38:41], v[176:179], v[218:221], v[38:41]
	v_mfma_f32_16x16x32_bf16 v[34:37], v[184:187], v[218:221], v[34:37]
	v_mfma_f32_16x16x32_bf16 v[62:65], v[180:183], v[196:199], v[62:65]
	v_mfma_f32_16x16x32_bf16 v[58:61], v[188:191], v[196:199], v[58:61]
	v_mfma_f32_16x16x32_bf16 v[54:57], v[180:183], v[204:207], v[54:57]
	v_mfma_f32_16x16x32_bf16 v[50:53], v[188:191], v[204:207], v[50:53]
	v_mfma_f32_16x16x32_bf16 v[46:49], v[180:183], v[214:217], v[46:49]
	v_mfma_f32_16x16x32_bf16 v[42:45], v[188:191], v[214:217], v[42:45]
	s_waitcnt lgkmcnt(0)
	v_mfma_f32_16x16x32_bf16 v[38:41], v[180:183], v[222:225], v[38:41]
	v_mfma_f32_16x16x32_bf16 v[34:37], v[188:191], v[222:225], v[34:37]
	s_barrier
	v_lshl_add_u64 v[170:171], v[170:171], 0, s[34:35]
	s_add_i32 s6, s7, s13
	v_lshl_add_u64 v[176:177], v[170:171], 0, v[132:133]
	s_mov_b32 m0, s6
	v_lshl_add_u64 v[170:171], v[170:171], 0, v[142:143]
	global_load_lds_dwordx4 v[176:177], off
	s_add_i32 m0, s6, 0x2000
	s_nop 0
	global_load_lds_dwordx4 v[170:171], off
	s_waitcnt vmcnt(6)
	s_barrier
	v_mfma_f32_16x16x32_bf16 v[30:33], v[228:231], v[192:195], v[30:33]
	v_mfma_f32_16x16x32_bf16 v[26:29], v[236:239], v[192:195], v[26:29]
	v_mfma_f32_16x16x32_bf16 v[22:25], v[228:231], v[200:203], v[22:25]
	v_mfma_f32_16x16x32_bf16 v[18:21], v[236:239], v[200:203], v[18:21]
	v_mfma_f32_16x16x32_bf16 v[14:17], v[228:231], v[210:213], v[14:17]
	v_mfma_f32_16x16x32_bf16 v[10:13], v[236:239], v[210:213], v[10:13]
	v_mfma_f32_16x16x32_bf16 v[6:9], v[228:231], v[218:221], v[6:9]
	v_mfma_f32_16x16x32_bf16 v[2:5], v[236:239], v[218:221], v[2:5]
	v_mfma_f32_16x16x32_bf16 v[30:33], v[232:235], v[196:199], v[30:33]
	v_mfma_f32_16x16x32_bf16 v[26:29], v[240:243], v[196:199], v[26:29]
	v_mfma_f32_16x16x32_bf16 v[22:25], v[232:235], v[204:207], v[22:25]
	v_mfma_f32_16x16x32_bf16 v[18:21], v[240:243], v[204:207], v[18:21]
	v_mfma_f32_16x16x32_bf16 v[14:17], v[232:235], v[214:217], v[14:17]
	v_mfma_f32_16x16x32_bf16 v[10:13], v[240:243], v[214:217], v[10:13]
	v_mfma_f32_16x16x32_bf16 v[6:9], v[232:235], v[222:225], v[6:9]
	v_mfma_f32_16x16x32_bf16 v[2:5], v[240:243], v[222:225], v[2:5]
	s_add_i32 s46, s46, 2
	s_add_u32 s4, s4, 0x100
	s_addc_u32 s5, s5, 0
	s_cmp_lt_u32 s46, 14
	s_barrier
	s_cbranch_scc1 .LBB0_243
	s_setprio 0
	s_waitcnt vmcnt(0)
	s_cmpk_gt_u32 s12, 0xff
	s_cbranch_scc1 .LBB0_246
	s_barrier

.LBB0_755:
	s_add_i32 m0, s34, 0x18000
	v_lshl_add_u64 v[2:3], v[2:3], 0, s[16:17]
	s_waitcnt vmcnt(4)
	s_barrier
	global_load_lds_dwordx4 v[2:3], off
	v_lshl_add_u64 v[2:3], v[4:5], 0, s[16:17]
	s_add_i32 m0, s34, 0x1a000
	s_add_i32 s39, s34, 0x8000
	global_load_lds_dwordx4 v[2:3], off
	v_lshl_add_u64 v[2:3], v[8:9], 0, s[16:17]
	s_mov_b32 m0, s39
	s_add_i32 s40, s34, 0xa000
	global_load_lds_dwordx4 v[2:3], off
	v_lshl_add_u64 v[2:3], v[6:7], 0, s[16:17]
	s_mov_b32 m0, s40
	v_bfe_u32 v166, v15, 4, 2
	global_load_lds_dwordx4 v[2:3], off
	v_lshl_add_u64 v[2:3], v[144:145], 0, s[18:19]
	s_add_i32 m0, s34, 0x1c000
	v_lshl_add_u64 v[4:5], v[2:3], 0, v[134:135]
	global_load_lds_dwordx4 v[4:5], off
	v_lshl_add_u64 v[2:3], v[2:3], 0, v[142:143]
	s_add_i32 m0, s34, 0x1e000
	s_lshl_b32 s6, s6, 5
	global_load_lds_dwordx4 v[2:3], off
	v_and_b32_e32 v19, 15, v15
	v_lshlrev_b32_e32 v20, 4, v166
	s_and_b32 s36, s6, 0x60
	v_lshlrev_b32_e32 v15, 2, v15
	v_lshl_or_b32 v167, s7, 6, v19
	v_lshl_or_b32 v19, v19, 6, v20
	s_lshl_b32 s6, s36, 7
	v_and_b32_e32 v15, 32, v15
	v_bitop3_b32 v168, v19, s6, v15 bitop3:0xde
	s_lshl_b32 s6, s7, 13
	v_lshrrev_b32_e32 v3, 1, v10
	v_mul_lo_u32 v2, v11, s3
	v_bitop3_b32 v15, v19, s6, v15 bitop3:0xde
	v_mad_u64_u32 v[2:3], s[6:7], v3, s25, v[2:3]
	v_or_b32_e32 v2, v2, v12
	s_mul_hi_i32 s43, s30, 0xc0000
	s_mul_i32 s42, s30, 0xc0000
	v_add_lshl_u32 v2, v2, v13, 1
	v_mov_b32_e32 v3, v135
	v_lshl_add_u64 v[2:3], s[42:43], 0, v[2:3]
	v_lshl_add_u64 v[148:149], v[154:155], 0, v[2:3]
	v_lshrrev_b32_e32 v3, 1, v14
	v_mul_lo_u32 v2, v16, s3
	v_mad_u64_u32 v[2:3], s[6:7], v3, s25, v[2:3]
	v_or_b32_e32 v2, v2, v17
	v_add_lshl_u32 v2, v2, v18, 1
	v_mov_b32_e32 v3, v135
	s_waitcnt vmcnt(6)
	v_lshl_add_u64 v[2:3], s[42:43], 0, v[2:3]
	v_lshl_add_u64 v[150:151], v[154:155], 0, v[2:3]
	v_mov_b32_e32 v2, 0
	s_mov_b32 s41, -2
	s_mov_b64 s[6:7], 0x42e0080
	v_add_u32_e32 v169, 0, v15
	v_mov_b32_e32 v3, v2
	v_mov_b32_e32 v4, v2
	v_mov_b32_e32 v5, v2
	v_mov_b32_e32 v6, v2
	v_mov_b32_e32 v7, v2
	v_mov_b32_e32 v8, v2
	v_mov_b32_e32 v9, v2
	v_mov_b32_e32 v10, v2
	v_mov_b32_e32 v11, v2
	v_mov_b32_e32 v12, v2
	v_mov_b32_e32 v13, v2
	v_mov_b32_e32 v14, v2
	v_mov_b32_e32 v15, v2
	v_mov_b32_e32 v16, v2
	v_mov_b32_e32 v17, v2
	v_mov_b32_e32 v18, v2
	v_mov_b32_e32 v19, v2
	v_mov_b32_e32 v20, v2
	v_mov_b32_e32 v21, v2
	v_mov_b32_e32 v22, v2
	v_mov_b32_e32 v23, v2
	v_mov_b32_e32 v24, v2
	v_mov_b32_e32 v25, v2
	v_mov_b32_e32 v26, v2
	v_mov_b32_e32 v27, v2
	v_mov_b32_e32 v28, v2
	v_mov_b32_e32 v29, v2
	v_mov_b32_e32 v30, v2
	v_mov_b32_e32 v31, v2
	v_mov_b32_e32 v32, v2
	v_mov_b32_e32 v33, v2
	v_mov_b32_e32 v34, v2
	v_mov_b32_e32 v35, v2
	v_mov_b32_e32 v36, v2
	v_mov_b32_e32 v37, v2
	v_mov_b32_e32 v38, v2
	v_mov_b32_e32 v39, v2
	v_mov_b32_e32 v40, v2
	v_mov_b32_e32 v41, v2
	v_mov_b32_e32 v42, v2
	v_mov_b32_e32 v43, v2
	v_mov_b32_e32 v44, v2
	v_mov_b32_e32 v45, v2
	v_mov_b32_e32 v46, v2
	v_mov_b32_e32 v47, v2
	v_mov_b32_e32 v48, v2
	v_mov_b32_e32 v49, v2
	v_mov_b32_e32 v50, v2
	v_mov_b32_e32 v51, v2
	v_mov_b32_e32 v52, v2
	v_mov_b32_e32 v53, v2
	v_mov_b32_e32 v54, v2
	v_mov_b32_e32 v55, v2
	v_mov_b32_e32 v56, v2
	v_mov_b32_e32 v57, v2
	v_mov_b32_e32 v58, v2
	v_mov_b32_e32 v59, v2
	v_mov_b32_e32 v60, v2
	v_mov_b32_e32 v61, v2
	v_mov_b32_e32 v62, v2
	v_mov_b32_e32 v63, v2
	v_mov_b32_e32 v64, v2
	v_mov_b32_e32 v65, v2
	v_mov_b32_e32 v66, v2
	v_mov_b32_e32 v67, v2
	v_mov_b32_e32 v68, v2
	v_mov_b32_e32 v69, v2
	v_mov_b32_e32 v70, v2
	v_mov_b32_e32 v71, v2
	v_mov_b32_e32 v72, v2
	v_mov_b32_e32 v73, v2
	v_mov_b32_e32 v74, v2
	v_mov_b32_e32 v75, v2
	v_mov_b32_e32 v76, v2
	v_mov_b32_e32 v77, v2
	v_mov_b32_e32 v78, v2
	v_mov_b32_e32 v79, v2
	v_mov_b32_e32 v80, v2
	v_mov_b32_e32 v81, v2
	v_mov_b32_e32 v82, v2
	v_mov_b32_e32 v83, v2
	v_mov_b32_e32 v84, v2
	v_mov_b32_e32 v85, v2
	v_mov_b32_e32 v86, v2
	v_mov_b32_e32 v87, v2
	v_mov_b32_e32 v88, v2
	v_mov_b32_e32 v89, v2
	v_mov_b32_e32 v90, v2
	v_mov_b32_e32 v91, v2
	v_mov_b32_e32 v92, v2
	v_mov_b32_e32 v93, v2
	v_mov_b32_e32 v94, v2
	v_mov_b32_e32 v95, v2
	v_mov_b32_e32 v96, v2
	v_mov_b32_e32 v97, v2
	v_mov_b32_e32 v98, v2
	v_mov_b32_e32 v99, v2
	v_mov_b32_e32 v100, v2
	v_mov_b32_e32 v101, v2
	v_mov_b32_e32 v102, v2
	v_mov_b32_e32 v103, v2
	v_mov_b32_e32 v104, v2
	v_mov_b32_e32 v105, v2
	v_mov_b32_e32 v106, v2
	v_mov_b32_e32 v107, v2
	v_mov_b32_e32 v108, v2
	v_mov_b32_e32 v109, v2
	v_mov_b32_e32 v110, v2
	v_mov_b32_e32 v111, v2
	v_mov_b32_e32 v112, v2
	v_mov_b32_e32 v113, v2
	v_mov_b32_e32 v114, v2
	v_mov_b32_e32 v115, v2
	v_mov_b32_e32 v116, v2
	v_mov_b32_e32 v117, v2
	v_mov_b32_e32 v118, v2
	v_mov_b32_e32 v119, v2
	v_mov_b32_e32 v120, v2
	v_mov_b32_e32 v121, v2
	v_mov_b32_e32 v122, v2
	v_mov_b32_e32 v123, v2
	v_mov_b32_e32 v124, v2
	v_mov_b32_e32 v125, v2
	v_mov_b32_e32 v126, v2
	v_mov_b32_e32 v127, v2
	v_mov_b32_e32 v128, v2
	v_mov_b32_e32 v129, v2
	s_barrier
	v_readfirstlane_b32 s98, v0
	s_bitcmp1_b32 s98, 8
	s_cbranch_scc0 .Lkprio_1
	s_setprio 1
.Lkprio_1:
.LBB0_756:
	s_add_u32 s42, s6, 0xfbd20080
	s_addc_u32 s43, s7, -1
	s_cmp_lg_u32 s41, 20
	s_cselect_b32 s43, s43, 0
	s_cselect_b32 s42, s42, 0
	s_add_i32 s44, 0, 0x10000
	v_add_u32_e32 v152, s44, v168
	ds_read_b128 v[170:173], v152
	ds_read_b128 v[174:177], v152 offset:1024
	ds_read_b128 v[178:181], v152 offset:2048
	ds_read_b128 v[182:185], v152 offset:3072
	v_lshl_add_u64 v[206:207], v[146:147], 0, s[42:43]
	v_lshl_add_u64 v[152:153], v[144:145], 0, s[42:43]
	v_lshl_add_u64 v[222:223], v[148:149], 0, s[6:7]
	s_add_i32 m0, s34, 0xc000
	ds_read_b128 v[186:189], v169
	ds_read_b128 v[190:193], v169 offset:1024
	ds_read_b128 v[194:197], v169 offset:2048
	ds_read_b128 v[198:201], v169 offset:3072
	ds_read_b128 v[202:205], v169 offset:4096
	ds_read_b128 v[210:213], v169 offset:5120
	ds_read_b128 v[214:217], v169 offset:6144
	ds_read_b128 v[218:221], v169 offset:7168
	global_load_lds_dwordx4 v[222:223], off
	v_lshl_add_u64 v[222:223], v[150:151], 0, s[6:7]
	s_add_i32 m0, s34, 0xe000
	s_nop 0
	global_load_lds_dwordx4 v[222:223], off
	s_waitcnt lgkmcnt(8)
	s_barrier
	s_waitcnt lgkmcnt(7)
	v_mfma_f32_16x16x32_bf16 v[126:129], v[170:173], v[186:189], v[126:129]
	v_mfma_f32_16x16x32_bf16 v[122:125], v[178:181], v[186:189], v[122:125]
	s_waitcnt lgkmcnt(5)
	v_mfma_f32_16x16x32_bf16 v[118:121], v[170:173], v[194:197], v[118:121]
	v_mfma_f32_16x16x32_bf16 v[114:117], v[178:181], v[194:197], v[114:117]
	s_waitcnt lgkmcnt(3)
	v_mfma_f32_16x16x32_bf16 v[110:113], v[170:173], v[202:205], v[110:113]
	v_mfma_f32_16x16x32_bf16 v[106:109], v[178:181], v[202:205], v[106:109]
	s_waitcnt lgkmcnt(1)
	v_mfma_f32_16x16x32_bf16 v[102:105], v[170:173], v[214:217], v[102:105]
	v_mfma_f32_16x16x32_bf16 v[98:101], v[178:181], v[214:217], v[98:101]
	v_mfma_f32_16x16x32_bf16 v[126:129], v[174:177], v[190:193], v[126:129]
	v_mfma_f32_16x16x32_bf16 v[122:125], v[182:185], v[190:193], v[122:125]
	v_mfma_f32_16x16x32_bf16 v[118:121], v[174:177], v[198:201], v[118:121]
	v_mfma_f32_16x16x32_bf16 v[114:117], v[182:185], v[198:201], v[114:117]
	v_mfma_f32_16x16x32_bf16 v[110:113], v[174:177], v[210:213], v[110:113]
	v_mfma_f32_16x16x32_bf16 v[106:109], v[182:185], v[210:213], v[106:109]
	s_waitcnt lgkmcnt(0)
	v_mfma_f32_16x16x32_bf16 v[102:105], v[174:177], v[218:221], v[102:105]
	v_mfma_f32_16x16x32_bf16 v[98:101], v[182:185], v[218:221], v[98:101]
	s_barrier
	s_add_i32 s42, 0, 0x14000
	s_add_i32 s43, s44, s33
	v_add_u32_e32 v208, s42, v168
	v_lshl_add_u64 v[240:241], v[152:153], 0, v[134:135]
	s_mov_b32 m0, s43
	ds_read_b128 v[222:225], v208
	ds_read_b128 v[228:231], v208 offset:1024
	ds_read_b128 v[232:235], v208 offset:2048
	ds_read_b128 v[236:239], v208 offset:3072
	global_load_lds_dwordx4 v[240:241], off
	v_lshl_add_u64 v[242:243], v[152:153], 0, v[142:143]
	s_add_i32 m0, s43, 0x2000
	s_nop 0
	global_load_lds_dwordx4 v[242:243], off
	s_barrier
	s_waitcnt lgkmcnt(3)
	v_mfma_f32_16x16x32_bf16 v[94:97], v[222:225], v[186:189], v[94:97]
	s_waitcnt lgkmcnt(1)
	v_mfma_f32_16x16x32_bf16 v[90:93], v[232:235], v[186:189], v[90:93]
	v_mfma_f32_16x16x32_bf16 v[86:89], v[222:225], v[194:197], v[86:89]
	v_mfma_f32_16x16x32_bf16 v[82:85], v[232:235], v[194:197], v[82:85]
	v_mfma_f32_16x16x32_bf16 v[78:81], v[222:225], v[202:205], v[78:81]
	v_mfma_f32_16x16x32_bf16 v[74:77], v[232:235], v[202:205], v[74:77]
	v_mfma_f32_16x16x32_bf16 v[70:73], v[222:225], v[214:217], v[70:73]
	v_mfma_f32_16x16x32_bf16 v[66:69], v[232:235], v[214:217], v[66:69]
	v_mfma_f32_16x16x32_bf16 v[94:97], v[228:231], v[190:193], v[94:97]
	s_waitcnt lgkmcnt(0)
	v_mfma_f32_16x16x32_bf16 v[90:93], v[236:239], v[190:193], v[90:93]
	v_mfma_f32_16x16x32_bf16 v[86:89], v[228:231], v[198:201], v[86:89]
	v_mfma_f32_16x16x32_bf16 v[82:85], v[236:239], v[198:201], v[82:85]
	v_mfma_f32_16x16x32_bf16 v[78:81], v[228:231], v[210:213], v[78:81]
	v_mfma_f32_16x16x32_bf16 v[74:77], v[236:239], v[210:213], v[74:77]
	v_mfma_f32_16x16x32_bf16 v[70:73], v[228:231], v[218:221], v[70:73]
	v_mfma_f32_16x16x32_bf16 v[66:69], v[236:239], v[218:221], v[66:69]
	s_mov_b32 m0, s34
	v_lshl_add_u64 v[244:245], v[206:207], 0, v[134:135]
	s_barrier
	ds_read_b128 v[186:189], v169 offset:16384
	ds_read_b128 v[190:193], v169 offset:17408
	ds_read_b128 v[194:197], v169 offset:18432
	ds_read_b128 v[198:201], v169 offset:19456
	ds_read_b128 v[202:205], v169 offset:20480
	ds_read_b128 v[210:213], v169 offset:21504
	ds_read_b128 v[214:217], v169 offset:22528
	ds_read_b128 v[218:221], v169 offset:23552
	global_load_lds_dwordx4 v[244:245], off
	v_lshl_add_u64 v[246:247], v[206:207], 0, v[142:143]
	s_mov_b32 m0, s35
	s_nop 0
	global_load_lds_dwordx4 v[246:247], off
	s_barrier
	s_waitcnt lgkmcnt(7)
	v_mfma_f32_16x16x32_bf16 v[62:65], v[170:173], v[186:189], v[62:65]
	v_mfma_f32_16x16x32_bf16 v[58:61], v[178:181], v[186:189], v[58:61]
	s_waitcnt lgkmcnt(5)
	v_mfma_f32_16x16x32_bf16 v[54:57], v[170:173], v[194:197], v[54:57]
	v_mfma_f32_16x16x32_bf16 v[50:53], v[178:181], v[194:197], v[50:53]
	s_waitcnt lgkmcnt(3)
	v_mfma_f32_16x16x32_bf16 v[46:49], v[170:173], v[202:205], v[46:49]
	v_mfma_f32_16x16x32_bf16 v[42:45], v[178:181], v[202:205], v[42:45]
	s_waitcnt lgkmcnt(1)
	v_mfma_f32_16x16x32_bf16 v[38:41], v[170:173], v[214:217], v[38:41]
	v_mfma_f32_16x16x32_bf16 v[34:37], v[178:181], v[214:217], v[34:37]
	v_mfma_f32_16x16x32_bf16 v[62:65], v[174:177], v[190:193], v[62:65]
	v_mfma_f32_16x16x32_bf16 v[58:61], v[182:185], v[190:193], v[58:61]
	v_mfma_f32_16x16x32_bf16 v[54:57], v[174:177], v[198:201], v[54:57]
	v_mfma_f32_16x16x32_bf16 v[50:53], v[182:185], v[198:201], v[50:53]
	v_mfma_f32_16x16x32_bf16 v[46:49], v[174:177], v[210:213], v[46:49]
	v_mfma_f32_16x16x32_bf16 v[42:45], v[182:185], v[210:213], v[42:45]
	s_waitcnt lgkmcnt(0)
	v_mfma_f32_16x16x32_bf16 v[38:41], v[174:177], v[218:221], v[38:41]
	v_mfma_f32_16x16x32_bf16 v[34:37], v[182:185], v[218:221], v[34:37]
	s_barrier
	v_lshl_add_u64 v[170:171], v[152:153], 0, s[14:15]
	s_add_i32 s42, s42, s33
	v_lshl_add_u64 v[172:173], v[170:171], 0, v[134:135]
	s_mov_b32 m0, s42
	v_lshl_add_u64 v[170:171], v[170:171], 0, v[142:143]
	global_load_lds_dwordx4 v[172:173], off
	s_add_i32 m0, s42, 0x2000
	s_nop 0
	global_load_lds_dwordx4 v[170:171], off
	s_waitcnt vmcnt(6)
	s_barrier
	v_mfma_f32_16x16x32_bf16 v[30:33], v[222:225], v[186:189], v[30:33]
	v_mfma_f32_16x16x32_bf16 v[26:29], v[232:235], v[186:189], v[26:29]
	v_mfma_f32_16x16x32_bf16 v[22:25], v[222:225], v[194:197], v[22:25]
	v_mfma_f32_16x16x32_bf16 v[18:21], v[232:235], v[194:197], v[18:21]
	v_mfma_f32_16x16x32_bf16 v[14:17], v[222:225], v[202:205], v[14:17]
	v_mfma_f32_16x16x32_bf16 v[10:13], v[232:235], v[202:205], v[10:13]
	v_mfma_f32_16x16x32_bf16 v[6:9], v[222:225], v[214:217], v[6:9]
	v_mfma_f32_16x16x32_bf16 v[2:5], v[232:235], v[214:217], v[2:5]
	v_mfma_f32_16x16x32_bf16 v[30:33], v[228:231], v[190:193], v[30:33]
	v_mfma_f32_16x16x32_bf16 v[26:29], v[236:239], v[190:193], v[26:29]
	v_mfma_f32_16x16x32_bf16 v[22:25], v[228:231], v[198:201], v[22:25]
	v_mfma_f32_16x16x32_bf16 v[18:21], v[236:239], v[198:201], v[18:21]
	v_mfma_f32_16x16x32_bf16 v[14:17], v[228:231], v[210:213], v[14:17]
	v_mfma_f32_16x16x32_bf16 v[10:13], v[236:239], v[210:213], v[10:13]
	v_mfma_f32_16x16x32_bf16 v[6:9], v[228:231], v[218:221], v[6:9]
	v_mfma_f32_16x16x32_bf16 v[2:5], v[236:239], v[218:221], v[2:5]
	s_add_i32 s42, 0, 0x18000
	v_add_u32_e32 v182, s42, v168
	s_barrier
	ds_read_b128 v[170:173], v182
	ds_read_b128 v[174:177], v182 offset:1024
	ds_read_b128 v[178:181], v182 offset:2048
	ds_read_b128 v[182:185], v182 offset:3072
	v_lshl_add_u64 v[206:207], v[206:207], 0, s[14:15]
	s_mov_b32 m0, s37
	v_lshl_add_u64 v[222:223], v[206:207], 0, v[134:135]
	ds_read_b128 v[186:189], v169 offset:32768
	ds_read_b128 v[190:193], v169 offset:33792
	ds_read_b128 v[194:197], v169 offset:34816
	ds_read_b128 v[198:201], v169 offset:35840
	ds_read_b128 v[202:205], v169 offset:36864
	ds_read_b128 v[210:213], v169 offset:37888
	ds_read_b128 v[214:217], v169 offset:38912
	ds_read_b128 v[218:221], v169 offset:39936
	global_load_lds_dwordx4 v[222:223], off
	v_lshl_add_u64 v[206:207], v[206:207], 0, v[142:143]
	s_mov_b32 m0, s38
	s_nop 0
	global_load_lds_dwordx4 v[206:207], off
	s_waitcnt lgkmcnt(8)
	s_barrier
	s_waitcnt lgkmcnt(7)
	v_mfma_f32_16x16x32_bf16 v[126:129], v[170:173], v[186:189], v[126:129]
	v_mfma_f32_16x16x32_bf16 v[122:125], v[178:181], v[186:189], v[122:125]
	s_waitcnt lgkmcnt(5)
	v_mfma_f32_16x16x32_bf16 v[118:121], v[170:173], v[194:197], v[118:121]
	v_mfma_f32_16x16x32_bf16 v[114:117], v[178:181], v[194:197], v[114:117]
	s_waitcnt lgkmcnt(3)
	v_mfma_f32_16x16x32_bf16 v[110:113], v[170:173], v[202:205], v[110:113]
	v_mfma_f32_16x16x32_bf16 v[106:109], v[178:181], v[202:205], v[106:109]
	s_waitcnt lgkmcnt(1)
	v_mfma_f32_16x16x32_bf16 v[102:105], v[170:173], v[214:217], v[102:105]
	v_mfma_f32_16x16x32_bf16 v[98:101], v[178:181], v[214:217], v[98:101]
	v_mfma_f32_16x16x32_bf16 v[126:129], v[174:177], v[190:193], v[126:129]
	v_mfma_f32_16x16x32_bf16 v[122:125], v[182:185], v[190:193], v[122:125]
	v_mfma_f32_16x16x32_bf16 v[118:121], v[174:177], v[198:201], v[118:121]
	v_mfma_f32_16x16x32_bf16 v[114:117], v[182:185], v[198:201], v[114:117]
	v_mfma_f32_16x16x32_bf16 v[110:113], v[174:177], v[210:213], v[110:113]
	v_mfma_f32_16x16x32_bf16 v[106:109], v[182:185], v[210:213], v[106:109]
	s_waitcnt lgkmcnt(0)
	v_mfma_f32_16x16x32_bf16 v[102:105], v[174:177], v[218:221], v[102:105]
	v_mfma_f32_16x16x32_bf16 v[98:101], v[182:185], v[218:221], v[98:101]
	s_barrier
	s_add_i32 s43, 0, 0x1c000
	v_add_u32_e32 v206, s43, v168
	s_add_i32 s42, s42, s33
	ds_read_b128 v[222:225], v206
	ds_read_b128 v[228:231], v206 offset:1024
	ds_read_b128 v[232:235], v206 offset:2048
	ds_read_b128 v[236:239], v206 offset:3072
	v_lshl_add_u64 v[206:207], v[240:241], 0, s[16:17]
	s_mov_b32 m0, s42
	s_nop 0
	global_load_lds_dwordx4 v[206:207], off
	v_lshl_add_u64 v[206:207], v[242:243], 0, s[16:17]
	s_add_i32 m0, s42, 0x2000
	s_nop 0
	global_load_lds_dwordx4 v[206:207], off
	s_barrier
	s_waitcnt lgkmcnt(3)
	v_mfma_f32_16x16x32_bf16 v[94:97], v[222:225], v[186:189], v[94:97]
	s_waitcnt lgkmcnt(1)
	v_mfma_f32_16x16x32_bf16 v[90:93], v[232:235], v[186:189], v[90:93]
	v_mfma_f32_16x16x32_bf16 v[86:89], v[222:225], v[194:197], v[86:89]
	v_mfma_f32_16x16x32_bf16 v[82:85], v[232:235], v[194:197], v[82:85]
	v_mfma_f32_16x16x32_bf16 v[78:81], v[222:225], v[202:205], v[78:81]
	v_mfma_f32_16x16x32_bf16 v[74:77], v[232:235], v[202:205], v[74:77]
	v_mfma_f32_16x16x32_bf16 v[70:73], v[222:225], v[214:217], v[70:73]
	v_mfma_f32_16x16x32_bf16 v[66:69], v[232:235], v[214:217], v[66:69]
	v_mfma_f32_16x16x32_bf16 v[94:97], v[228:231], v[190:193], v[94:97]
	s_waitcnt lgkmcnt(0)
	v_mfma_f32_16x16x32_bf16 v[90:93], v[236:239], v[190:193], v[90:93]
	v_mfma_f32_16x16x32_bf16 v[86:89], v[228:231], v[198:201], v[86:89]
	v_mfma_f32_16x16x32_bf16 v[82:85], v[236:239], v[198:201], v[82:85]
	v_mfma_f32_16x16x32_bf16 v[78:81], v[228:231], v[210:213], v[78:81]
	v_mfma_f32_16x16x32_bf16 v[74:77], v[236:239], v[210:213], v[74:77]
	v_mfma_f32_16x16x32_bf16 v[70:73], v[228:231], v[218:221], v[70:73]
	v_mfma_f32_16x16x32_bf16 v[66:69], v[236:239], v[218:221], v[66:69]
	s_mov_b32 m0, s39
	v_lshl_add_u64 v[206:207], v[244:245], 0, s[16:17]
	s_barrier
	ds_read_b128 v[186:189], v169 offset:49152
	ds_read_b128 v[190:193], v169 offset:50176
	ds_read_b128 v[194:197], v169 offset:51200
	ds_read_b128 v[198:201], v169 offset:52224
	ds_read_b128 v[202:205], v169 offset:53248
	ds_read_b128 v[210:213], v169 offset:54272
	ds_read_b128 v[214:217], v169 offset:55296
	ds_read_b128 v[218:221], v169 offset:56320
	global_load_lds_dwordx4 v[206:207], off
	v_lshl_add_u64 v[206:207], v[246:247], 0, s[16:17]
	s_mov_b32 m0, s40
	s_nop 0
	global_load_lds_dwordx4 v[206:207], off
	s_barrier
	s_waitcnt lgkmcnt(7)
	v_mfma_f32_16x16x32_bf16 v[62:65], v[170:173], v[186:189], v[62:65]
	v_mfma_f32_16x16x32_bf16 v[58:61], v[178:181], v[186:189], v[58:61]
	s_waitcnt lgkmcnt(5)
	v_mfma_f32_16x16x32_bf16 v[54:57], v[170:173], v[194:197], v[54:57]
	v_mfma_f32_16x16x32_bf16 v[50:53], v[178:181], v[194:197], v[50:53]
	s_waitcnt lgkmcnt(3)
	v_mfma_f32_16x16x32_bf16 v[46:49], v[170:173], v[202:205], v[46:49]
	v_mfma_f32_16x16x32_bf16 v[42:45], v[178:181], v[202:205], v[42:45]
	s_waitcnt lgkmcnt(1)
	v_mfma_f32_16x16x32_bf16 v[38:41], v[170:173], v[214:217], v[38:41]
	v_mfma_f32_16x16x32_bf16 v[34:37], v[178:181], v[214:217], v[34:37]
	v_mfma_f32_16x16x32_bf16 v[62:65], v[174:177], v[190:193], v[62:65]
	v_mfma_f32_16x16x32_bf16 v[58:61], v[182:185], v[190:193], v[58:61]
	v_mfma_f32_16x16x32_bf16 v[54:57], v[174:177], v[198:201], v[54:57]
	v_mfma_f32_16x16x32_bf16 v[50:53], v[182:185], v[198:201], v[50:53]
	v_mfma_f32_16x16x32_bf16 v[46:49], v[174:177], v[210:213], v[46:49]
	v_mfma_f32_16x16x32_bf16 v[42:45], v[182:185], v[210:213], v[42:45]
	s_waitcnt lgkmcnt(0)
	v_mfma_f32_16x16x32_bf16 v[38:41], v[174:177], v[218:221], v[38:41]
	v_mfma_f32_16x16x32_bf16 v[34:37], v[182:185], v[218:221], v[34:37]
	s_barrier
	v_lshl_add_u64 v[152:153], v[152:153], 0, s[18:19]
	s_add_i32 s42, s43, s33
	v_lshl_add_u64 v[170:171], v[152:153], 0, v[134:135]
	s_mov_b32 m0, s42
	v_lshl_add_u64 v[152:153], v[152:153], 0, v[142:143]
	global_load_lds_dwordx4 v[170:171], off
	s_add_i32 m0, s42, 0x2000
	s_nop 0
	global_load_lds_dwordx4 v[152:153], off
	s_waitcnt vmcnt(6)
	s_barrier
	v_mfma_f32_16x16x32_bf16 v[30:33], v[222:225], v[186:189], v[30:33]
	v_mfma_f32_16x16x32_bf16 v[26:29], v[232:235], v[186:189], v[26:29]
	v_mfma_f32_16x16x32_bf16 v[22:25], v[222:225], v[194:197], v[22:25]
	v_mfma_f32_16x16x32_bf16 v[18:21], v[232:235], v[194:197], v[18:21]
	v_mfma_f32_16x16x32_bf16 v[14:17], v[222:225], v[202:205], v[14:17]
	v_mfma_f32_16x16x32_bf16 v[10:13], v[232:235], v[202:205], v[10:13]
	v_mfma_f32_16x16x32_bf16 v[6:9], v[222:225], v[214:217], v[6:9]
	v_mfma_f32_16x16x32_bf16 v[2:5], v[232:235], v[214:217], v[2:5]
	v_mfma_f32_16x16x32_bf16 v[30:33], v[228:231], v[190:193], v[30:33]
	v_mfma_f32_16x16x32_bf16 v[26:29], v[236:239], v[190:193], v[26:29]
	v_mfma_f32_16x16x32_bf16 v[22:25], v[228:231], v[198:201], v[22:25]
	v_mfma_f32_16x16x32_bf16 v[18:21], v[236:239], v[198:201], v[18:21]
	v_mfma_f32_16x16x32_bf16 v[14:17], v[228:231], v[210:213], v[14:17]
	v_mfma_f32_16x16x32_bf16 v[10:13], v[236:239], v[210:213], v[10:13]
	v_mfma_f32_16x16x32_bf16 v[6:9], v[228:231], v[218:221], v[6:9]
	v_mfma_f32_16x16x32_bf16 v[2:5], v[236:239], v[218:221], v[2:5]
	s_add_i32 s41, s41, 2
	s_add_u32 s6, s6, 0x100
	s_addc_u32 s7, s7, 0
	s_cmp_lt_u32 s41, 22
	s_barrier
	s_cbranch_scc1 .LBB0_756
	s_setprio 0
	s_waitcnt vmcnt(0)
	s_cmpk_gt_u32 s31, 0xff
	s_cbranch_scc1 .LBB0_759
	s_barrier

.LBB0_913:
	v_bfe_u32 v172, v15, 4, 2
	s_lshl_b32 s40, s40, 5
	v_and_b32_e32 v17, 15, v15
	v_lshlrev_b32_e32 v18, 4, v172
	s_and_b32 s40, s40, 0x60
	v_lshlrev_b32_e32 v15, 2, v15
	v_lshl_or_b32 v1, s55, 6, v17
	v_lshl_or_b32 v17, v17, 6, v18
	s_lshl_b32 s56, s40, 7
	v_and_b32_e32 v15, 32, v15
	s_lshl_b32 s55, s55, 13
	s_add_i32 m0, s34, 0x18000
	v_lshl_add_u64 v[2:3], v[2:3], 0, s[16:17]
	v_bitop3_b32 v173, v17, s56, v15 bitop3:0xde
	v_bitop3_b32 v15, v17, s55, v15 bitop3:0xde
	s_waitcnt vmcnt(4)
	s_barrier
	global_load_lds_dwordx4 v[2:3], off
	v_lshl_add_u64 v[2:3], v[4:5], 0, s[16:17]
	s_add_i32 m0, s34, 0x1a000
	s_add_i32 s55, s34, 0x8000
	global_load_lds_dwordx4 v[2:3], off
	v_lshl_add_u64 v[2:3], v[8:9], 0, s[16:17]
	s_mov_b32 m0, s55
	s_add_i32 s56, s34, 0xa000
	global_load_lds_dwordx4 v[2:3], off
	v_lshl_add_u64 v[2:3], v[6:7], 0, s[16:17]
	s_mov_b32 m0, s56
	v_lshl_add_u64 v[150:151], v[154:155], 0, s[8:9]
	global_load_lds_dwordx4 v[2:3], off
	v_lshl_add_u64 v[2:3], v[146:147], 0, s[18:19]
	s_add_i32 m0, s34, 0x1c000
	v_lshl_add_u64 v[4:5], v[2:3], 0, v[134:135]
	global_load_lds_dwordx4 v[4:5], off
	v_lshl_add_u64 v[2:3], v[2:3], 0, v[144:145]
	s_add_i32 m0, s34, 0x1e000
	v_lshl_add_u64 v[168:169], v[138:139], 0, s[6:7]
	global_load_lds_dwordx4 v[2:3], off
	v_lshlrev_b32_e32 v2, 14, v10
	v_and_b32_e32 v2, 0xffff8000, v2
	v_lshl_add_u32 v2, v11, 11, v2
	v_and_b32_e32 v3, 1, v10
	v_lshl_or_b32 v2, v3, 6, v2
	v_lshl_add_u32 v2, v12, 1, v2
	v_mov_b32_e32 v3, v135
	v_lshl_add_u64 v[2:3], s[8:9], 0, v[2:3]
	v_lshl_add_u64 v[152:153], v[160:161], 0, v[2:3]
	v_lshlrev_b32_e32 v2, 14, v13
	v_and_b32_e32 v2, 0xffff8000, v2
	v_lshl_add_u32 v2, v14, 11, v2
	v_and_b32_e32 v3, 1, v13
	v_lshl_or_b32 v2, v3, 6, v2
	v_lshl_add_u32 v2, v16, 1, v2
	v_mov_b32_e32 v3, v135
	s_waitcnt vmcnt(6)
	v_lshl_add_u64 v[2:3], s[8:9], 0, v[2:3]
	v_lshl_add_u64 v[166:167], v[160:161], 0, v[2:3]
	v_mov_b32_e32 v2, 0
	s_mov_b32 s8, -2
	s_mov_b64 s[6:7], 0
	v_add_u32_e32 v174, 0, v15
	v_mov_b32_e32 v3, v2
	v_mov_b32_e32 v4, v2
	v_mov_b32_e32 v5, v2
	v_mov_b32_e32 v6, v2
	v_mov_b32_e32 v7, v2
	v_mov_b32_e32 v8, v2
	v_mov_b32_e32 v9, v2
	v_mov_b32_e32 v10, v2
	v_mov_b32_e32 v11, v2
	v_mov_b32_e32 v12, v2
	v_mov_b32_e32 v13, v2
	v_mov_b32_e32 v14, v2
	v_mov_b32_e32 v15, v2
	v_mov_b32_e32 v16, v2
	v_mov_b32_e32 v17, v2
	v_mov_b32_e32 v18, v2
	v_mov_b32_e32 v19, v2
	v_mov_b32_e32 v20, v2
	v_mov_b32_e32 v21, v2
	v_mov_b32_e32 v22, v2
	v_mov_b32_e32 v23, v2
	v_mov_b32_e32 v24, v2
	v_mov_b32_e32 v25, v2
	v_mov_b32_e32 v26, v2
	v_mov_b32_e32 v27, v2
	v_mov_b32_e32 v28, v2
	v_mov_b32_e32 v29, v2
	v_mov_b32_e32 v30, v2
	v_mov_b32_e32 v31, v2
	v_mov_b32_e32 v32, v2
	v_mov_b32_e32 v33, v2
	v_mov_b32_e32 v34, v2
	v_mov_b32_e32 v35, v2
	v_mov_b32_e32 v36, v2
	v_mov_b32_e32 v37, v2
	v_mov_b32_e32 v38, v2
	v_mov_b32_e32 v39, v2
	v_mov_b32_e32 v40, v2
	v_mov_b32_e32 v41, v2
	v_mov_b32_e32 v42, v2
	v_mov_b32_e32 v43, v2
	v_mov_b32_e32 v44, v2
	v_mov_b32_e32 v45, v2
	v_mov_b32_e32 v46, v2
	v_mov_b32_e32 v47, v2
	v_mov_b32_e32 v48, v2
	v_mov_b32_e32 v49, v2
	v_mov_b32_e32 v50, v2
	v_mov_b32_e32 v51, v2
	v_mov_b32_e32 v52, v2
	v_mov_b32_e32 v53, v2
	v_mov_b32_e32 v54, v2
	v_mov_b32_e32 v55, v2
	v_mov_b32_e32 v56, v2
	v_mov_b32_e32 v57, v2
	v_mov_b32_e32 v58, v2
	v_mov_b32_e32 v59, v2
	v_mov_b32_e32 v60, v2
	v_mov_b32_e32 v61, v2
	v_mov_b32_e32 v62, v2
	v_mov_b32_e32 v63, v2
	v_mov_b32_e32 v64, v2
	v_mov_b32_e32 v65, v2
	v_mov_b32_e32 v66, v2
	v_mov_b32_e32 v67, v2
	v_mov_b32_e32 v68, v2
	v_mov_b32_e32 v69, v2
	v_mov_b32_e32 v70, v2
	v_mov_b32_e32 v71, v2
	v_mov_b32_e32 v72, v2
	v_mov_b32_e32 v73, v2
	v_mov_b32_e32 v74, v2
	v_mov_b32_e32 v75, v2
	v_mov_b32_e32 v76, v2
	v_mov_b32_e32 v77, v2
	v_mov_b32_e32 v78, v2
	v_mov_b32_e32 v79, v2
	v_mov_b32_e32 v80, v2
	v_mov_b32_e32 v81, v2
	v_mov_b32_e32 v82, v2
	v_mov_b32_e32 v83, v2
	v_mov_b32_e32 v84, v2
	v_mov_b32_e32 v85, v2
	v_mov_b32_e32 v86, v2
	v_mov_b32_e32 v87, v2
	v_mov_b32_e32 v88, v2
	v_mov_b32_e32 v89, v2
	v_mov_b32_e32 v90, v2
	v_mov_b32_e32 v91, v2
	v_mov_b32_e32 v92, v2
	v_mov_b32_e32 v93, v2
	v_mov_b32_e32 v94, v2
	v_mov_b32_e32 v95, v2
	v_mov_b32_e32 v96, v2
	v_mov_b32_e32 v97, v2
	v_mov_b32_e32 v98, v2
	v_mov_b32_e32 v99, v2
	v_mov_b32_e32 v100, v2
	v_mov_b32_e32 v101, v2
	v_mov_b32_e32 v102, v2
	v_mov_b32_e32 v103, v2
	v_mov_b32_e32 v104, v2
	v_mov_b32_e32 v105, v2
	v_mov_b32_e32 v106, v2
	v_mov_b32_e32 v107, v2
	v_mov_b32_e32 v108, v2
	v_mov_b32_e32 v109, v2
	v_mov_b32_e32 v110, v2
	v_mov_b32_e32 v111, v2
	v_mov_b32_e32 v112, v2
	v_mov_b32_e32 v113, v2
	v_mov_b32_e32 v114, v2
	v_mov_b32_e32 v115, v2
	v_mov_b32_e32 v116, v2
	v_mov_b32_e32 v117, v2
	v_mov_b32_e32 v118, v2
	v_mov_b32_e32 v119, v2
	v_mov_b32_e32 v120, v2
	v_mov_b32_e32 v121, v2
	v_mov_b32_e32 v122, v2
	v_mov_b32_e32 v123, v2
	v_mov_b32_e32 v124, v2
	v_mov_b32_e32 v125, v2
	v_mov_b32_e32 v126, v2
	v_mov_b32_e32 v127, v2
	v_mov_b32_e32 v128, v2
	v_mov_b32_e32 v129, v2
	s_barrier
	v_readfirstlane_b32 s98, v0
	s_bitcmp1_b32 s98, 8
	s_cbranch_scc0 .Lkprio_2
	s_setprio 1
.Lkprio_2:
.LBB0_914:
	s_cmpk_eq_i32 s6, 0x700
	v_lshl_add_u64 v[170:171], v[150:151], 0, s[6:7]
	v_lshl_add_u64 v[170:171], v[170:171], 0, s[20:21]
	s_cselect_b64 vcc, -1, 0
	s_add_i32 s9, 0, 0x10000
	v_cndmask_b32_e32 v245, v171, v149, vcc
	v_add_u32_e32 v171, s9, v173
	ds_read_b128 v[176:179], v171
	ds_read_b128 v[180:183], v171 offset:1024
	ds_read_b128 v[184:187], v171 offset:2048
	ds_read_b128 v[188:191], v171 offset:3072
	v_cndmask_b32_e32 v244, v170, v148, vcc
	v_lshl_add_u64 v[170:171], v[168:169], 0, s[6:7]
	v_cndmask_b32_e32 v171, v171, v147, vcc
	v_cndmask_b32_e32 v170, v170, v146, vcc
	v_lshl_add_u64 v[228:229], v[152:153], 0, s[6:7]
	s_add_i32 m0, s34, 0xc000
	ds_read_b128 v[192:195], v174
	ds_read_b128 v[196:199], v174 offset:1024
	ds_read_b128 v[200:203], v174 offset:2048
	ds_read_b128 v[204:207], v174 offset:3072
	ds_read_b128 v[210:213], v174 offset:4096
	ds_read_b128 v[214:217], v174 offset:5120
	ds_read_b128 v[218:221], v174 offset:6144
	ds_read_b128 v[222:225], v174 offset:7168
	global_load_lds_dwordx4 v[228:229], off
	v_lshl_add_u64 v[228:229], v[166:167], 0, s[6:7]
	s_add_i32 m0, s34, 0xe000
	s_nop 0
	global_load_lds_dwordx4 v[228:229], off
	s_waitcnt lgkmcnt(8)
	s_barrier
	s_waitcnt lgkmcnt(7)
	v_mfma_f32_16x16x32_bf16 v[126:129], v[176:179], v[192:195], v[126:129]
	v_mfma_f32_16x16x32_bf16 v[122:125], v[184:187], v[192:195], v[122:125]
	s_waitcnt lgkmcnt(5)
	v_mfma_f32_16x16x32_bf16 v[118:121], v[176:179], v[200:203], v[118:121]
	v_mfma_f32_16x16x32_bf16 v[114:117], v[184:187], v[200:203], v[114:117]
	s_waitcnt lgkmcnt(3)
	v_mfma_f32_16x16x32_bf16 v[110:113], v[176:179], v[210:213], v[110:113]
	v_mfma_f32_16x16x32_bf16 v[106:109], v[184:187], v[210:213], v[106:109]
	s_waitcnt lgkmcnt(1)
	v_mfma_f32_16x16x32_bf16 v[102:105], v[176:179], v[218:221], v[102:105]
	v_mfma_f32_16x16x32_bf16 v[98:101], v[184:187], v[218:221], v[98:101]
	v_mfma_f32_16x16x32_bf16 v[126:129], v[180:183], v[196:199], v[126:129]
	v_mfma_f32_16x16x32_bf16 v[122:125], v[188:191], v[196:199], v[122:125]
	v_mfma_f32_16x16x32_bf16 v[118:121], v[180:183], v[204:207], v[118:121]
	v_mfma_f32_16x16x32_bf16 v[114:117], v[188:191], v[204:207], v[114:117]
	v_mfma_f32_16x16x32_bf16 v[110:113], v[180:183], v[214:217], v[110:113]
	v_mfma_f32_16x16x32_bf16 v[106:109], v[188:191], v[214:217], v[106:109]
	s_waitcnt lgkmcnt(0)
	v_mfma_f32_16x16x32_bf16 v[102:105], v[180:183], v[222:225], v[102:105]
	v_mfma_f32_16x16x32_bf16 v[98:101], v[188:191], v[222:225], v[98:101]
	s_barrier
	s_add_i32 s57, 0, 0x14000
	s_add_i32 s9, s9, s39
	v_add_u32_e32 v175, s57, v173
	v_lshl_add_u64 v[246:247], v[170:171], 0, v[134:135]
	s_mov_b32 m0, s9
	ds_read_b128 v[228:231], v175
	ds_read_b128 v[232:235], v175 offset:1024
	ds_read_b128 v[236:239], v175 offset:2048
	ds_read_b128 v[240:243], v175 offset:3072
	global_load_lds_dwordx4 v[246:247], off
	v_lshl_add_u64 v[248:249], v[170:171], 0, v[144:145]
	s_add_i32 m0, s9, 0x2000
	s_nop 0
	global_load_lds_dwordx4 v[248:249], off
	s_barrier
	s_waitcnt lgkmcnt(3)
	v_mfma_f32_16x16x32_bf16 v[94:97], v[228:231], v[192:195], v[94:97]
	s_waitcnt lgkmcnt(1)
	v_mfma_f32_16x16x32_bf16 v[90:93], v[236:239], v[192:195], v[90:93]
	v_mfma_f32_16x16x32_bf16 v[86:89], v[228:231], v[200:203], v[86:89]
	v_mfma_f32_16x16x32_bf16 v[82:85], v[236:239], v[200:203], v[82:85]
	v_mfma_f32_16x16x32_bf16 v[78:81], v[228:231], v[210:213], v[78:81]
	v_mfma_f32_16x16x32_bf16 v[74:77], v[236:239], v[210:213], v[74:77]
	v_mfma_f32_16x16x32_bf16 v[70:73], v[228:231], v[218:221], v[70:73]
	v_mfma_f32_16x16x32_bf16 v[66:69], v[236:239], v[218:221], v[66:69]
	v_mfma_f32_16x16x32_bf16 v[94:97], v[232:235], v[196:199], v[94:97]
	s_waitcnt lgkmcnt(0)
	v_mfma_f32_16x16x32_bf16 v[90:93], v[240:243], v[196:199], v[90:93]
	v_mfma_f32_16x16x32_bf16 v[86:89], v[232:235], v[204:207], v[86:89]
	v_mfma_f32_16x16x32_bf16 v[82:85], v[240:243], v[204:207], v[82:85]
	v_mfma_f32_16x16x32_bf16 v[78:81], v[232:235], v[214:217], v[78:81]
	v_mfma_f32_16x16x32_bf16 v[74:77], v[240:243], v[214:217], v[74:77]
	v_mfma_f32_16x16x32_bf16 v[70:73], v[232:235], v[222:225], v[70:73]
	v_mfma_f32_16x16x32_bf16 v[66:69], v[240:243], v[222:225], v[66:69]
	s_mov_b32 m0, s34
	v_lshl_add_u64 v[250:251], v[244:245], 0, v[134:135]
	s_barrier
	ds_read_b128 v[192:195], v174 offset:16384
	ds_read_b128 v[196:199], v174 offset:17408
	ds_read_b128 v[200:203], v174 offset:18432
	ds_read_b128 v[204:207], v174 offset:19456
	ds_read_b128 v[210:213], v174 offset:20480
	ds_read_b128 v[214:217], v174 offset:21504
	ds_read_b128 v[218:221], v174 offset:22528
	ds_read_b128 v[222:225], v174 offset:23552
	global_load_lds_dwordx4 v[250:251], off
	v_lshl_add_u64 v[252:253], v[244:245], 0, v[144:145]
	s_mov_b32 m0, s41
	s_nop 0
	global_load_lds_dwordx4 v[252:253], off
	s_barrier
	s_waitcnt lgkmcnt(7)
	v_mfma_f32_16x16x32_bf16 v[62:65], v[176:179], v[192:195], v[62:65]
	v_mfma_f32_16x16x32_bf16 v[58:61], v[184:187], v[192:195], v[58:61]
	s_waitcnt lgkmcnt(5)
	v_mfma_f32_16x16x32_bf16 v[54:57], v[176:179], v[200:203], v[54:57]
	v_mfma_f32_16x16x32_bf16 v[50:53], v[184:187], v[200:203], v[50:53]
	s_waitcnt lgkmcnt(3)
	v_mfma_f32_16x16x32_bf16 v[46:49], v[176:179], v[210:213], v[46:49]
	v_mfma_f32_16x16x32_bf16 v[42:45], v[184:187], v[210:213], v[42:45]
	s_waitcnt lgkmcnt(1)
	v_mfma_f32_16x16x32_bf16 v[38:41], v[176:179], v[218:221], v[38:41]
	v_mfma_f32_16x16x32_bf16 v[34:37], v[184:187], v[218:221], v[34:37]
	v_mfma_f32_16x16x32_bf16 v[62:65], v[180:183], v[196:199], v[62:65]
	v_mfma_f32_16x16x32_bf16 v[58:61], v[188:191], v[196:199], v[58:61]
	v_mfma_f32_16x16x32_bf16 v[54:57], v[180:183], v[204:207], v[54:57]
	v_mfma_f32_16x16x32_bf16 v[50:53], v[188:191], v[204:207], v[50:53]
	v_mfma_f32_16x16x32_bf16 v[46:49], v[180:183], v[214:217], v[46:49]
	v_mfma_f32_16x16x32_bf16 v[42:45], v[188:191], v[214:217], v[42:45]
	s_waitcnt lgkmcnt(0)
	v_mfma_f32_16x16x32_bf16 v[38:41], v[180:183], v[222:225], v[38:41]
	v_mfma_f32_16x16x32_bf16 v[34:37], v[188:191], v[222:225], v[34:37]
	s_barrier
	v_lshl_add_u64 v[176:177], v[170:171], 0, s[10:11]
	s_add_i32 s9, s57, s39
	v_lshl_add_u64 v[178:179], v[176:177], 0, v[134:135]
	s_mov_b32 m0, s9
	v_lshl_add_u64 v[176:177], v[176:177], 0, v[144:145]
	global_load_lds_dwordx4 v[178:179], off
	s_add_i32 m0, s9, 0x2000
	s_nop 0
	global_load_lds_dwordx4 v[176:177], off
	s_waitcnt vmcnt(6)
	s_barrier
	v_mfma_f32_16x16x32_bf16 v[30:33], v[228:231], v[192:195], v[30:33]
	v_mfma_f32_16x16x32_bf16 v[26:29], v[236:239], v[192:195], v[26:29]
	v_mfma_f32_16x16x32_bf16 v[22:25], v[228:231], v[200:203], v[22:25]
	v_mfma_f32_16x16x32_bf16 v[18:21], v[236:239], v[200:203], v[18:21]
	v_mfma_f32_16x16x32_bf16 v[14:17], v[228:231], v[210:213], v[14:17]
	v_mfma_f32_16x16x32_bf16 v[10:13], v[236:239], v[210:213], v[10:13]
	v_mfma_f32_16x16x32_bf16 v[6:9], v[228:231], v[218:221], v[6:9]
	v_mfma_f32_16x16x32_bf16 v[2:5], v[236:239], v[218:221], v[2:5]
	v_mfma_f32_16x16x32_bf16 v[30:33], v[232:235], v[196:199], v[30:33]
	v_mfma_f32_16x16x32_bf16 v[26:29], v[240:243], v[196:199], v[26:29]
	v_mfma_f32_16x16x32_bf16 v[22:25], v[232:235], v[204:207], v[22:25]
	v_mfma_f32_16x16x32_bf16 v[18:21], v[240:243], v[204:207], v[18:21]
	v_mfma_f32_16x16x32_bf16 v[14:17], v[232:235], v[214:217], v[14:17]
	v_mfma_f32_16x16x32_bf16 v[10:13], v[240:243], v[214:217], v[10:13]
	v_mfma_f32_16x16x32_bf16 v[6:9], v[232:235], v[222:225], v[6:9]
	v_mfma_f32_16x16x32_bf16 v[2:5], v[240:243], v[222:225], v[2:5]
	s_add_i32 s9, 0, 0x18000
	v_add_u32_e32 v175, s9, v173
	s_barrier
	ds_read_b128 v[176:179], v175
	ds_read_b128 v[180:183], v175 offset:1024
	ds_read_b128 v[184:187], v175 offset:2048
	ds_read_b128 v[188:191], v175 offset:3072
	v_lshl_add_u64 v[228:229], v[244:245], 0, s[10:11]
	s_mov_b32 m0, s42
	v_lshl_add_u64 v[230:231], v[228:229], 0, v[134:135]
	ds_read_b128 v[192:195], v174 offset:32768
	ds_read_b128 v[196:199], v174 offset:33792
	ds_read_b128 v[200:203], v174 offset:34816
	ds_read_b128 v[204:207], v174 offset:35840
	ds_read_b128 v[210:213], v174 offset:36864
	ds_read_b128 v[214:217], v174 offset:37888
	ds_read_b128 v[218:221], v174 offset:38912
	ds_read_b128 v[222:225], v174 offset:39936
	global_load_lds_dwordx4 v[230:231], off
	v_lshl_add_u64 v[228:229], v[228:229], 0, v[144:145]
	s_mov_b32 m0, s43
	s_nop 0
	global_load_lds_dwordx4 v[228:229], off
	s_waitcnt lgkmcnt(8)
	s_barrier
	s_waitcnt lgkmcnt(7)
	v_mfma_f32_16x16x32_bf16 v[126:129], v[176:179], v[192:195], v[126:129]
	v_mfma_f32_16x16x32_bf16 v[122:125], v[184:187], v[192:195], v[122:125]
	s_waitcnt lgkmcnt(5)
	v_mfma_f32_16x16x32_bf16 v[118:121], v[176:179], v[200:203], v[118:121]
	v_mfma_f32_16x16x32_bf16 v[114:117], v[184:187], v[200:203], v[114:117]
	s_waitcnt lgkmcnt(3)
	v_mfma_f32_16x16x32_bf16 v[110:113], v[176:179], v[210:213], v[110:113]
	v_mfma_f32_16x16x32_bf16 v[106:109], v[184:187], v[210:213], v[106:109]
	s_waitcnt lgkmcnt(1)
	v_mfma_f32_16x16x32_bf16 v[102:105], v[176:179], v[218:221], v[102:105]
	v_mfma_f32_16x16x32_bf16 v[98:101], v[184:187], v[218:221], v[98:101]
	v_mfma_f32_16x16x32_bf16 v[126:129], v[180:183], v[196:199], v[126:129]
	v_mfma_f32_16x16x32_bf16 v[122:125], v[188:191], v[196:199], v[122:125]
	v_mfma_f32_16x16x32_bf16 v[118:121], v[180:183], v[204:207], v[118:121]
	v_mfma_f32_16x16x32_bf16 v[114:117], v[188:191], v[204:207], v[114:117]
	v_mfma_f32_16x16x32_bf16 v[110:113], v[180:183], v[214:217], v[110:113]
	v_mfma_f32_16x16x32_bf16 v[106:109], v[188:191], v[214:217], v[106:109]
	s_waitcnt lgkmcnt(0)
	v_mfma_f32_16x16x32_bf16 v[102:105], v[180:183], v[222:225], v[102:105]
	v_mfma_f32_16x16x32_bf16 v[98:101], v[188:191], v[222:225], v[98:101]
	s_barrier
	s_add_i32 s57, 0, 0x1c000
	s_add_i32 s9, s9, s39
	v_add_u32_e32 v175, s57, v173
	v_lshl_add_u64 v[244:245], v[246:247], 0, s[16:17]
	s_mov_b32 m0, s9
	ds_read_b128 v[228:231], v175
	ds_read_b128 v[232:235], v175 offset:1024
	ds_read_b128 v[236:239], v175 offset:2048
	ds_read_b128 v[240:243], v175 offset:3072
	global_load_lds_dwordx4 v[244:245], off
	v_lshl_add_u64 v[244:245], v[248:249], 0, s[16:17]
	s_add_i32 m0, s9, 0x2000
	s_nop 0
	global_load_lds_dwordx4 v[244:245], off
	s_barrier
	s_waitcnt lgkmcnt(3)
	v_mfma_f32_16x16x32_bf16 v[94:97], v[228:231], v[192:195], v[94:97]
	s_waitcnt lgkmcnt(1)
	v_mfma_f32_16x16x32_bf16 v[90:93], v[236:239], v[192:195], v[90:93]
	v_mfma_f32_16x16x32_bf16 v[86:89], v[228:231], v[200:203], v[86:89]
	v_mfma_f32_16x16x32_bf16 v[82:85], v[236:239], v[200:203], v[82:85]
	v_mfma_f32_16x16x32_bf16 v[78:81], v[228:231], v[210:213], v[78:81]
	v_mfma_f32_16x16x32_bf16 v[74:77], v[236:239], v[210:213], v[74:77]
	v_mfma_f32_16x16x32_bf16 v[70:73], v[228:231], v[218:221], v[70:73]
	v_mfma_f32_16x16x32_bf16 v[66:69], v[236:239], v[218:221], v[66:69]
	v_mfma_f32_16x16x32_bf16 v[94:97], v[232:235], v[196:199], v[94:97]
	s_waitcnt lgkmcnt(0)
	v_mfma_f32_16x16x32_bf16 v[90:93], v[240:243], v[196:199], v[90:93]
	v_mfma_f32_16x16x32_bf16 v[86:89], v[232:235], v[204:207], v[86:89]
	v_mfma_f32_16x16x32_bf16 v[82:85], v[240:243], v[204:207], v[82:85]
	v_mfma_f32_16x16x32_bf16 v[78:81], v[232:235], v[214:217], v[78:81]
	v_mfma_f32_16x16x32_bf16 v[74:77], v[240:243], v[214:217], v[74:77]
	v_mfma_f32_16x16x32_bf16 v[70:73], v[232:235], v[222:225], v[70:73]
	v_mfma_f32_16x16x32_bf16 v[66:69], v[240:243], v[222:225], v[66:69]
	s_mov_b32 m0, s55
	v_lshl_add_u64 v[244:245], v[250:251], 0, s[16:17]
	s_barrier
	ds_read_b128 v[192:195], v174 offset:49152
	ds_read_b128 v[196:199], v174 offset:50176
	ds_read_b128 v[200:203], v174 offset:51200
	ds_read_b128 v[204:207], v174 offset:52224
	ds_read_b128 v[210:213], v174 offset:53248
	ds_read_b128 v[214:217], v174 offset:54272
	ds_read_b128 v[218:221], v174 offset:55296
	ds_read_b128 v[222:225], v174 offset:56320
	global_load_lds_dwordx4 v[244:245], off
	v_lshl_add_u64 v[244:245], v[252:253], 0, s[16:17]
	s_mov_b32 m0, s56
	s_nop 0
	global_load_lds_dwordx4 v[244:245], off
	s_barrier
	s_waitcnt lgkmcnt(7)
	v_mfma_f32_16x16x32_bf16 v[62:65], v[176:179], v[192:195], v[62:65]
	v_mfma_f32_16x16x32_bf16 v[58:61], v[184:187], v[192:195], v[58:61]
	s_waitcnt lgkmcnt(5)
	v_mfma_f32_16x16x32_bf16 v[54:57], v[176:179], v[200:203], v[54:57]
	v_mfma_f32_16x16x32_bf16 v[50:53], v[184:187], v[200:203], v[50:53]
	s_waitcnt lgkmcnt(3)
	v_mfma_f32_16x16x32_bf16 v[46:49], v[176:179], v[210:213], v[46:49]
	v_mfma_f32_16x16x32_bf16 v[42:45], v[184:187], v[210:213], v[42:45]
	s_waitcnt lgkmcnt(1)
	v_mfma_f32_16x16x32_bf16 v[38:41], v[176:179], v[218:221], v[38:41]
	v_mfma_f32_16x16x32_bf16 v[34:37], v[184:187], v[218:221], v[34:37]
	v_mfma_f32_16x16x32_bf16 v[62:65], v[180:183], v[196:199], v[62:65]
	v_mfma_f32_16x16x32_bf16 v[58:61], v[188:191], v[196:199], v[58:61]
	v_mfma_f32_16x16x32_bf16 v[54:57], v[180:183], v[204:207], v[54:57]
	v_mfma_f32_16x16x32_bf16 v[50:53], v[188:191], v[204:207], v[50:53]
	v_mfma_f32_16x16x32_bf16 v[46:49], v[180:183], v[214:217], v[46:49]
	v_mfma_f32_16x16x32_bf16 v[42:45], v[188:191], v[214:217], v[42:45]
	s_waitcnt lgkmcnt(0)
	v_mfma_f32_16x16x32_bf16 v[38:41], v[180:183], v[222:225], v[38:41]
	v_mfma_f32_16x16x32_bf16 v[34:37], v[188:191], v[222:225], v[34:37]
	s_barrier
	v_lshl_add_u64 v[170:171], v[170:171], 0, s[18:19]
	s_add_i32 s9, s57, s39
	v_lshl_add_u64 v[176:177], v[170:171], 0, v[134:135]
	s_mov_b32 m0, s9
	v_lshl_add_u64 v[170:171], v[170:171], 0, v[144:145]
	global_load_lds_dwordx4 v[176:177], off
	s_add_i32 m0, s9, 0x2000
	s_nop 0
	global_load_lds_dwordx4 v[170:171], off
	s_waitcnt vmcnt(6)
	s_barrier
	v_mfma_f32_16x16x32_bf16 v[30:33], v[228:231], v[192:195], v[30:33]
	v_mfma_f32_16x16x32_bf16 v[26:29], v[236:239], v[192:195], v[26:29]
	v_mfma_f32_16x16x32_bf16 v[22:25], v[228:231], v[200:203], v[22:25]
	v_mfma_f32_16x16x32_bf16 v[18:21], v[236:239], v[200:203], v[18:21]
	v_mfma_f32_16x16x32_bf16 v[14:17], v[228:231], v[210:213], v[14:17]
	v_mfma_f32_16x16x32_bf16 v[10:13], v[236:239], v[210:213], v[10:13]
	v_mfma_f32_16x16x32_bf16 v[6:9], v[228:231], v[218:221], v[6:9]
	v_mfma_f32_16x16x32_bf16 v[2:5], v[236:239], v[218:221], v[2:5]
	v_mfma_f32_16x16x32_bf16 v[30:33], v[232:235], v[196:199], v[30:33]
	v_mfma_f32_16x16x32_bf16 v[26:29], v[240:243], v[196:199], v[26:29]
	v_mfma_f32_16x16x32_bf16 v[22:25], v[232:235], v[204:207], v[22:25]
	v_mfma_f32_16x16x32_bf16 v[18:21], v[240:243], v[204:207], v[18:21]
	v_mfma_f32_16x16x32_bf16 v[14:17], v[232:235], v[214:217], v[14:17]
	v_mfma_f32_16x16x32_bf16 v[10:13], v[240:243], v[214:217], v[10:13]
	v_mfma_f32_16x16x32_bf16 v[6:9], v[232:235], v[222:225], v[6:9]
	v_mfma_f32_16x16x32_bf16 v[2:5], v[240:243], v[222:225], v[2:5]
	s_add_i32 s8, s8, 2
	s_add_u32 s6, s6, 0x100
	s_addc_u32 s7, s7, 0
	s_cmp_lt_u32 s8, 14
	s_barrier
	s_cbranch_scc1 .LBB0_914
	s_setprio 0
	s_waitcnt vmcnt(0)
	s_cmpk_gt_u32 s38, 0xff
	s_cbranch_scc1 .LBB0_917
	s_barrier

.LBB0_1125:
	v_mov_b32_e32 v15, v0
	v_mad_i64_i32 v[148:149], s[28:29], s58, v166, v[136:137]
	v_ashrrev_i32_e32 v3, 31, v15
	v_lshrrev_b32_e32 v3, 26, v3
	v_add_u32_e32 v3, v15, v3
	v_ashrrev_i32_e32 v10, 6, v3
	v_bfe_i32 v3, v15, 27, 1
	v_lshlrev_b32_e32 v2, 4, v15
	v_lshrrev_b32_e32 v3, 22, v3
	v_add_u32_e32 v3, v2, v3
	v_and_b32_e32 v3, 0xfffffc00, v3
	v_sub_u32_e32 v3, v2, v3
	v_lshrrev_b32_e32 v4, 4, v3
	v_bitop3_b32 v3, v4, v3, 32 bitop3:0x6c
	v_ashrrev_i32_e32 v5, 31, v3
	v_lshrrev_b32_e32 v5, 26, v5
	v_add_u32_e32 v5, v3, v5
	v_lshlrev_b32_e32 v4, 3, v10
	v_ashrrev_i32_e32 v11, 6, v5
	v_and_b32_e32 v5, 0xc0, v5
	v_and_b32_e32 v4, 0xfffff0, v4
	v_sub_u32_e32 v3, v3, v5
	v_add_u32_e32 v4, v11, v4
	v_lshlrev_b32_e32 v6, 5, v10
	v_ashrrev_i16_sdwa v3, v131, sext(v3) dst_sel:DWORD dst_unused:UNUSED_PAD src0_sel:DWORD src1_sel:BYTE_0
	v_and_b32_e32 v12, 32, v6
	v_bfe_i32 v13, v3, 0, 16
	v_mul_lo_u32 v3, v4, s46
	v_or_b32_e32 v3, v3, v12
	v_add_u32_e32 v2, 0x2000, v2
	v_add_lshl_u32 v138, v3, v13, 1
	v_ashrrev_i32_e32 v3, 31, v2
	v_lshrrev_b32_e32 v3, 22, v3
	v_add_u32_e32 v3, v2, v3
	v_ashrrev_i32_e32 v14, 10, v3
	v_mul_i32_i24_e32 v3, 0x400, v14
	v_sub_u32_e32 v2, v2, v3
	v_lshrrev_b32_e32 v3, 4, v2
	v_bitop3_b32 v2, v3, v2, 32 bitop3:0x6c
	v_ashrrev_i32_e32 v4, 31, v2
	v_lshrrev_b32_e32 v4, 26, v4
	v_add_u32_e32 v4, v2, v4
	v_lshlrev_b32_e32 v3, 3, v14
	v_ashrrev_i32_e32 v16, 6, v4
	v_and_b32_e32 v4, 0xc0, v4
	v_readfirstlane_b32 s26, v15
	v_and_b32_e32 v3, 0xfffff0, v3
	v_sub_u32_e32 v2, v2, v4
	v_add_u32_e32 v3, v16, v3
	v_lshlrev_b32_e32 v5, 5, v14
	v_ashrrev_i16_sdwa v2, v131, sext(v2) dst_sel:DWORD dst_unused:UNUSED_PAD src0_sel:DWORD src1_sel:BYTE_0
	s_ashr_i32 s6, s26, 6
	v_and_b32_e32 v17, 32, v5
	v_bfe_i32 v18, v2, 0, 16
	v_mul_lo_u32 v2, v3, s46
	s_lshl_b32 s27, s6, 10
	v_or_b32_e32 v2, v2, v17
	s_add_i32 s28, s27, 0
	v_add_lshl_u32 v146, v2, v18, 1
	s_add_i32 m0, s28, 0x10000
	v_lshl_add_u64 v[2:3], v[148:149], 0, v[138:139]
	v_mov_b32_e32 v147, v139
	global_load_lds_dwordx4 v[2:3], off
	v_lshl_add_u64 v[4:5], v[148:149], 0, v[146:147]
	s_add_i32 m0, s28, 0x12000
	v_mad_i64_i32 v[150:151], s[30:31], s59, v166, v[132:133]
	global_load_lds_dwordx4 v[4:5], off
	v_lshl_add_u64 v[8:9], v[150:151], 0, v[138:139]
	s_mov_b32 m0, s28
	s_add_i32 s29, s28, 0x2000
	global_load_lds_dwordx4 v[8:9], off
	v_lshl_add_u64 v[6:7], v[150:151], 0, v[146:147]
	s_mov_b32 m0, s29
	v_lshl_add_u64 v[20:21], v[148:149], 0, s[16:17]
	global_load_lds_dwordx4 v[6:7], off
	s_add_i32 m0, s28, 0x14000
	v_lshl_add_u64 v[22:23], v[20:21], 0, v[138:139]
	global_load_lds_dwordx4 v[22:23], off
	v_lshl_add_u64 v[20:21], v[20:21], 0, v[146:147]
	s_add_i32 m0, s28, 0x16000
	s_add_i32 s31, s28, 0x4000
	global_load_lds_dwordx4 v[20:21], off
	v_lshl_add_u64 v[20:21], v[150:151], 0, s[16:17]
	v_lshl_add_u64 v[22:23], v[20:21], 0, v[138:139]
	s_mov_b32 m0, s31
	s_add_i32 s34, s28, 0x6000
	global_load_lds_dwordx4 v[22:23], off
	v_lshl_add_u64 v[20:21], v[20:21], 0, v[146:147]
	s_mov_b32 m0, s34
	s_ashr_i32 s7, s26, 8
	global_load_lds_dwordx4 v[20:21], off
	s_cmp_lg_u32 s7, 1
	s_cbranch_scc1 .LBB0_1127
	s_barrier
.LBB0_1127:
	s_add_i32 m0, s28, 0x18000
	v_lshl_add_u64 v[2:3], v[2:3], 0, s[18:19]
	s_waitcnt vmcnt(4)
	s_barrier
	global_load_lds_dwordx4 v[2:3], off
	v_lshl_add_u64 v[2:3], v[4:5], 0, s[18:19]
	s_add_i32 m0, s28, 0x1a000
	s_add_i32 s35, s28, 0x8000
	global_load_lds_dwordx4 v[2:3], off
	v_lshl_add_u64 v[2:3], v[8:9], 0, s[18:19]
	s_mov_b32 m0, s35
	s_add_i32 s36, s28, 0xa000
	global_load_lds_dwordx4 v[2:3], off
	v_lshl_add_u64 v[2:3], v[6:7], 0, s[18:19]
	s_mov_b32 m0, s36
	v_bfe_u32 v167, v15, 4, 2
	global_load_lds_dwordx4 v[2:3], off
	v_lshl_add_u64 v[2:3], v[148:149], 0, s[20:21]
	s_add_i32 m0, s28, 0x1c000
	v_lshl_add_u64 v[4:5], v[2:3], 0, v[138:139]
	global_load_lds_dwordx4 v[4:5], off
	v_lshl_add_u64 v[2:3], v[2:3], 0, v[146:147]
	s_add_i32 m0, s28, 0x1e000
	s_lshl_b32 s6, s6, 5
	global_load_lds_dwordx4 v[2:3], off
	v_and_b32_e32 v19, 15, v15
	v_lshlrev_b32_e32 v20, 4, v167
	s_and_b32 s30, s6, 0x60
	v_lshlrev_b32_e32 v15, 2, v15
	v_lshl_or_b32 v168, s7, 6, v19
	v_lshl_or_b32 v19, v19, 6, v20
	s_lshl_b32 s6, s30, 7
	v_and_b32_e32 v15, 32, v15
	v_bitop3_b32 v169, v19, s6, v15 bitop3:0xde
	s_lshl_b32 s6, s7, 13
	v_lshrrev_b32_e32 v3, 1, v10
	v_mul_lo_u32 v2, v11, s46
	v_bitop3_b32 v15, v19, s6, v15 bitop3:0xde
	v_mad_u64_u32 v[2:3], s[6:7], v3, s50, v[2:3]
	v_or_b32_e32 v2, v2, v12
	s_mul_hi_i32 s39, s59, 0x160000
	s_mul_i32 s38, s59, 0x160000
	v_add_lshl_u32 v2, v2, v13, 1
	v_mov_b32_e32 v3, v139
	v_lshl_add_u64 v[2:3], s[38:39], 0, v[2:3]
	v_lshl_add_u64 v[152:153], v[154:155], 0, v[2:3]
	v_lshrrev_b32_e32 v3, 1, v14
	v_mul_lo_u32 v2, v16, s46
	v_mad_u64_u32 v[2:3], s[6:7], v3, s50, v[2:3]
	v_or_b32_e32 v2, v2, v17
	v_add_lshl_u32 v2, v2, v18, 1
	v_mov_b32_e32 v3, v139
	s_waitcnt vmcnt(6)
	v_lshl_add_u64 v[2:3], s[38:39], 0, v[2:3]
	v_lshl_add_u64 v[162:163], v[154:155], 0, v[2:3]
	v_mov_b32_e32 v2, 0
	s_mov_b32 s37, -2
	s_mov_b64 s[6:7], 0x7330080
	v_add_u32_e32 v170, 0, v15
	v_mov_b32_e32 v3, v2
	v_mov_b32_e32 v4, v2
	v_mov_b32_e32 v5, v2
	v_mov_b32_e32 v6, v2
	v_mov_b32_e32 v7, v2
	v_mov_b32_e32 v8, v2
	v_mov_b32_e32 v9, v2
	v_mov_b32_e32 v10, v2
	v_mov_b32_e32 v11, v2
	v_mov_b32_e32 v12, v2
	v_mov_b32_e32 v13, v2
	v_mov_b32_e32 v14, v2
	v_mov_b32_e32 v15, v2
	v_mov_b32_e32 v16, v2
	v_mov_b32_e32 v17, v2
	v_mov_b32_e32 v18, v2
	v_mov_b32_e32 v19, v2
	v_mov_b32_e32 v20, v2
	v_mov_b32_e32 v21, v2
	v_mov_b32_e32 v22, v2
	v_mov_b32_e32 v23, v2
	v_mov_b32_e32 v24, v2
	v_mov_b32_e32 v25, v2
	v_mov_b32_e32 v26, v2
	v_mov_b32_e32 v27, v2
	v_mov_b32_e32 v28, v2
	v_mov_b32_e32 v29, v2
	v_mov_b32_e32 v30, v2
	v_mov_b32_e32 v31, v2
	v_mov_b32_e32 v32, v2
	v_mov_b32_e32 v33, v2
	v_mov_b32_e32 v34, v2
	v_mov_b32_e32 v35, v2
	v_mov_b32_e32 v36, v2
	v_mov_b32_e32 v37, v2
	v_mov_b32_e32 v38, v2
	v_mov_b32_e32 v39, v2
	v_mov_b32_e32 v40, v2
	v_mov_b32_e32 v41, v2
	v_mov_b32_e32 v42, v2
	v_mov_b32_e32 v43, v2
	v_mov_b32_e32 v44, v2
	v_mov_b32_e32 v45, v2
	v_mov_b32_e32 v46, v2
	v_mov_b32_e32 v47, v2
	v_mov_b32_e32 v48, v2
	v_mov_b32_e32 v49, v2
	v_mov_b32_e32 v50, v2
	v_mov_b32_e32 v51, v2
	v_mov_b32_e32 v52, v2
	v_mov_b32_e32 v53, v2
	v_mov_b32_e32 v54, v2
	v_mov_b32_e32 v55, v2
	v_mov_b32_e32 v56, v2
	v_mov_b32_e32 v57, v2
	v_mov_b32_e32 v58, v2
	v_mov_b32_e32 v59, v2
	v_mov_b32_e32 v60, v2
	v_mov_b32_e32 v61, v2
	v_mov_b32_e32 v62, v2
	v_mov_b32_e32 v63, v2
	v_mov_b32_e32 v64, v2
	v_mov_b32_e32 v65, v2
	v_mov_b32_e32 v66, v2
	v_mov_b32_e32 v67, v2
	v_mov_b32_e32 v68, v2
	v_mov_b32_e32 v69, v2
	v_mov_b32_e32 v70, v2
	v_mov_b32_e32 v71, v2
	v_mov_b32_e32 v72, v2
	v_mov_b32_e32 v73, v2
	v_mov_b32_e32 v74, v2
	v_mov_b32_e32 v75, v2
	v_mov_b32_e32 v76, v2
	v_mov_b32_e32 v77, v2
	v_mov_b32_e32 v78, v2
	v_mov_b32_e32 v79, v2
	v_mov_b32_e32 v80, v2
	v_mov_b32_e32 v81, v2
	v_mov_b32_e32 v82, v2
	v_mov_b32_e32 v83, v2
	v_mov_b32_e32 v84, v2
	v_mov_b32_e32 v85, v2
	v_mov_b32_e32 v86, v2
	v_mov_b32_e32 v87, v2
	v_mov_b32_e32 v88, v2
	v_mov_b32_e32 v89, v2
	v_mov_b32_e32 v90, v2
	v_mov_b32_e32 v91, v2
	v_mov_b32_e32 v92, v2
	v_mov_b32_e32 v93, v2
	v_mov_b32_e32 v94, v2
	v_mov_b32_e32 v95, v2
	v_mov_b32_e32 v96, v2
	v_mov_b32_e32 v97, v2
	v_mov_b32_e32 v98, v2
	v_mov_b32_e32 v99, v2
	v_mov_b32_e32 v100, v2
	v_mov_b32_e32 v101, v2
	v_mov_b32_e32 v102, v2
	v_mov_b32_e32 v103, v2
	v_mov_b32_e32 v104, v2
	v_mov_b32_e32 v105, v2
	v_mov_b32_e32 v106, v2
	v_mov_b32_e32 v107, v2
	v_mov_b32_e32 v108, v2
	v_mov_b32_e32 v109, v2
	v_mov_b32_e32 v110, v2
	v_mov_b32_e32 v111, v2
	v_mov_b32_e32 v112, v2
	v_mov_b32_e32 v113, v2
	v_mov_b32_e32 v114, v2
	v_mov_b32_e32 v115, v2
	v_mov_b32_e32 v116, v2
	v_mov_b32_e32 v117, v2
	v_mov_b32_e32 v118, v2
	v_mov_b32_e32 v119, v2
	v_mov_b32_e32 v120, v2
	v_mov_b32_e32 v121, v2
	v_mov_b32_e32 v122, v2
	v_mov_b32_e32 v123, v2
	v_mov_b32_e32 v124, v2
	v_mov_b32_e32 v125, v2
	v_mov_b32_e32 v126, v2
	v_mov_b32_e32 v127, v2
	v_mov_b32_e32 v128, v2
	v_mov_b32_e32 v129, v2
	s_barrier
	v_readfirstlane_b32 s98, v0
	s_bitcmp1_b32 s98, 8
	s_cbranch_scc0 .Lkprio_3
	s_setprio 1
.Lkprio_3:
.LBB0_1128:
	s_add_u32 s38, s6, 0xf8cd0080
	s_addc_u32 s39, s7, -1
	s_cmp_lg_u32 s37, 40
	s_cselect_b32 s39, s39, 0
	s_cselect_b32 s38, s38, 0
	s_add_i32 s40, 0, 0x10000
	v_add_u32_e32 v164, s40, v169
	ds_read_b128 v[172:175], v164
	ds_read_b128 v[176:179], v164 offset:1024
	ds_read_b128 v[180:183], v164 offset:2048
	ds_read_b128 v[184:187], v164 offset:3072
	v_lshl_add_u64 v[240:241], v[150:151], 0, s[38:39]
	v_lshl_add_u64 v[164:165], v[148:149], 0, s[38:39]
	v_lshl_add_u64 v[222:223], v[152:153], 0, s[6:7]
	s_add_i32 m0, s28, 0xc000
	ds_read_b128 v[188:191], v170
	ds_read_b128 v[192:195], v170 offset:1024
	ds_read_b128 v[196:199], v170 offset:2048
	ds_read_b128 v[200:203], v170 offset:3072
	ds_read_b128 v[204:207], v170 offset:4096
	ds_read_b128 v[210:213], v170 offset:5120
	ds_read_b128 v[214:217], v170 offset:6144
	ds_read_b128 v[218:221], v170 offset:7168
	global_load_lds_dwordx4 v[222:223], off
	v_lshl_add_u64 v[222:223], v[162:163], 0, s[6:7]
	s_add_i32 m0, s28, 0xe000
	s_nop 0
	global_load_lds_dwordx4 v[222:223], off
	s_waitcnt lgkmcnt(8)
	s_barrier
	s_waitcnt lgkmcnt(7)
	v_mfma_f32_16x16x32_bf16 v[126:129], v[172:175], v[188:191], v[126:129]
	v_mfma_f32_16x16x32_bf16 v[122:125], v[180:183], v[188:191], v[122:125]
	s_waitcnt lgkmcnt(5)
	v_mfma_f32_16x16x32_bf16 v[118:121], v[172:175], v[196:199], v[118:121]
	v_mfma_f32_16x16x32_bf16 v[114:117], v[180:183], v[196:199], v[114:117]
	s_waitcnt lgkmcnt(3)
	v_mfma_f32_16x16x32_bf16 v[110:113], v[172:175], v[204:207], v[110:113]
	v_mfma_f32_16x16x32_bf16 v[106:109], v[180:183], v[204:207], v[106:109]
	s_waitcnt lgkmcnt(1)
	v_mfma_f32_16x16x32_bf16 v[102:105], v[172:175], v[214:217], v[102:105]
	v_mfma_f32_16x16x32_bf16 v[98:101], v[180:183], v[214:217], v[98:101]
	v_mfma_f32_16x16x32_bf16 v[126:129], v[176:179], v[192:195], v[126:129]
	v_mfma_f32_16x16x32_bf16 v[122:125], v[184:187], v[192:195], v[122:125]
	v_mfma_f32_16x16x32_bf16 v[118:121], v[176:179], v[200:203], v[118:121]
	v_mfma_f32_16x16x32_bf16 v[114:117], v[184:187], v[200:203], v[114:117]
	v_mfma_f32_16x16x32_bf16 v[110:113], v[176:179], v[210:213], v[110:113]
	v_mfma_f32_16x16x32_bf16 v[106:109], v[184:187], v[210:213], v[106:109]
	s_waitcnt lgkmcnt(0)
	v_mfma_f32_16x16x32_bf16 v[102:105], v[176:179], v[218:221], v[102:105]
	v_mfma_f32_16x16x32_bf16 v[98:101], v[184:187], v[218:221], v[98:101]
	s_barrier
	s_add_i32 s38, 0, 0x14000
	s_add_i32 s39, s40, s27
	v_add_u32_e32 v171, s38, v169
	v_lshl_add_u64 v[242:243], v[164:165], 0, v[138:139]
	s_mov_b32 m0, s39
	ds_read_b128 v[222:225], v171
	ds_read_b128 v[228:231], v171 offset:1024
	ds_read_b128 v[232:235], v171 offset:2048
	ds_read_b128 v[236:239], v171 offset:3072
	global_load_lds_dwordx4 v[242:243], off
	v_lshl_add_u64 v[244:245], v[164:165], 0, v[146:147]
	s_add_i32 m0, s39, 0x2000
	s_nop 0
	global_load_lds_dwordx4 v[244:245], off
	s_barrier
	s_waitcnt lgkmcnt(3)
	v_mfma_f32_16x16x32_bf16 v[94:97], v[222:225], v[188:191], v[94:97]
	s_waitcnt lgkmcnt(1)
	v_mfma_f32_16x16x32_bf16 v[90:93], v[232:235], v[188:191], v[90:93]
	v_mfma_f32_16x16x32_bf16 v[86:89], v[222:225], v[196:199], v[86:89]
	v_mfma_f32_16x16x32_bf16 v[82:85], v[232:235], v[196:199], v[82:85]
	v_mfma_f32_16x16x32_bf16 v[78:81], v[222:225], v[204:207], v[78:81]
	v_mfma_f32_16x16x32_bf16 v[74:77], v[232:235], v[204:207], v[74:77]
	v_mfma_f32_16x16x32_bf16 v[70:73], v[222:225], v[214:217], v[70:73]
	v_mfma_f32_16x16x32_bf16 v[66:69], v[232:235], v[214:217], v[66:69]
	v_mfma_f32_16x16x32_bf16 v[94:97], v[228:231], v[192:195], v[94:97]
	s_waitcnt lgkmcnt(0)
	v_mfma_f32_16x16x32_bf16 v[90:93], v[236:239], v[192:195], v[90:93]
	v_mfma_f32_16x16x32_bf16 v[86:89], v[228:231], v[200:203], v[86:89]
	v_mfma_f32_16x16x32_bf16 v[82:85], v[236:239], v[200:203], v[82:85]
	v_mfma_f32_16x16x32_bf16 v[78:81], v[228:231], v[210:213], v[78:81]
	v_mfma_f32_16x16x32_bf16 v[74:77], v[236:239], v[210:213], v[74:77]
	v_mfma_f32_16x16x32_bf16 v[70:73], v[228:231], v[218:221], v[70:73]
	v_mfma_f32_16x16x32_bf16 v[66:69], v[236:239], v[218:221], v[66:69]
	s_mov_b32 m0, s28
	v_lshl_add_u64 v[246:247], v[240:241], 0, v[138:139]
	s_barrier
	ds_read_b128 v[188:191], v170 offset:16384
	ds_read_b128 v[192:195], v170 offset:17408
	ds_read_b128 v[196:199], v170 offset:18432
	ds_read_b128 v[200:203], v170 offset:19456
	ds_read_b128 v[204:207], v170 offset:20480
	ds_read_b128 v[210:213], v170 offset:21504
	ds_read_b128 v[214:217], v170 offset:22528
	ds_read_b128 v[218:221], v170 offset:23552
	global_load_lds_dwordx4 v[246:247], off
	v_lshl_add_u64 v[248:249], v[240:241], 0, v[146:147]
	s_mov_b32 m0, s29
	s_nop 0
	global_load_lds_dwordx4 v[248:249], off
	s_barrier
	s_waitcnt lgkmcnt(7)
	v_mfma_f32_16x16x32_bf16 v[62:65], v[172:175], v[188:191], v[62:65]
	v_mfma_f32_16x16x32_bf16 v[58:61], v[180:183], v[188:191], v[58:61]
	s_waitcnt lgkmcnt(5)
	v_mfma_f32_16x16x32_bf16 v[54:57], v[172:175], v[196:199], v[54:57]
	v_mfma_f32_16x16x32_bf16 v[50:53], v[180:183], v[196:199], v[50:53]
	s_waitcnt lgkmcnt(3)
	v_mfma_f32_16x16x32_bf16 v[46:49], v[172:175], v[204:207], v[46:49]
	v_mfma_f32_16x16x32_bf16 v[42:45], v[180:183], v[204:207], v[42:45]
	s_waitcnt lgkmcnt(1)
	v_mfma_f32_16x16x32_bf16 v[38:41], v[172:175], v[214:217], v[38:41]
	v_mfma_f32_16x16x32_bf16 v[34:37], v[180:183], v[214:217], v[34:37]
	v_mfma_f32_16x16x32_bf16 v[62:65], v[176:179], v[192:195], v[62:65]
	v_mfma_f32_16x16x32_bf16 v[58:61], v[184:187], v[192:195], v[58:61]
	v_mfma_f32_16x16x32_bf16 v[54:57], v[176:179], v[200:203], v[54:57]
	v_mfma_f32_16x16x32_bf16 v[50:53], v[184:187], v[200:203], v[50:53]
	v_mfma_f32_16x16x32_bf16 v[46:49], v[176:179], v[210:213], v[46:49]
	v_mfma_f32_16x16x32_bf16 v[42:45], v[184:187], v[210:213], v[42:45]
	s_waitcnt lgkmcnt(0)
	v_mfma_f32_16x16x32_bf16 v[38:41], v[176:179], v[218:221], v[38:41]
	v_mfma_f32_16x16x32_bf16 v[34:37], v[184:187], v[218:221], v[34:37]
	s_barrier
	v_lshl_add_u64 v[172:173], v[164:165], 0, s[16:17]
	s_add_i32 s38, s38, s27
	v_lshl_add_u64 v[174:175], v[172:173], 0, v[138:139]
	s_mov_b32 m0, s38
	v_lshl_add_u64 v[172:173], v[172:173], 0, v[146:147]
	global_load_lds_dwordx4 v[174:175], off
	s_add_i32 m0, s38, 0x2000
	s_nop 0
	global_load_lds_dwordx4 v[172:173], off
	s_waitcnt vmcnt(6)
	s_barrier
	v_mfma_f32_16x16x32_bf16 v[30:33], v[222:225], v[188:191], v[30:33]
	v_mfma_f32_16x16x32_bf16 v[26:29], v[232:235], v[188:191], v[26:29]
	v_mfma_f32_16x16x32_bf16 v[22:25], v[222:225], v[196:199], v[22:25]
	v_mfma_f32_16x16x32_bf16 v[18:21], v[232:235], v[196:199], v[18:21]
	v_mfma_f32_16x16x32_bf16 v[14:17], v[222:225], v[204:207], v[14:17]
	v_mfma_f32_16x16x32_bf16 v[10:13], v[232:235], v[204:207], v[10:13]
	v_mfma_f32_16x16x32_bf16 v[6:9], v[222:225], v[214:217], v[6:9]
	v_mfma_f32_16x16x32_bf16 v[2:5], v[232:235], v[214:217], v[2:5]
	v_mfma_f32_16x16x32_bf16 v[30:33], v[228:231], v[192:195], v[30:33]
	v_mfma_f32_16x16x32_bf16 v[26:29], v[236:239], v[192:195], v[26:29]
	v_mfma_f32_16x16x32_bf16 v[22:25], v[228:231], v[200:203], v[22:25]
	v_mfma_f32_16x16x32_bf16 v[18:21], v[236:239], v[200:203], v[18:21]
	v_mfma_f32_16x16x32_bf16 v[14:17], v[228:231], v[210:213], v[14:17]
	v_mfma_f32_16x16x32_bf16 v[10:13], v[236:239], v[210:213], v[10:13]
	v_mfma_f32_16x16x32_bf16 v[6:9], v[228:231], v[218:221], v[6:9]
	v_mfma_f32_16x16x32_bf16 v[2:5], v[236:239], v[218:221], v[2:5]
	s_add_i32 s38, 0, 0x18000
	v_add_u32_e32 v171, s38, v169
	s_barrier
	ds_read_b128 v[172:175], v171
	ds_read_b128 v[176:179], v171 offset:1024
	ds_read_b128 v[180:183], v171 offset:2048
	ds_read_b128 v[184:187], v171 offset:3072
	v_lshl_add_u64 v[222:223], v[240:241], 0, s[16:17]
	s_mov_b32 m0, s31
	v_lshl_add_u64 v[224:225], v[222:223], 0, v[138:139]
	ds_read_b128 v[188:191], v170 offset:32768
	ds_read_b128 v[192:195], v170 offset:33792
	ds_read_b128 v[196:199], v170 offset:34816
	ds_read_b128 v[200:203], v170 offset:35840
	ds_read_b128 v[204:207], v170 offset:36864
	ds_read_b128 v[210:213], v170 offset:37888
	ds_read_b128 v[214:217], v170 offset:38912
	ds_read_b128 v[218:221], v170 offset:39936
	global_load_lds_dwordx4 v[224:225], off
	v_lshl_add_u64 v[222:223], v[222:223], 0, v[146:147]
	s_mov_b32 m0, s34
	s_nop 0
	global_load_lds_dwordx4 v[222:223], off
	s_waitcnt lgkmcnt(8)
	s_barrier
	s_waitcnt lgkmcnt(7)
	v_mfma_f32_16x16x32_bf16 v[126:129], v[172:175], v[188:191], v[126:129]
	v_mfma_f32_16x16x32_bf16 v[122:125], v[180:183], v[188:191], v[122:125]
	s_waitcnt lgkmcnt(5)
	v_mfma_f32_16x16x32_bf16 v[118:121], v[172:175], v[196:199], v[118:121]
	v_mfma_f32_16x16x32_bf16 v[114:117], v[180:183], v[196:199], v[114:117]
	s_waitcnt lgkmcnt(3)
	v_mfma_f32_16x16x32_bf16 v[110:113], v[172:175], v[204:207], v[110:113]
	v_mfma_f32_16x16x32_bf16 v[106:109], v[180:183], v[204:207], v[106:109]
	s_waitcnt lgkmcnt(1)
	v_mfma_f32_16x16x32_bf16 v[102:105], v[172:175], v[214:217], v[102:105]
	v_mfma_f32_16x16x32_bf16 v[98:101], v[180:183], v[214:217], v[98:101]
	v_mfma_f32_16x16x32_bf16 v[126:129], v[176:179], v[192:195], v[126:129]
	v_mfma_f32_16x16x32_bf16 v[122:125], v[184:187], v[192:195], v[122:125]
	v_mfma_f32_16x16x32_bf16 v[118:121], v[176:179], v[200:203], v[118:121]
	v_mfma_f32_16x16x32_bf16 v[114:117], v[184:187], v[200:203], v[114:117]
	v_mfma_f32_16x16x32_bf16 v[110:113], v[176:179], v[210:213], v[110:113]
	v_mfma_f32_16x16x32_bf16 v[106:109], v[184:187], v[210:213], v[106:109]
	s_waitcnt lgkmcnt(0)
	v_mfma_f32_16x16x32_bf16 v[102:105], v[176:179], v[218:221], v[102:105]
	v_mfma_f32_16x16x32_bf16 v[98:101], v[184:187], v[218:221], v[98:101]
	s_barrier
	s_add_i32 s39, 0, 0x1c000
	s_add_i32 s38, s38, s27
	v_add_u32_e32 v171, s39, v169
	v_lshl_add_u64 v[240:241], v[242:243], 0, s[18:19]
	s_mov_b32 m0, s38
	ds_read_b128 v[222:225], v171
	ds_read_b128 v[228:231], v171 offset:1024
	ds_read_b128 v[232:235], v171 offset:2048
	ds_read_b128 v[236:239], v171 offset:3072
	global_load_lds_dwordx4 v[240:241], off
	v_lshl_add_u64 v[240:241], v[244:245], 0, s[18:19]
	s_add_i32 m0, s38, 0x2000
	s_nop 0
	global_load_lds_dwordx4 v[240:241], off
	s_barrier
	s_waitcnt lgkmcnt(3)
	v_mfma_f32_16x16x32_bf16 v[94:97], v[222:225], v[188:191], v[94:97]
	s_waitcnt lgkmcnt(1)
	v_mfma_f32_16x16x32_bf16 v[90:93], v[232:235], v[188:191], v[90:93]
	v_mfma_f32_16x16x32_bf16 v[86:89], v[222:225], v[196:199], v[86:89]
	v_mfma_f32_16x16x32_bf16 v[82:85], v[232:235], v[196:199], v[82:85]
	v_mfma_f32_16x16x32_bf16 v[78:81], v[222:225], v[204:207], v[78:81]
	v_mfma_f32_16x16x32_bf16 v[74:77], v[232:235], v[204:207], v[74:77]
	v_mfma_f32_16x16x32_bf16 v[70:73], v[222:225], v[214:217], v[70:73]
	v_mfma_f32_16x16x32_bf16 v[66:69], v[232:235], v[214:217], v[66:69]
	v_mfma_f32_16x16x32_bf16 v[94:97], v[228:231], v[192:195], v[94:97]
	s_waitcnt lgkmcnt(0)
	v_mfma_f32_16x16x32_bf16 v[90:93], v[236:239], v[192:195], v[90:93]
	v_mfma_f32_16x16x32_bf16 v[86:89], v[228:231], v[200:203], v[86:89]
	v_mfma_f32_16x16x32_bf16 v[82:85], v[236:239], v[200:203], v[82:85]
	v_mfma_f32_16x16x32_bf16 v[78:81], v[228:231], v[210:213], v[78:81]
	v_mfma_f32_16x16x32_bf16 v[74:77], v[236:239], v[210:213], v[74:77]
	v_mfma_f32_16x16x32_bf16 v[70:73], v[228:231], v[218:221], v[70:73]
	v_mfma_f32_16x16x32_bf16 v[66:69], v[236:239], v[218:221], v[66:69]
	s_mov_b32 m0, s35
	v_lshl_add_u64 v[240:241], v[246:247], 0, s[18:19]
	s_barrier
	ds_read_b128 v[188:191], v170 offset:49152
	ds_read_b128 v[192:195], v170 offset:50176
	ds_read_b128 v[196:199], v170 offset:51200
	ds_read_b128 v[200:203], v170 offset:52224
	ds_read_b128 v[204:207], v170 offset:53248
	ds_read_b128 v[210:213], v170 offset:54272
	ds_read_b128 v[214:217], v170 offset:55296
	ds_read_b128 v[218:221], v170 offset:56320
	global_load_lds_dwordx4 v[240:241], off
	v_lshl_add_u64 v[240:241], v[248:249], 0, s[18:19]
	s_mov_b32 m0, s36
	s_nop 0
	global_load_lds_dwordx4 v[240:241], off
	s_barrier
	s_waitcnt lgkmcnt(7)
	v_mfma_f32_16x16x32_bf16 v[62:65], v[172:175], v[188:191], v[62:65]
	v_mfma_f32_16x16x32_bf16 v[58:61], v[180:183], v[188:191], v[58:61]
	s_waitcnt lgkmcnt(5)
	v_mfma_f32_16x16x32_bf16 v[54:57], v[172:175], v[196:199], v[54:57]
	v_mfma_f32_16x16x32_bf16 v[50:53], v[180:183], v[196:199], v[50:53]
	s_waitcnt lgkmcnt(3)
	v_mfma_f32_16x16x32_bf16 v[46:49], v[172:175], v[204:207], v[46:49]
	v_mfma_f32_16x16x32_bf16 v[42:45], v[180:183], v[204:207], v[42:45]
	s_waitcnt lgkmcnt(1)
	v_mfma_f32_16x16x32_bf16 v[38:41], v[172:175], v[214:217], v[38:41]
	v_mfma_f32_16x16x32_bf16 v[34:37], v[180:183], v[214:217], v[34:37]
	v_mfma_f32_16x16x32_bf16 v[62:65], v[176:179], v[192:195], v[62:65]
	v_mfma_f32_16x16x32_bf16 v[58:61], v[184:187], v[192:195], v[58:61]
	v_mfma_f32_16x16x32_bf16 v[54:57], v[176:179], v[200:203], v[54:57]
	v_mfma_f32_16x16x32_bf16 v[50:53], v[184:187], v[200:203], v[50:53]
	v_mfma_f32_16x16x32_bf16 v[46:49], v[176:179], v[210:213], v[46:49]
	v_mfma_f32_16x16x32_bf16 v[42:45], v[184:187], v[210:213], v[42:45]
	s_waitcnt lgkmcnt(0)
	v_mfma_f32_16x16x32_bf16 v[38:41], v[176:179], v[218:221], v[38:41]
	v_mfma_f32_16x16x32_bf16 v[34:37], v[184:187], v[218:221], v[34:37]
	s_barrier
	v_lshl_add_u64 v[164:165], v[164:165], 0, s[20:21]
	s_add_i32 s38, s39, s27
	v_lshl_add_u64 v[172:173], v[164:165], 0, v[138:139]
	s_mov_b32 m0, s38
	v_lshl_add_u64 v[164:165], v[164:165], 0, v[146:147]
	global_load_lds_dwordx4 v[172:173], off
	s_add_i32 m0, s38, 0x2000
	s_nop 0
	global_load_lds_dwordx4 v[164:165], off
	s_waitcnt vmcnt(6)
	s_barrier
	v_mfma_f32_16x16x32_bf16 v[30:33], v[222:225], v[188:191], v[30:33]
	v_mfma_f32_16x16x32_bf16 v[26:29], v[232:235], v[188:191], v[26:29]
	v_mfma_f32_16x16x32_bf16 v[22:25], v[222:225], v[196:199], v[22:25]
	v_mfma_f32_16x16x32_bf16 v[18:21], v[232:235], v[196:199], v[18:21]
	v_mfma_f32_16x16x32_bf16 v[14:17], v[222:225], v[204:207], v[14:17]
	v_mfma_f32_16x16x32_bf16 v[10:13], v[232:235], v[204:207], v[10:13]
	v_mfma_f32_16x16x32_bf16 v[6:9], v[222:225], v[214:217], v[6:9]
	v_mfma_f32_16x16x32_bf16 v[2:5], v[232:235], v[214:217], v[2:5]
	v_mfma_f32_16x16x32_bf16 v[30:33], v[228:231], v[192:195], v[30:33]
	v_mfma_f32_16x16x32_bf16 v[26:29], v[236:239], v[192:195], v[26:29]
	v_mfma_f32_16x16x32_bf16 v[22:25], v[228:231], v[200:203], v[22:25]
	v_mfma_f32_16x16x32_bf16 v[18:21], v[236:239], v[200:203], v[18:21]
	v_mfma_f32_16x16x32_bf16 v[14:17], v[228:231], v[210:213], v[14:17]
	v_mfma_f32_16x16x32_bf16 v[10:13], v[236:239], v[210:213], v[10:13]
	v_mfma_f32_16x16x32_bf16 v[6:9], v[228:231], v[218:221], v[6:9]
	v_mfma_f32_16x16x32_bf16 v[2:5], v[236:239], v[218:221], v[2:5]
	s_add_i32 s37, s37, 2
	s_add_u32 s6, s6, 0x100
	s_addc_u32 s7, s7, 0
	s_cmp_lt_u32 s37, 42
	s_barrier
	s_cbranch_scc1 .LBB0_1128
	s_setprio 0
	s_waitcnt vmcnt(0)
	s_cmpk_gt_u32 s26, 0xff
	s_cbranch_scc1 .LBB0_1131
	s_barrier

.LBB0_1270:
	v_bfe_u32 v172, v15, 4, 2
	s_lshl_b32 s22, s39, 5
	v_and_b32_e32 v17, 15, v15
	v_lshlrev_b32_e32 v18, 4, v172
	s_and_b32 s22, s22, 0x60
	v_lshlrev_b32_e32 v15, 2, v15
	v_lshl_or_b32 v131, s40, 6, v17
	v_lshl_or_b32 v17, v17, 6, v18
	s_lshl_b32 s39, s22, 7
	v_and_b32_e32 v15, 32, v15
	v_bitop3_b32 v173, v17, s39, v15 bitop3:0xde
	s_lshl_b32 s39, s40, 13
	s_add_i32 m0, s20, 0x18000
	v_lshl_add_u64 v[2:3], v[2:3], 0, s[14:15]
	v_bitop3_b32 v15, v17, s39, v15 bitop3:0xde
	s_waitcnt vmcnt(4)
	s_barrier
	global_load_lds_dwordx4 v[2:3], off
	v_lshl_add_u64 v[2:3], v[4:5], 0, s[14:15]
	s_add_i32 m0, s20, 0x1a000
	s_add_i32 s39, s20, 0x8000
	global_load_lds_dwordx4 v[2:3], off
	v_lshl_add_u64 v[2:3], v[8:9], 0, s[14:15]
	s_mov_b32 m0, s39
	s_add_i32 s40, s20, 0xa000
	global_load_lds_dwordx4 v[2:3], off
	v_lshl_add_u64 v[2:3], v[6:7], 0, s[14:15]
	s_mov_b32 m0, s40
	v_lshl_add_u64 v[162:163], v[154:155], 0, s[24:25]
	global_load_lds_dwordx4 v[2:3], off
	v_lshl_add_u64 v[2:3], v[150:151], 0, s[16:17]
	s_add_i32 m0, s20, 0x1c000
	v_lshl_add_u64 v[4:5], v[2:3], 0, v[138:139]
	global_load_lds_dwordx4 v[4:5], off
	v_lshl_add_u64 v[2:3], v[2:3], 0, v[148:149]
	s_add_i32 m0, s20, 0x1e000
	v_lshl_add_u64 v[168:169], v[142:143], 0, s[6:7]
	global_load_lds_dwordx4 v[2:3], off
	v_lshlrev_b32_e32 v2, 14, v10
	v_and_b32_e32 v2, 0xffff8000, v2
	v_lshl_add_u32 v2, v11, 11, v2
	v_and_b32_e32 v3, 1, v10
	v_lshl_or_b32 v2, v3, 6, v2
	v_lshl_add_u32 v2, v12, 1, v2
	v_mov_b32_e32 v3, v139
	v_lshl_add_u64 v[2:3], s[24:25], 0, v[2:3]
	v_lshl_add_u64 v[164:165], v[160:161], 0, v[2:3]
	v_lshlrev_b32_e32 v2, 14, v13
	v_and_b32_e32 v2, 0xffff8000, v2
	v_lshl_add_u32 v2, v14, 11, v2
	v_and_b32_e32 v3, 1, v13
	v_lshl_or_b32 v2, v3, 6, v2
	v_lshl_add_u32 v2, v16, 1, v2
	v_mov_b32_e32 v3, v139
	s_waitcnt vmcnt(6)
	v_lshl_add_u64 v[2:3], s[24:25], 0, v[2:3]
	v_lshl_add_u64 v[166:167], v[160:161], 0, v[2:3]
	v_mov_b32_e32 v2, 0
	s_mov_b32 s24, -2
	s_mov_b64 s[6:7], 0
	v_add_u32_e32 v174, 0, v15
	v_mov_b32_e32 v3, v2
	v_mov_b32_e32 v4, v2
	v_mov_b32_e32 v5, v2
	v_mov_b32_e32 v6, v2
	v_mov_b32_e32 v7, v2
	v_mov_b32_e32 v8, v2
	v_mov_b32_e32 v9, v2
	v_mov_b32_e32 v10, v2
	v_mov_b32_e32 v11, v2
	v_mov_b32_e32 v12, v2
	v_mov_b32_e32 v13, v2
	v_mov_b32_e32 v14, v2
	v_mov_b32_e32 v15, v2
	v_mov_b32_e32 v16, v2
	v_mov_b32_e32 v17, v2
	v_mov_b32_e32 v18, v2
	v_mov_b32_e32 v19, v2
	v_mov_b32_e32 v20, v2
	v_mov_b32_e32 v21, v2
	v_mov_b32_e32 v22, v2
	v_mov_b32_e32 v23, v2
	v_mov_b32_e32 v24, v2
	v_mov_b32_e32 v25, v2
	v_mov_b32_e32 v26, v2
	v_mov_b32_e32 v27, v2
	v_mov_b32_e32 v28, v2
	v_mov_b32_e32 v29, v2
	v_mov_b32_e32 v30, v2
	v_mov_b32_e32 v31, v2
	v_mov_b32_e32 v32, v2
	v_mov_b32_e32 v33, v2
	v_mov_b32_e32 v34, v2
	v_mov_b32_e32 v35, v2
	v_mov_b32_e32 v36, v2
	v_mov_b32_e32 v37, v2
	v_mov_b32_e32 v38, v2
	v_mov_b32_e32 v39, v2
	v_mov_b32_e32 v40, v2
	v_mov_b32_e32 v41, v2
	v_mov_b32_e32 v42, v2
	v_mov_b32_e32 v43, v2
	v_mov_b32_e32 v44, v2
	v_mov_b32_e32 v45, v2
	v_mov_b32_e32 v46, v2
	v_mov_b32_e32 v47, v2
	v_mov_b32_e32 v48, v2
	v_mov_b32_e32 v49, v2
	v_mov_b32_e32 v50, v2
	v_mov_b32_e32 v51, v2
	v_mov_b32_e32 v52, v2
	v_mov_b32_e32 v53, v2
	v_mov_b32_e32 v54, v2
	v_mov_b32_e32 v55, v2
	v_mov_b32_e32 v56, v2
	v_mov_b32_e32 v57, v2
	v_mov_b32_e32 v58, v2
	v_mov_b32_e32 v59, v2
	v_mov_b32_e32 v60, v2
	v_mov_b32_e32 v61, v2
	v_mov_b32_e32 v62, v2
	v_mov_b32_e32 v63, v2
	v_mov_b32_e32 v64, v2
	v_mov_b32_e32 v65, v2
	v_mov_b32_e32 v66, v2
	v_mov_b32_e32 v67, v2
	v_mov_b32_e32 v68, v2
	v_mov_b32_e32 v69, v2
	v_mov_b32_e32 v70, v2
	v_mov_b32_e32 v71, v2
	v_mov_b32_e32 v72, v2
	v_mov_b32_e32 v73, v2
	v_mov_b32_e32 v74, v2
	v_mov_b32_e32 v75, v2
	v_mov_b32_e32 v76, v2
	v_mov_b32_e32 v77, v2
	v_mov_b32_e32 v78, v2
	v_mov_b32_e32 v79, v2
	v_mov_b32_e32 v80, v2
	v_mov_b32_e32 v81, v2
	v_mov_b32_e32 v82, v2
	v_mov_b32_e32 v83, v2
	v_mov_b32_e32 v84, v2
	v_mov_b32_e32 v85, v2
	v_mov_b32_e32 v86, v2
	v_mov_b32_e32 v87, v2
	v_mov_b32_e32 v88, v2
	v_mov_b32_e32 v89, v2
	v_mov_b32_e32 v90, v2
	v_mov_b32_e32 v91, v2
	v_mov_b32_e32 v92, v2
	v_mov_b32_e32 v93, v2
	v_mov_b32_e32 v94, v2
	v_mov_b32_e32 v95, v2
	v_mov_b32_e32 v96, v2
	v_mov_b32_e32 v97, v2
	v_mov_b32_e32 v98, v2
	v_mov_b32_e32 v99, v2
	v_mov_b32_e32 v100, v2
	v_mov_b32_e32 v101, v2
	v_mov_b32_e32 v102, v2
	v_mov_b32_e32 v103, v2
	v_mov_b32_e32 v104, v2
	v_mov_b32_e32 v105, v2
	v_mov_b32_e32 v106, v2
	v_mov_b32_e32 v107, v2
	v_mov_b32_e32 v108, v2
	v_mov_b32_e32 v109, v2
	v_mov_b32_e32 v110, v2
	v_mov_b32_e32 v111, v2
	v_mov_b32_e32 v112, v2
	v_mov_b32_e32 v113, v2
	v_mov_b32_e32 v114, v2
	v_mov_b32_e32 v115, v2
	v_mov_b32_e32 v116, v2
	v_mov_b32_e32 v117, v2
	v_mov_b32_e32 v118, v2
	v_mov_b32_e32 v119, v2
	v_mov_b32_e32 v120, v2
	v_mov_b32_e32 v121, v2
	v_mov_b32_e32 v122, v2
	v_mov_b32_e32 v123, v2
	v_mov_b32_e32 v124, v2
	v_mov_b32_e32 v125, v2
	v_mov_b32_e32 v126, v2
	v_mov_b32_e32 v127, v2
	v_mov_b32_e32 v128, v2
	v_mov_b32_e32 v129, v2
	s_barrier
	v_readfirstlane_b32 s98, v0
	s_bitcmp1_b32 s98, 8
	s_cbranch_scc0 .Lkprio_4
	s_setprio 1
.Lkprio_4:
.LBB0_1271:
	s_cmpk_eq_i32 s6, 0x700
	v_lshl_add_u64 v[170:171], v[162:163], 0, s[6:7]
	v_lshl_add_u64 v[170:171], v[170:171], 0, s[18:19]
	s_cselect_b64 vcc, -1, 0
	s_add_i32 s25, 0, 0x10000
	v_cndmask_b32_e32 v245, v171, v153, vcc
	v_add_u32_e32 v171, s25, v173
	ds_read_b128 v[176:179], v171
	ds_read_b128 v[180:183], v171 offset:1024
	ds_read_b128 v[184:187], v171 offset:2048
	ds_read_b128 v[188:191], v171 offset:3072
	v_cndmask_b32_e32 v244, v170, v152, vcc
	v_lshl_add_u64 v[170:171], v[168:169], 0, s[6:7]
	v_cndmask_b32_e32 v171, v171, v151, vcc
	v_cndmask_b32_e32 v170, v170, v150, vcc
	v_lshl_add_u64 v[228:229], v[164:165], 0, s[6:7]
	s_add_i32 m0, s20, 0xc000
	ds_read_b128 v[192:195], v174
	ds_read_b128 v[196:199], v174 offset:1024
	ds_read_b128 v[200:203], v174 offset:2048
	ds_read_b128 v[204:207], v174 offset:3072
	ds_read_b128 v[210:213], v174 offset:4096
	ds_read_b128 v[214:217], v174 offset:5120
	ds_read_b128 v[218:221], v174 offset:6144
	ds_read_b128 v[222:225], v174 offset:7168
	global_load_lds_dwordx4 v[228:229], off
	v_lshl_add_u64 v[228:229], v[166:167], 0, s[6:7]
	s_add_i32 m0, s20, 0xe000
	s_nop 0
	global_load_lds_dwordx4 v[228:229], off
	s_waitcnt lgkmcnt(8)
	s_barrier
	s_waitcnt lgkmcnt(7)
	v_mfma_f32_16x16x32_bf16 v[126:129], v[176:179], v[192:195], v[126:129]
	v_mfma_f32_16x16x32_bf16 v[122:125], v[184:187], v[192:195], v[122:125]
	s_waitcnt lgkmcnt(5)
	v_mfma_f32_16x16x32_bf16 v[118:121], v[176:179], v[200:203], v[118:121]
	v_mfma_f32_16x16x32_bf16 v[114:117], v[184:187], v[200:203], v[114:117]
	s_waitcnt lgkmcnt(3)
	v_mfma_f32_16x16x32_bf16 v[110:113], v[176:179], v[210:213], v[110:113]
	v_mfma_f32_16x16x32_bf16 v[106:109], v[184:187], v[210:213], v[106:109]
	s_waitcnt lgkmcnt(1)
	v_mfma_f32_16x16x32_bf16 v[102:105], v[176:179], v[218:221], v[102:105]
	v_mfma_f32_16x16x32_bf16 v[98:101], v[184:187], v[218:221], v[98:101]
	v_mfma_f32_16x16x32_bf16 v[126:129], v[180:183], v[196:199], v[126:129]
	v_mfma_f32_16x16x32_bf16 v[122:125], v[188:191], v[196:199], v[122:125]
	v_mfma_f32_16x16x32_bf16 v[118:121], v[180:183], v[204:207], v[118:121]
	v_mfma_f32_16x16x32_bf16 v[114:117], v[188:191], v[204:207], v[114:117]
	v_mfma_f32_16x16x32_bf16 v[110:113], v[180:183], v[214:217], v[110:113]
	v_mfma_f32_16x16x32_bf16 v[106:109], v[188:191], v[214:217], v[106:109]
	s_waitcnt lgkmcnt(0)
	v_mfma_f32_16x16x32_bf16 v[102:105], v[180:183], v[222:225], v[102:105]
	v_mfma_f32_16x16x32_bf16 v[98:101], v[188:191], v[222:225], v[98:101]
	s_barrier
	s_add_i32 s41, 0, 0x14000
	s_add_i32 s25, s25, s35
	v_add_u32_e32 v175, s41, v173
	v_lshl_add_u64 v[246:247], v[170:171], 0, v[138:139]
	s_mov_b32 m0, s25
	ds_read_b128 v[228:231], v175
	ds_read_b128 v[232:235], v175 offset:1024
	ds_read_b128 v[236:239], v175 offset:2048
	ds_read_b128 v[240:243], v175 offset:3072
	global_load_lds_dwordx4 v[246:247], off
	v_lshl_add_u64 v[248:249], v[170:171], 0, v[148:149]
	s_add_i32 m0, s25, 0x2000
	s_nop 0
	global_load_lds_dwordx4 v[248:249], off
	s_barrier
	s_waitcnt lgkmcnt(3)
	v_mfma_f32_16x16x32_bf16 v[94:97], v[228:231], v[192:195], v[94:97]
	s_waitcnt lgkmcnt(1)
	v_mfma_f32_16x16x32_bf16 v[90:93], v[236:239], v[192:195], v[90:93]
	v_mfma_f32_16x16x32_bf16 v[86:89], v[228:231], v[200:203], v[86:89]
	v_mfma_f32_16x16x32_bf16 v[82:85], v[236:239], v[200:203], v[82:85]
	v_mfma_f32_16x16x32_bf16 v[78:81], v[228:231], v[210:213], v[78:81]
	v_mfma_f32_16x16x32_bf16 v[74:77], v[236:239], v[210:213], v[74:77]
	v_mfma_f32_16x16x32_bf16 v[70:73], v[228:231], v[218:221], v[70:73]
	v_mfma_f32_16x16x32_bf16 v[66:69], v[236:239], v[218:221], v[66:69]
	v_mfma_f32_16x16x32_bf16 v[94:97], v[232:235], v[196:199], v[94:97]
	s_waitcnt lgkmcnt(0)
	v_mfma_f32_16x16x32_bf16 v[90:93], v[240:243], v[196:199], v[90:93]
	v_mfma_f32_16x16x32_bf16 v[86:89], v[232:235], v[204:207], v[86:89]
	v_mfma_f32_16x16x32_bf16 v[82:85], v[240:243], v[204:207], v[82:85]
	v_mfma_f32_16x16x32_bf16 v[78:81], v[232:235], v[214:217], v[78:81]
	v_mfma_f32_16x16x32_bf16 v[74:77], v[240:243], v[214:217], v[74:77]
	v_mfma_f32_16x16x32_bf16 v[70:73], v[232:235], v[222:225], v[70:73]
	v_mfma_f32_16x16x32_bf16 v[66:69], v[240:243], v[222:225], v[66:69]
	s_mov_b32 m0, s20
	v_lshl_add_u64 v[250:251], v[244:245], 0, v[138:139]
	s_barrier
	ds_read_b128 v[192:195], v174 offset:16384
	ds_read_b128 v[196:199], v174 offset:17408
	ds_read_b128 v[200:203], v174 offset:18432
	ds_read_b128 v[204:207], v174 offset:19456
	ds_read_b128 v[210:213], v174 offset:20480
	ds_read_b128 v[214:217], v174 offset:21504
	ds_read_b128 v[218:221], v174 offset:22528
	ds_read_b128 v[222:225], v174 offset:23552
	global_load_lds_dwordx4 v[250:251], off
	v_lshl_add_u64 v[252:253], v[244:245], 0, v[148:149]
	s_mov_b32 m0, s36
	s_nop 0
	global_load_lds_dwordx4 v[252:253], off
	s_barrier
	s_waitcnt lgkmcnt(7)
	v_mfma_f32_16x16x32_bf16 v[62:65], v[176:179], v[192:195], v[62:65]
	v_mfma_f32_16x16x32_bf16 v[58:61], v[184:187], v[192:195], v[58:61]
	s_waitcnt lgkmcnt(5)
	v_mfma_f32_16x16x32_bf16 v[54:57], v[176:179], v[200:203], v[54:57]
	v_mfma_f32_16x16x32_bf16 v[50:53], v[184:187], v[200:203], v[50:53]
	s_waitcnt lgkmcnt(3)
	v_mfma_f32_16x16x32_bf16 v[46:49], v[176:179], v[210:213], v[46:49]
	v_mfma_f32_16x16x32_bf16 v[42:45], v[184:187], v[210:213], v[42:45]
	s_waitcnt lgkmcnt(1)
	v_mfma_f32_16x16x32_bf16 v[38:41], v[176:179], v[218:221], v[38:41]
	v_mfma_f32_16x16x32_bf16 v[34:37], v[184:187], v[218:221], v[34:37]
	v_mfma_f32_16x16x32_bf16 v[62:65], v[180:183], v[196:199], v[62:65]
	v_mfma_f32_16x16x32_bf16 v[58:61], v[188:191], v[196:199], v[58:61]
	v_mfma_f32_16x16x32_bf16 v[54:57], v[180:183], v[204:207], v[54:57]
	v_mfma_f32_16x16x32_bf16 v[50:53], v[188:191], v[204:207], v[50:53]
	v_mfma_f32_16x16x32_bf16 v[46:49], v[180:183], v[214:217], v[46:49]
	v_mfma_f32_16x16x32_bf16 v[42:45], v[188:191], v[214:217], v[42:45]
	s_waitcnt lgkmcnt(0)
	v_mfma_f32_16x16x32_bf16 v[38:41], v[180:183], v[222:225], v[38:41]
	v_mfma_f32_16x16x32_bf16 v[34:37], v[188:191], v[222:225], v[34:37]
	s_barrier
	v_lshl_add_u64 v[176:177], v[170:171], 0, s[12:13]
	s_add_i32 s25, s41, s35
	v_lshl_add_u64 v[178:179], v[176:177], 0, v[138:139]
	s_mov_b32 m0, s25
	v_lshl_add_u64 v[176:177], v[176:177], 0, v[148:149]
	global_load_lds_dwordx4 v[178:179], off
	s_add_i32 m0, s25, 0x2000
	s_nop 0
	global_load_lds_dwordx4 v[176:177], off
	s_waitcnt vmcnt(6)
	s_barrier
	v_mfma_f32_16x16x32_bf16 v[30:33], v[228:231], v[192:195], v[30:33]
	v_mfma_f32_16x16x32_bf16 v[26:29], v[236:239], v[192:195], v[26:29]
	v_mfma_f32_16x16x32_bf16 v[22:25], v[228:231], v[200:203], v[22:25]
	v_mfma_f32_16x16x32_bf16 v[18:21], v[236:239], v[200:203], v[18:21]
	v_mfma_f32_16x16x32_bf16 v[14:17], v[228:231], v[210:213], v[14:17]
	v_mfma_f32_16x16x32_bf16 v[10:13], v[236:239], v[210:213], v[10:13]
	v_mfma_f32_16x16x32_bf16 v[6:9], v[228:231], v[218:221], v[6:9]
	v_mfma_f32_16x16x32_bf16 v[2:5], v[236:239], v[218:221], v[2:5]
	v_mfma_f32_16x16x32_bf16 v[30:33], v[232:235], v[196:199], v[30:33]
	v_mfma_f32_16x16x32_bf16 v[26:29], v[240:243], v[196:199], v[26:29]
	v_mfma_f32_16x16x32_bf16 v[22:25], v[232:235], v[204:207], v[22:25]
	v_mfma_f32_16x16x32_bf16 v[18:21], v[240:243], v[204:207], v[18:21]
	v_mfma_f32_16x16x32_bf16 v[14:17], v[232:235], v[214:217], v[14:17]
	v_mfma_f32_16x16x32_bf16 v[10:13], v[240:243], v[214:217], v[10:13]
	v_mfma_f32_16x16x32_bf16 v[6:9], v[232:235], v[222:225], v[6:9]
	v_mfma_f32_16x16x32_bf16 v[2:5], v[240:243], v[222:225], v[2:5]
	s_add_i32 s25, 0, 0x18000
	v_add_u32_e32 v175, s25, v173
	s_barrier
	ds_read_b128 v[176:179], v175
	ds_read_b128 v[180:183], v175 offset:1024
	ds_read_b128 v[184:187], v175 offset:2048
	ds_read_b128 v[188:191], v175 offset:3072
	v_lshl_add_u64 v[228:229], v[244:245], 0, s[12:13]
	s_mov_b32 m0, s37
	v_lshl_add_u64 v[230:231], v[228:229], 0, v[138:139]
	ds_read_b128 v[192:195], v174 offset:32768
	ds_read_b128 v[196:199], v174 offset:33792
	ds_read_b128 v[200:203], v174 offset:34816
	ds_read_b128 v[204:207], v174 offset:35840
	ds_read_b128 v[210:213], v174 offset:36864
	ds_read_b128 v[214:217], v174 offset:37888
	ds_read_b128 v[218:221], v174 offset:38912
	ds_read_b128 v[222:225], v174 offset:39936
	global_load_lds_dwordx4 v[230:231], off
	v_lshl_add_u64 v[228:229], v[228:229], 0, v[148:149]
	s_mov_b32 m0, s38
	s_nop 0
	global_load_lds_dwordx4 v[228:229], off
	s_waitcnt lgkmcnt(8)
	s_barrier
	s_waitcnt lgkmcnt(7)
	v_mfma_f32_16x16x32_bf16 v[126:129], v[176:179], v[192:195], v[126:129]
	v_mfma_f32_16x16x32_bf16 v[122:125], v[184:187], v[192:195], v[122:125]
	s_waitcnt lgkmcnt(5)
	v_mfma_f32_16x16x32_bf16 v[118:121], v[176:179], v[200:203], v[118:121]
	v_mfma_f32_16x16x32_bf16 v[114:117], v[184:187], v[200:203], v[114:117]
	s_waitcnt lgkmcnt(3)
	v_mfma_f32_16x16x32_bf16 v[110:113], v[176:179], v[210:213], v[110:113]
	v_mfma_f32_16x16x32_bf16 v[106:109], v[184:187], v[210:213], v[106:109]
	s_waitcnt lgkmcnt(1)
	v_mfma_f32_16x16x32_bf16 v[102:105], v[176:179], v[218:221], v[102:105]
	v_mfma_f32_16x16x32_bf16 v[98:101], v[184:187], v[218:221], v[98:101]
	v_mfma_f32_16x16x32_bf16 v[126:129], v[180:183], v[196:199], v[126:129]
	v_mfma_f32_16x16x32_bf16 v[122:125], v[188:191], v[196:199], v[122:125]
	v_mfma_f32_16x16x32_bf16 v[118:121], v[180:183], v[204:207], v[118:121]
	v_mfma_f32_16x16x32_bf16 v[114:117], v[188:191], v[204:207], v[114:117]
	v_mfma_f32_16x16x32_bf16 v[110:113], v[180:183], v[214:217], v[110:113]
	v_mfma_f32_16x16x32_bf16 v[106:109], v[188:191], v[214:217], v[106:109]
	s_waitcnt lgkmcnt(0)
	v_mfma_f32_16x16x32_bf16 v[102:105], v[180:183], v[222:225], v[102:105]
	v_mfma_f32_16x16x32_bf16 v[98:101], v[188:191], v[222:225], v[98:101]
	s_barrier
	s_add_i32 s41, 0, 0x1c000
	s_add_i32 s25, s25, s35
	v_add_u32_e32 v175, s41, v173
	v_lshl_add_u64 v[244:245], v[246:247], 0, s[14:15]
	s_mov_b32 m0, s25
	ds_read_b128 v[228:231], v175
	ds_read_b128 v[232:235], v175 offset:1024
	ds_read_b128 v[236:239], v175 offset:2048
	ds_read_b128 v[240:243], v175 offset:3072
	global_load_lds_dwordx4 v[244:245], off
	v_lshl_add_u64 v[244:245], v[248:249], 0, s[14:15]
	s_add_i32 m0, s25, 0x2000
	s_nop 0
	global_load_lds_dwordx4 v[244:245], off
	s_barrier
	s_waitcnt lgkmcnt(3)
	v_mfma_f32_16x16x32_bf16 v[94:97], v[228:231], v[192:195], v[94:97]
	s_waitcnt lgkmcnt(1)
	v_mfma_f32_16x16x32_bf16 v[90:93], v[236:239], v[192:195], v[90:93]
	v_mfma_f32_16x16x32_bf16 v[86:89], v[228:231], v[200:203], v[86:89]
	v_mfma_f32_16x16x32_bf16 v[82:85], v[236:239], v[200:203], v[82:85]
	v_mfma_f32_16x16x32_bf16 v[78:81], v[228:231], v[210:213], v[78:81]
	v_mfma_f32_16x16x32_bf16 v[74:77], v[236:239], v[210:213], v[74:77]
	v_mfma_f32_16x16x32_bf16 v[70:73], v[228:231], v[218:221], v[70:73]
	v_mfma_f32_16x16x32_bf16 v[66:69], v[236:239], v[218:221], v[66:69]
	v_mfma_f32_16x16x32_bf16 v[94:97], v[232:235], v[196:199], v[94:97]
	s_waitcnt lgkmcnt(0)
	v_mfma_f32_16x16x32_bf16 v[90:93], v[240:243], v[196:199], v[90:93]
	v_mfma_f32_16x16x32_bf16 v[86:89], v[232:235], v[204:207], v[86:89]
	v_mfma_f32_16x16x32_bf16 v[82:85], v[240:243], v[204:207], v[82:85]
	v_mfma_f32_16x16x32_bf16 v[78:81], v[232:235], v[214:217], v[78:81]
	v_mfma_f32_16x16x32_bf16 v[74:77], v[240:243], v[214:217], v[74:77]
	v_mfma_f32_16x16x32_bf16 v[70:73], v[232:235], v[222:225], v[70:73]
	v_mfma_f32_16x16x32_bf16 v[66:69], v[240:243], v[222:225], v[66:69]
	s_mov_b32 m0, s39
	v_lshl_add_u64 v[244:245], v[250:251], 0, s[14:15]
	s_barrier
	ds_read_b128 v[192:195], v174 offset:49152
	ds_read_b128 v[196:199], v174 offset:50176
	ds_read_b128 v[200:203], v174 offset:51200
	ds_read_b128 v[204:207], v174 offset:52224
	ds_read_b128 v[210:213], v174 offset:53248
	ds_read_b128 v[214:217], v174 offset:54272
	ds_read_b128 v[218:221], v174 offset:55296
	ds_read_b128 v[222:225], v174 offset:56320
	global_load_lds_dwordx4 v[244:245], off
	v_lshl_add_u64 v[244:245], v[252:253], 0, s[14:15]
	s_mov_b32 m0, s40
	s_nop 0
	global_load_lds_dwordx4 v[244:245], off
	s_barrier
	s_waitcnt lgkmcnt(7)
	v_mfma_f32_16x16x32_bf16 v[62:65], v[176:179], v[192:195], v[62:65]
	v_mfma_f32_16x16x32_bf16 v[58:61], v[184:187], v[192:195], v[58:61]
	s_waitcnt lgkmcnt(5)
	v_mfma_f32_16x16x32_bf16 v[54:57], v[176:179], v[200:203], v[54:57]
	v_mfma_f32_16x16x32_bf16 v[50:53], v[184:187], v[200:203], v[50:53]
	s_waitcnt lgkmcnt(3)
	v_mfma_f32_16x16x32_bf16 v[46:49], v[176:179], v[210:213], v[46:49]
	v_mfma_f32_16x16x32_bf16 v[42:45], v[184:187], v[210:213], v[42:45]
	s_waitcnt lgkmcnt(1)
	v_mfma_f32_16x16x32_bf16 v[38:41], v[176:179], v[218:221], v[38:41]
	v_mfma_f32_16x16x32_bf16 v[34:37], v[184:187], v[218:221], v[34:37]
	v_mfma_f32_16x16x32_bf16 v[62:65], v[180:183], v[196:199], v[62:65]
	v_mfma_f32_16x16x32_bf16 v[58:61], v[188:191], v[196:199], v[58:61]
	v_mfma_f32_16x16x32_bf16 v[54:57], v[180:183], v[204:207], v[54:57]
	v_mfma_f32_16x16x32_bf16 v[50:53], v[188:191], v[204:207], v[50:53]
	v_mfma_f32_16x16x32_bf16 v[46:49], v[180:183], v[214:217], v[46:49]
	v_mfma_f32_16x16x32_bf16 v[42:45], v[188:191], v[214:217], v[42:45]
	s_waitcnt lgkmcnt(0)
	v_mfma_f32_16x16x32_bf16 v[38:41], v[180:183], v[222:225], v[38:41]
	v_mfma_f32_16x16x32_bf16 v[34:37], v[188:191], v[222:225], v[34:37]
	s_barrier
	v_lshl_add_u64 v[170:171], v[170:171], 0, s[16:17]
	s_add_i32 s25, s41, s35
	v_lshl_add_u64 v[176:177], v[170:171], 0, v[138:139]
	s_mov_b32 m0, s25
	v_lshl_add_u64 v[170:171], v[170:171], 0, v[148:149]
	global_load_lds_dwordx4 v[176:177], off
	s_add_i32 m0, s25, 0x2000
	s_nop 0
	global_load_lds_dwordx4 v[170:171], off
	s_waitcnt vmcnt(6)
	s_barrier
	v_mfma_f32_16x16x32_bf16 v[30:33], v[228:231], v[192:195], v[30:33]
	v_mfma_f32_16x16x32_bf16 v[26:29], v[236:239], v[192:195], v[26:29]
	v_mfma_f32_16x16x32_bf16 v[22:25], v[228:231], v[200:203], v[22:25]
	v_mfma_f32_16x16x32_bf16 v[18:21], v[236:239], v[200:203], v[18:21]
	v_mfma_f32_16x16x32_bf16 v[14:17], v[228:231], v[210:213], v[14:17]
	v_mfma_f32_16x16x32_bf16 v[10:13], v[236:239], v[210:213], v[10:13]
	v_mfma_f32_16x16x32_bf16 v[6:9], v[228:231], v[218:221], v[6:9]
	v_mfma_f32_16x16x32_bf16 v[2:5], v[236:239], v[218:221], v[2:5]
	v_mfma_f32_16x16x32_bf16 v[30:33], v[232:235], v[196:199], v[30:33]
	v_mfma_f32_16x16x32_bf16 v[26:29], v[240:243], v[196:199], v[26:29]
	v_mfma_f32_16x16x32_bf16 v[22:25], v[232:235], v[204:207], v[22:25]
	v_mfma_f32_16x16x32_bf16 v[18:21], v[240:243], v[204:207], v[18:21]
	v_mfma_f32_16x16x32_bf16 v[14:17], v[232:235], v[214:217], v[14:17]
	v_mfma_f32_16x16x32_bf16 v[10:13], v[240:243], v[214:217], v[10:13]
	v_mfma_f32_16x16x32_bf16 v[6:9], v[232:235], v[222:225], v[6:9]
	v_mfma_f32_16x16x32_bf16 v[2:5], v[240:243], v[222:225], v[2:5]
	s_add_i32 s24, s24, 2
	s_add_u32 s6, s6, 0x100
	s_addc_u32 s7, s7, 0
	s_cmp_lt_u32 s24, 14
	s_barrier
	s_cbranch_scc1 .LBB0_1271
	s_setprio 0
	s_waitcnt vmcnt(0)
	s_cmpk_gt_u32 s27, 0xff
	s_cbranch_scc1 .LBB0_1274
	s_barrier

.LBB0_1644:
	v_bfe_u32 v131, v16, 4, 2
	s_lshl_b32 s19, s29, 5
	v_and_b32_e32 v19, 15, v16
	v_lshlrev_b32_e32 v20, 4, v131
	s_and_b32 s19, s19, 0x60
	v_lshlrev_b32_e32 v16, 2, v16
	v_lshl_or_b32 v166, s30, 6, v19
	v_lshl_or_b32 v19, v19, 6, v20
	s_lshl_b32 s29, s19, 7
	v_and_b32_e32 v16, 32, v16
	v_bitop3_b32 v167, v19, s29, v16 bitop3:0xde
	s_lshl_b32 s29, s30, 13
	s_add_i32 m0, s17, 0x18000
	v_lshl_add_u64 v[2:3], v[2:3], 0, s[10:11]
	v_bitop3_b32 v16, v19, s29, v16 bitop3:0xde
	s_waitcnt vmcnt(4)
	s_barrier
	global_load_lds_dwordx4 v[2:3], off
	v_lshl_add_u64 v[2:3], v[4:5], 0, s[10:11]
	s_add_i32 m0, s17, 0x1a000
	s_add_i32 s29, s17, 0x8000
	global_load_lds_dwordx4 v[2:3], off
	v_lshl_add_u64 v[2:3], v[8:9], 0, s[10:11]
	s_mov_b32 m0, s29
	s_add_i32 s30, s17, 0xa000
	global_load_lds_dwordx4 v[2:3], off
	v_lshl_add_u64 v[2:3], v[6:7], 0, s[10:11]
	s_mov_b32 m0, s30
	s_mov_b32 s31, -2
	global_load_lds_dwordx4 v[2:3], off
	v_lshl_add_u64 v[2:3], v[148:149], 0, s[12:13]
	s_add_i32 m0, s17, 0x1c000
	v_lshl_add_u64 v[4:5], v[2:3], 0, v[138:139]
	global_load_lds_dwordx4 v[4:5], off
	v_lshl_add_u64 v[2:3], v[2:3], 0, v[146:147]
	s_add_i32 m0, s17, 0x1e000
	v_add_u32_e32 v168, 0, v16
	global_load_lds_dwordx4 v[2:3], off
	v_lshlrev_b32_e32 v2, 13, v10
	v_and_b32_e32 v2, 0x7fffc000, v2
	v_lshl_add_u32 v2, v11, 10, v2
	v_or_b32_e32 v2, v2, v12
	v_add_lshl_u32 v2, v2, v13, 1
	v_mov_b32_e32 v3, v139
	v_lshl_add_u64 v[2:3], s[6:7], 0, v[2:3]
	v_lshl_add_u64 v[152:153], v[154:155], 0, v[2:3]
	v_lshlrev_b32_e32 v2, 13, v14
	v_and_b32_e32 v2, 0x7fffc000, v2
	v_lshl_add_u32 v2, v15, 10, v2
	v_or_b32_e32 v2, v2, v17
	v_add_lshl_u32 v2, v2, v18, 1
	v_mov_b32_e32 v3, v139
	s_waitcnt vmcnt(6)
	v_lshl_add_u64 v[2:3], s[6:7], 0, v[2:3]
	v_lshl_add_u64 v[162:163], v[154:155], 0, v[2:3]
	v_mov_b32_e32 v2, 0
	s_mov_b64 s[6:7], 0x42c0080
	v_mov_b32_e32 v3, v2
	v_mov_b32_e32 v4, v2
	v_mov_b32_e32 v5, v2
	v_mov_b32_e32 v6, v2
	v_mov_b32_e32 v7, v2
	v_mov_b32_e32 v8, v2
	v_mov_b32_e32 v9, v2
	v_mov_b32_e32 v10, v2
	v_mov_b32_e32 v11, v2
	v_mov_b32_e32 v12, v2
	v_mov_b32_e32 v13, v2
	v_mov_b32_e32 v14, v2
	v_mov_b32_e32 v15, v2
	v_mov_b32_e32 v16, v2
	v_mov_b32_e32 v17, v2
	v_mov_b32_e32 v18, v2
	v_mov_b32_e32 v19, v2
	v_mov_b32_e32 v20, v2
	v_mov_b32_e32 v21, v2
	v_mov_b32_e32 v22, v2
	v_mov_b32_e32 v23, v2
	v_mov_b32_e32 v24, v2
	v_mov_b32_e32 v25, v2
	v_mov_b32_e32 v26, v2
	v_mov_b32_e32 v27, v2
	v_mov_b32_e32 v28, v2
	v_mov_b32_e32 v29, v2
	v_mov_b32_e32 v30, v2
	v_mov_b32_e32 v31, v2
	v_mov_b32_e32 v32, v2
	v_mov_b32_e32 v33, v2
	v_mov_b32_e32 v34, v2
	v_mov_b32_e32 v35, v2
	v_mov_b32_e32 v36, v2
	v_mov_b32_e32 v37, v2
	v_mov_b32_e32 v38, v2
	v_mov_b32_e32 v39, v2
	v_mov_b32_e32 v40, v2
	v_mov_b32_e32 v41, v2
	v_mov_b32_e32 v42, v2
	v_mov_b32_e32 v43, v2
	v_mov_b32_e32 v44, v2
	v_mov_b32_e32 v45, v2
	v_mov_b32_e32 v46, v2
	v_mov_b32_e32 v47, v2
	v_mov_b32_e32 v48, v2
	v_mov_b32_e32 v49, v2
	v_mov_b32_e32 v50, v2
	v_mov_b32_e32 v51, v2
	v_mov_b32_e32 v52, v2
	v_mov_b32_e32 v53, v2
	v_mov_b32_e32 v54, v2
	v_mov_b32_e32 v55, v2
	v_mov_b32_e32 v56, v2
	v_mov_b32_e32 v57, v2
	v_mov_b32_e32 v58, v2
	v_mov_b32_e32 v59, v2
	v_mov_b32_e32 v60, v2
	v_mov_b32_e32 v61, v2
	v_mov_b32_e32 v62, v2
	v_mov_b32_e32 v63, v2
	v_mov_b32_e32 v64, v2
	v_mov_b32_e32 v65, v2
	v_mov_b32_e32 v66, v2
	v_mov_b32_e32 v67, v2
	v_mov_b32_e32 v68, v2
	v_mov_b32_e32 v69, v2
	v_mov_b32_e32 v70, v2
	v_mov_b32_e32 v71, v2
	v_mov_b32_e32 v72, v2
	v_mov_b32_e32 v73, v2
	v_mov_b32_e32 v74, v2
	v_mov_b32_e32 v75, v2
	v_mov_b32_e32 v76, v2
	v_mov_b32_e32 v77, v2
	v_mov_b32_e32 v78, v2
	v_mov_b32_e32 v79, v2
	v_mov_b32_e32 v80, v2
	v_mov_b32_e32 v81, v2
	v_mov_b32_e32 v82, v2
	v_mov_b32_e32 v83, v2
	v_mov_b32_e32 v84, v2
	v_mov_b32_e32 v85, v2
	v_mov_b32_e32 v86, v2
	v_mov_b32_e32 v87, v2
	v_mov_b32_e32 v88, v2
	v_mov_b32_e32 v89, v2
	v_mov_b32_e32 v90, v2
	v_mov_b32_e32 v91, v2
	v_mov_b32_e32 v92, v2
	v_mov_b32_e32 v93, v2
	v_mov_b32_e32 v94, v2
	v_mov_b32_e32 v95, v2
	v_mov_b32_e32 v96, v2
	v_mov_b32_e32 v97, v2
	v_mov_b32_e32 v98, v2
	v_mov_b32_e32 v99, v2
	v_mov_b32_e32 v100, v2
	v_mov_b32_e32 v101, v2
	v_mov_b32_e32 v102, v2
	v_mov_b32_e32 v103, v2
	v_mov_b32_e32 v104, v2
	v_mov_b32_e32 v105, v2
	v_mov_b32_e32 v106, v2
	v_mov_b32_e32 v107, v2
	v_mov_b32_e32 v108, v2
	v_mov_b32_e32 v109, v2
	v_mov_b32_e32 v110, v2
	v_mov_b32_e32 v111, v2
	v_mov_b32_e32 v112, v2
	v_mov_b32_e32 v113, v2
	v_mov_b32_e32 v114, v2
	v_mov_b32_e32 v115, v2
	v_mov_b32_e32 v116, v2
	v_mov_b32_e32 v117, v2
	v_mov_b32_e32 v118, v2
	v_mov_b32_e32 v119, v2
	v_mov_b32_e32 v120, v2
	v_mov_b32_e32 v121, v2
	v_mov_b32_e32 v122, v2
	v_mov_b32_e32 v123, v2
	v_mov_b32_e32 v124, v2
	v_mov_b32_e32 v125, v2
	v_mov_b32_e32 v126, v2
	v_mov_b32_e32 v127, v2
	v_mov_b32_e32 v128, v2
	v_mov_b32_e32 v129, v2
	s_barrier
	v_readfirstlane_b32 s98, v0
	s_bitcmp1_b32 s98, 8
	s_cbranch_scc0 .Lkprio_5
	s_setprio 1
.Lkprio_5:
.LBB0_1645:
	s_add_u32 s33, s6, 0xfbd40080
	s_addc_u32 s34, s7, -1
	s_cmp_lg_u32 s31, 12
	s_cselect_b32 s35, s34, 0
	s_cselect_b32 s34, s33, 0
	s_add_i32 s33, 0, 0x10000
	v_add_u32_e32 v164, s33, v167
	ds_read_b128 v[170:173], v164
	ds_read_b128 v[174:177], v164 offset:1024
	ds_read_b128 v[178:181], v164 offset:2048
	ds_read_b128 v[182:185], v164 offset:3072
	v_lshl_add_u64 v[206:207], v[150:151], 0, s[34:35]
	v_lshl_add_u64 v[164:165], v[148:149], 0, s[34:35]
	v_lshl_add_u64 v[222:223], v[152:153], 0, s[6:7]
	s_add_i32 m0, s17, 0xc000
	ds_read_b128 v[186:189], v168
	ds_read_b128 v[190:193], v168 offset:1024
	ds_read_b128 v[194:197], v168 offset:2048
	ds_read_b128 v[198:201], v168 offset:3072
	ds_read_b128 v[202:205], v168 offset:4096
	ds_read_b128 v[210:213], v168 offset:5120
	ds_read_b128 v[214:217], v168 offset:6144
	ds_read_b128 v[218:221], v168 offset:7168
	global_load_lds_dwordx4 v[222:223], off
	v_lshl_add_u64 v[222:223], v[162:163], 0, s[6:7]
	s_add_i32 m0, s17, 0xe000
	s_nop 0
	global_load_lds_dwordx4 v[222:223], off
	s_waitcnt lgkmcnt(8)
	s_barrier
	s_waitcnt lgkmcnt(7)
	v_mfma_f32_16x16x32_bf16 v[126:129], v[170:173], v[186:189], v[126:129]
	v_mfma_f32_16x16x32_bf16 v[122:125], v[178:181], v[186:189], v[122:125]
	s_waitcnt lgkmcnt(5)
	v_mfma_f32_16x16x32_bf16 v[118:121], v[170:173], v[194:197], v[118:121]
	v_mfma_f32_16x16x32_bf16 v[114:117], v[178:181], v[194:197], v[114:117]
	s_waitcnt lgkmcnt(3)
	v_mfma_f32_16x16x32_bf16 v[110:113], v[170:173], v[202:205], v[110:113]
	v_mfma_f32_16x16x32_bf16 v[106:109], v[178:181], v[202:205], v[106:109]
	s_waitcnt lgkmcnt(1)
	v_mfma_f32_16x16x32_bf16 v[102:105], v[170:173], v[214:217], v[102:105]
	v_mfma_f32_16x16x32_bf16 v[98:101], v[178:181], v[214:217], v[98:101]
	v_mfma_f32_16x16x32_bf16 v[126:129], v[174:177], v[190:193], v[126:129]
	v_mfma_f32_16x16x32_bf16 v[122:125], v[182:185], v[190:193], v[122:125]
	v_mfma_f32_16x16x32_bf16 v[118:121], v[174:177], v[198:201], v[118:121]
	v_mfma_f32_16x16x32_bf16 v[114:117], v[182:185], v[198:201], v[114:117]
	v_mfma_f32_16x16x32_bf16 v[110:113], v[174:177], v[210:213], v[110:113]
	v_mfma_f32_16x16x32_bf16 v[106:109], v[182:185], v[210:213], v[106:109]
	s_waitcnt lgkmcnt(0)
	v_mfma_f32_16x16x32_bf16 v[102:105], v[174:177], v[218:221], v[102:105]
	v_mfma_f32_16x16x32_bf16 v[98:101], v[182:185], v[218:221], v[98:101]
	s_barrier
	s_add_i32 s34, 0, 0x14000
	s_add_i32 s33, s33, s25
	v_add_u32_e32 v169, s34, v167
	v_lshl_add_u64 v[240:241], v[164:165], 0, v[138:139]
	s_mov_b32 m0, s33
	ds_read_b128 v[222:225], v169
	ds_read_b128 v[228:231], v169 offset:1024
	ds_read_b128 v[232:235], v169 offset:2048
	ds_read_b128 v[236:239], v169 offset:3072
	global_load_lds_dwordx4 v[240:241], off
	v_lshl_add_u64 v[242:243], v[164:165], 0, v[146:147]
	s_add_i32 m0, s33, 0x2000
	s_nop 0
	global_load_lds_dwordx4 v[242:243], off
	s_barrier
	s_waitcnt lgkmcnt(3)
	v_mfma_f32_16x16x32_bf16 v[94:97], v[222:225], v[186:189], v[94:97]
	s_waitcnt lgkmcnt(1)
	v_mfma_f32_16x16x32_bf16 v[90:93], v[232:235], v[186:189], v[90:93]
	v_mfma_f32_16x16x32_bf16 v[86:89], v[222:225], v[194:197], v[86:89]
	v_mfma_f32_16x16x32_bf16 v[82:85], v[232:235], v[194:197], v[82:85]
	v_mfma_f32_16x16x32_bf16 v[78:81], v[222:225], v[202:205], v[78:81]
	v_mfma_f32_16x16x32_bf16 v[74:77], v[232:235], v[202:205], v[74:77]
	v_mfma_f32_16x16x32_bf16 v[70:73], v[222:225], v[214:217], v[70:73]
	v_mfma_f32_16x16x32_bf16 v[66:69], v[232:235], v[214:217], v[66:69]
	v_mfma_f32_16x16x32_bf16 v[94:97], v[228:231], v[190:193], v[94:97]
	s_waitcnt lgkmcnt(0)
	v_mfma_f32_16x16x32_bf16 v[90:93], v[236:239], v[190:193], v[90:93]
	v_mfma_f32_16x16x32_bf16 v[86:89], v[228:231], v[198:201], v[86:89]
	v_mfma_f32_16x16x32_bf16 v[82:85], v[236:239], v[198:201], v[82:85]
	v_mfma_f32_16x16x32_bf16 v[78:81], v[228:231], v[210:213], v[78:81]
	v_mfma_f32_16x16x32_bf16 v[74:77], v[236:239], v[210:213], v[74:77]
	v_mfma_f32_16x16x32_bf16 v[70:73], v[228:231], v[218:221], v[70:73]
	v_mfma_f32_16x16x32_bf16 v[66:69], v[236:239], v[218:221], v[66:69]
	s_mov_b32 m0, s17
	v_lshl_add_u64 v[244:245], v[206:207], 0, v[138:139]
	s_barrier
	ds_read_b128 v[186:189], v168 offset:16384
	ds_read_b128 v[190:193], v168 offset:17408
	ds_read_b128 v[194:197], v168 offset:18432
	ds_read_b128 v[198:201], v168 offset:19456
	ds_read_b128 v[202:205], v168 offset:20480
	ds_read_b128 v[210:213], v168 offset:21504
	ds_read_b128 v[214:217], v168 offset:22528
	ds_read_b128 v[218:221], v168 offset:23552
	global_load_lds_dwordx4 v[244:245], off
	v_lshl_add_u64 v[246:247], v[206:207], 0, v[146:147]
	s_mov_b32 m0, s26
	s_nop 0
	global_load_lds_dwordx4 v[246:247], off
	s_barrier
	s_waitcnt lgkmcnt(7)
	v_mfma_f32_16x16x32_bf16 v[62:65], v[170:173], v[186:189], v[62:65]
	v_mfma_f32_16x16x32_bf16 v[58:61], v[178:181], v[186:189], v[58:61]
	s_waitcnt lgkmcnt(5)
	v_mfma_f32_16x16x32_bf16 v[54:57], v[170:173], v[194:197], v[54:57]
	v_mfma_f32_16x16x32_bf16 v[50:53], v[178:181], v[194:197], v[50:53]
	s_waitcnt lgkmcnt(3)
	v_mfma_f32_16x16x32_bf16 v[46:49], v[170:173], v[202:205], v[46:49]
	v_mfma_f32_16x16x32_bf16 v[42:45], v[178:181], v[202:205], v[42:45]
	s_waitcnt lgkmcnt(1)
	v_mfma_f32_16x16x32_bf16 v[38:41], v[170:173], v[214:217], v[38:41]
	v_mfma_f32_16x16x32_bf16 v[34:37], v[178:181], v[214:217], v[34:37]
	v_mfma_f32_16x16x32_bf16 v[62:65], v[174:177], v[190:193], v[62:65]
	v_mfma_f32_16x16x32_bf16 v[58:61], v[182:185], v[190:193], v[58:61]
	v_mfma_f32_16x16x32_bf16 v[54:57], v[174:177], v[198:201], v[54:57]
	v_mfma_f32_16x16x32_bf16 v[50:53], v[182:185], v[198:201], v[50:53]
	v_mfma_f32_16x16x32_bf16 v[46:49], v[174:177], v[210:213], v[46:49]
	v_mfma_f32_16x16x32_bf16 v[42:45], v[182:185], v[210:213], v[42:45]
	s_waitcnt lgkmcnt(0)
	v_mfma_f32_16x16x32_bf16 v[38:41], v[174:177], v[218:221], v[38:41]
	v_mfma_f32_16x16x32_bf16 v[34:37], v[182:185], v[218:221], v[34:37]
	s_barrier
	v_lshl_add_u64 v[170:171], v[164:165], 0, s[8:9]
	s_add_i32 s33, s34, s25
	v_lshl_add_u64 v[172:173], v[170:171], 0, v[138:139]
	s_mov_b32 m0, s33
	v_lshl_add_u64 v[170:171], v[170:171], 0, v[146:147]
	global_load_lds_dwordx4 v[172:173], off
	s_add_i32 m0, s33, 0x2000
	s_nop 0
	global_load_lds_dwordx4 v[170:171], off
	s_waitcnt vmcnt(6)
	s_barrier
	v_mfma_f32_16x16x32_bf16 v[30:33], v[222:225], v[186:189], v[30:33]
	v_mfma_f32_16x16x32_bf16 v[26:29], v[232:235], v[186:189], v[26:29]
	v_mfma_f32_16x16x32_bf16 v[22:25], v[222:225], v[194:197], v[22:25]
	v_mfma_f32_16x16x32_bf16 v[18:21], v[232:235], v[194:197], v[18:21]
	v_mfma_f32_16x16x32_bf16 v[14:17], v[222:225], v[202:205], v[14:17]
	v_mfma_f32_16x16x32_bf16 v[10:13], v[232:235], v[202:205], v[10:13]
	v_mfma_f32_16x16x32_bf16 v[6:9], v[222:225], v[214:217], v[6:9]
	v_mfma_f32_16x16x32_bf16 v[2:5], v[232:235], v[214:217], v[2:5]
	v_mfma_f32_16x16x32_bf16 v[30:33], v[228:231], v[190:193], v[30:33]
	v_mfma_f32_16x16x32_bf16 v[26:29], v[236:239], v[190:193], v[26:29]
	v_mfma_f32_16x16x32_bf16 v[22:25], v[228:231], v[198:201], v[22:25]
	v_mfma_f32_16x16x32_bf16 v[18:21], v[236:239], v[198:201], v[18:21]
	v_mfma_f32_16x16x32_bf16 v[14:17], v[228:231], v[210:213], v[14:17]
	v_mfma_f32_16x16x32_bf16 v[10:13], v[236:239], v[210:213], v[10:13]
	v_mfma_f32_16x16x32_bf16 v[6:9], v[228:231], v[218:221], v[6:9]
	v_mfma_f32_16x16x32_bf16 v[2:5], v[236:239], v[218:221], v[2:5]
	s_add_i32 s33, 0, 0x18000
	v_add_u32_e32 v169, s33, v167
	s_barrier
	ds_read_b128 v[170:173], v169
	ds_read_b128 v[174:177], v169 offset:1024
	ds_read_b128 v[178:181], v169 offset:2048
	ds_read_b128 v[182:185], v169 offset:3072
	v_lshl_add_u64 v[206:207], v[206:207], 0, s[8:9]
	s_mov_b32 m0, s27
	v_lshl_add_u64 v[222:223], v[206:207], 0, v[138:139]
	ds_read_b128 v[186:189], v168 offset:32768
	ds_read_b128 v[190:193], v168 offset:33792
	ds_read_b128 v[194:197], v168 offset:34816
	ds_read_b128 v[198:201], v168 offset:35840
	ds_read_b128 v[202:205], v168 offset:36864
	ds_read_b128 v[210:213], v168 offset:37888
	ds_read_b128 v[214:217], v168 offset:38912
	ds_read_b128 v[218:221], v168 offset:39936
	global_load_lds_dwordx4 v[222:223], off
	v_lshl_add_u64 v[206:207], v[206:207], 0, v[146:147]
	s_mov_b32 m0, s28
	s_nop 0
	global_load_lds_dwordx4 v[206:207], off
	s_waitcnt lgkmcnt(8)
	s_barrier
	s_waitcnt lgkmcnt(7)
	v_mfma_f32_16x16x32_bf16 v[126:129], v[170:173], v[186:189], v[126:129]
	v_mfma_f32_16x16x32_bf16 v[122:125], v[178:181], v[186:189], v[122:125]
	s_waitcnt lgkmcnt(5)
	v_mfma_f32_16x16x32_bf16 v[118:121], v[170:173], v[194:197], v[118:121]
	v_mfma_f32_16x16x32_bf16 v[114:117], v[178:181], v[194:197], v[114:117]
	s_waitcnt lgkmcnt(3)
	v_mfma_f32_16x16x32_bf16 v[110:113], v[170:173], v[202:205], v[110:113]
	v_mfma_f32_16x16x32_bf16 v[106:109], v[178:181], v[202:205], v[106:109]
	s_waitcnt lgkmcnt(1)
	v_mfma_f32_16x16x32_bf16 v[102:105], v[170:173], v[214:217], v[102:105]
	v_mfma_f32_16x16x32_bf16 v[98:101], v[178:181], v[214:217], v[98:101]
	v_mfma_f32_16x16x32_bf16 v[126:129], v[174:177], v[190:193], v[126:129]
	v_mfma_f32_16x16x32_bf16 v[122:125], v[182:185], v[190:193], v[122:125]
	v_mfma_f32_16x16x32_bf16 v[118:121], v[174:177], v[198:201], v[118:121]
	v_mfma_f32_16x16x32_bf16 v[114:117], v[182:185], v[198:201], v[114:117]
	v_mfma_f32_16x16x32_bf16 v[110:113], v[174:177], v[210:213], v[110:113]
	v_mfma_f32_16x16x32_bf16 v[106:109], v[182:185], v[210:213], v[106:109]
	s_waitcnt lgkmcnt(0)
	v_mfma_f32_16x16x32_bf16 v[102:105], v[174:177], v[218:221], v[102:105]
	v_mfma_f32_16x16x32_bf16 v[98:101], v[182:185], v[218:221], v[98:101]
	s_barrier
	s_add_i32 s34, 0, 0x1c000
	s_add_i32 s33, s33, s25
	v_add_u32_e32 v169, s34, v167
	v_lshl_add_u64 v[206:207], v[240:241], 0, s[10:11]
	s_mov_b32 m0, s33
	ds_read_b128 v[222:225], v169
	ds_read_b128 v[228:231], v169 offset:1024
	ds_read_b128 v[232:235], v169 offset:2048
	ds_read_b128 v[236:239], v169 offset:3072
	global_load_lds_dwordx4 v[206:207], off
	v_lshl_add_u64 v[206:207], v[242:243], 0, s[10:11]
	s_add_i32 m0, s33, 0x2000
	s_nop 0
	global_load_lds_dwordx4 v[206:207], off
	s_barrier
	s_waitcnt lgkmcnt(3)
	v_mfma_f32_16x16x32_bf16 v[94:97], v[222:225], v[186:189], v[94:97]
	s_waitcnt lgkmcnt(1)
	v_mfma_f32_16x16x32_bf16 v[90:93], v[232:235], v[186:189], v[90:93]
	v_mfma_f32_16x16x32_bf16 v[86:89], v[222:225], v[194:197], v[86:89]
	v_mfma_f32_16x16x32_bf16 v[82:85], v[232:235], v[194:197], v[82:85]
	v_mfma_f32_16x16x32_bf16 v[78:81], v[222:225], v[202:205], v[78:81]
	v_mfma_f32_16x16x32_bf16 v[74:77], v[232:235], v[202:205], v[74:77]
	v_mfma_f32_16x16x32_bf16 v[70:73], v[222:225], v[214:217], v[70:73]
	v_mfma_f32_16x16x32_bf16 v[66:69], v[232:235], v[214:217], v[66:69]
	v_mfma_f32_16x16x32_bf16 v[94:97], v[228:231], v[190:193], v[94:97]
	s_waitcnt lgkmcnt(0)
	v_mfma_f32_16x16x32_bf16 v[90:93], v[236:239], v[190:193], v[90:93]
	v_mfma_f32_16x16x32_bf16 v[86:89], v[228:231], v[198:201], v[86:89]
	v_mfma_f32_16x16x32_bf16 v[82:85], v[236:239], v[198:201], v[82:85]
	v_mfma_f32_16x16x32_bf16 v[78:81], v[228:231], v[210:213], v[78:81]
	v_mfma_f32_16x16x32_bf16 v[74:77], v[236:239], v[210:213], v[74:77]
	v_mfma_f32_16x16x32_bf16 v[70:73], v[228:231], v[218:221], v[70:73]
	v_mfma_f32_16x16x32_bf16 v[66:69], v[236:239], v[218:221], v[66:69]
	s_mov_b32 m0, s29
	v_lshl_add_u64 v[206:207], v[244:245], 0, s[10:11]
	s_barrier
	ds_read_b128 v[186:189], v168 offset:49152
	ds_read_b128 v[190:193], v168 offset:50176
	ds_read_b128 v[194:197], v168 offset:51200
	ds_read_b128 v[198:201], v168 offset:52224
	ds_read_b128 v[202:205], v168 offset:53248
	ds_read_b128 v[210:213], v168 offset:54272
	ds_read_b128 v[214:217], v168 offset:55296
	ds_read_b128 v[218:221], v168 offset:56320
	global_load_lds_dwordx4 v[206:207], off
	v_lshl_add_u64 v[206:207], v[246:247], 0, s[10:11]
	s_mov_b32 m0, s30
	s_nop 0
	global_load_lds_dwordx4 v[206:207], off
	s_barrier
	s_waitcnt lgkmcnt(7)
	v_mfma_f32_16x16x32_bf16 v[62:65], v[170:173], v[186:189], v[62:65]
	v_mfma_f32_16x16x32_bf16 v[58:61], v[178:181], v[186:189], v[58:61]
	s_waitcnt lgkmcnt(5)
	v_mfma_f32_16x16x32_bf16 v[54:57], v[170:173], v[194:197], v[54:57]
	v_mfma_f32_16x16x32_bf16 v[50:53], v[178:181], v[194:197], v[50:53]
	s_waitcnt lgkmcnt(3)
	v_mfma_f32_16x16x32_bf16 v[46:49], v[170:173], v[202:205], v[46:49]
	v_mfma_f32_16x16x32_bf16 v[42:45], v[178:181], v[202:205], v[42:45]
	s_waitcnt lgkmcnt(1)
	v_mfma_f32_16x16x32_bf16 v[38:41], v[170:173], v[214:217], v[38:41]
	v_mfma_f32_16x16x32_bf16 v[34:37], v[178:181], v[214:217], v[34:37]
	v_mfma_f32_16x16x32_bf16 v[62:65], v[174:177], v[190:193], v[62:65]
	v_mfma_f32_16x16x32_bf16 v[58:61], v[182:185], v[190:193], v[58:61]
	v_mfma_f32_16x16x32_bf16 v[54:57], v[174:177], v[198:201], v[54:57]
	v_mfma_f32_16x16x32_bf16 v[50:53], v[182:185], v[198:201], v[50:53]
	v_mfma_f32_16x16x32_bf16 v[46:49], v[174:177], v[210:213], v[46:49]
	v_mfma_f32_16x16x32_bf16 v[42:45], v[182:185], v[210:213], v[42:45]
	s_waitcnt lgkmcnt(0)
	v_mfma_f32_16x16x32_bf16 v[38:41], v[174:177], v[218:221], v[38:41]
	v_mfma_f32_16x16x32_bf16 v[34:37], v[182:185], v[218:221], v[34:37]
	s_barrier
	v_lshl_add_u64 v[164:165], v[164:165], 0, s[12:13]
	s_add_i32 s33, s34, s25
	v_lshl_add_u64 v[170:171], v[164:165], 0, v[138:139]
	s_mov_b32 m0, s33
	v_lshl_add_u64 v[164:165], v[164:165], 0, v[146:147]
	global_load_lds_dwordx4 v[170:171], off
	s_add_i32 m0, s33, 0x2000
	s_nop 0
	global_load_lds_dwordx4 v[164:165], off
	s_waitcnt vmcnt(6)
	s_barrier
	v_mfma_f32_16x16x32_bf16 v[30:33], v[222:225], v[186:189], v[30:33]
	v_mfma_f32_16x16x32_bf16 v[26:29], v[232:235], v[186:189], v[26:29]
	v_mfma_f32_16x16x32_bf16 v[22:25], v[222:225], v[194:197], v[22:25]
	v_mfma_f32_16x16x32_bf16 v[18:21], v[232:235], v[194:197], v[18:21]
	v_mfma_f32_16x16x32_bf16 v[14:17], v[222:225], v[202:205], v[14:17]
	v_mfma_f32_16x16x32_bf16 v[10:13], v[232:235], v[202:205], v[10:13]
	v_mfma_f32_16x16x32_bf16 v[6:9], v[222:225], v[214:217], v[6:9]
	v_mfma_f32_16x16x32_bf16 v[2:5], v[232:235], v[214:217], v[2:5]
	v_mfma_f32_16x16x32_bf16 v[30:33], v[228:231], v[190:193], v[30:33]
	v_mfma_f32_16x16x32_bf16 v[26:29], v[236:239], v[190:193], v[26:29]
	v_mfma_f32_16x16x32_bf16 v[22:25], v[228:231], v[198:201], v[22:25]
	v_mfma_f32_16x16x32_bf16 v[18:21], v[236:239], v[198:201], v[18:21]
	v_mfma_f32_16x16x32_bf16 v[14:17], v[228:231], v[210:213], v[14:17]
	v_mfma_f32_16x16x32_bf16 v[10:13], v[236:239], v[210:213], v[10:13]
	v_mfma_f32_16x16x32_bf16 v[6:9], v[228:231], v[218:221], v[6:9]
	v_mfma_f32_16x16x32_bf16 v[2:5], v[236:239], v[218:221], v[2:5]
	s_add_i32 s31, s31, 2
	s_add_u32 s6, s6, 0x100
	s_addc_u32 s7, s7, 0
	s_cmp_lt_u32 s31, 14
	s_barrier
	s_cbranch_scc1 .LBB0_1645
	s_setprio 0
	s_waitcnt vmcnt(0)
	s_cmpk_gt_u32 s24, 0xff
	s_cbranch_scc1 .LBB0_1648
	s_barrier

.LBB0_1787:
	v_bfe_u32 v172, v15, 4, 2
	s_lshl_b32 s40, s40, 5
	v_and_b32_e32 v17, 15, v15
	v_lshlrev_b32_e32 v18, 4, v172
	s_and_b32 s40, s40, 0x60
	v_lshlrev_b32_e32 v15, 2, v15
	v_lshl_or_b32 v1, s55, 6, v17
	v_lshl_or_b32 v17, v17, 6, v18
	s_lshl_b32 s56, s40, 7
	v_and_b32_e32 v15, 32, v15
	s_lshl_b32 s55, s55, 13
	s_add_i32 m0, s34, 0x18000
	v_lshl_add_u64 v[2:3], v[2:3], 0, s[18:19]
	v_bitop3_b32 v173, v17, s56, v15 bitop3:0xde
	v_bitop3_b32 v15, v17, s55, v15 bitop3:0xde
	s_waitcnt vmcnt(4)
	s_barrier
	global_load_lds_dwordx4 v[2:3], off
	v_lshl_add_u64 v[2:3], v[4:5], 0, s[18:19]
	s_add_i32 m0, s34, 0x1a000
	s_add_i32 s55, s34, 0x8000
	global_load_lds_dwordx4 v[2:3], off
	v_lshl_add_u64 v[2:3], v[8:9], 0, s[18:19]
	s_mov_b32 m0, s55
	s_add_i32 s56, s34, 0xa000
	global_load_lds_dwordx4 v[2:3], off
	v_lshl_add_u64 v[2:3], v[6:7], 0, s[18:19]
	s_mov_b32 m0, s56
	v_lshl_add_u64 v[162:163], v[154:155], 0, s[6:7]
	global_load_lds_dwordx4 v[2:3], off
	v_lshl_add_u64 v[2:3], v[150:151], 0, s[20:21]
	s_add_i32 m0, s34, 0x1c000
	v_lshl_add_u64 v[4:5], v[2:3], 0, v[138:139]
	global_load_lds_dwordx4 v[4:5], off
	v_lshl_add_u64 v[2:3], v[2:3], 0, v[148:149]
	s_add_i32 m0, s34, 0x1e000
	v_lshl_add_u64 v[168:169], v[142:143], 0, s[4:5]
	global_load_lds_dwordx4 v[2:3], off
	v_lshlrev_b32_e32 v2, 14, v10
	v_and_b32_e32 v2, 0xffff8000, v2
	v_lshl_add_u32 v2, v11, 11, v2
	v_and_b32_e32 v3, 1, v10
	v_lshl_or_b32 v2, v3, 6, v2
	v_lshl_add_u32 v2, v12, 1, v2
	v_mov_b32_e32 v3, v139
	v_lshl_add_u64 v[2:3], s[6:7], 0, v[2:3]
	v_lshl_add_u64 v[164:165], v[160:161], 0, v[2:3]
	v_lshlrev_b32_e32 v2, 14, v13
	v_and_b32_e32 v2, 0xffff8000, v2
	v_lshl_add_u32 v2, v14, 11, v2
	v_and_b32_e32 v3, 1, v13
	v_lshl_or_b32 v2, v3, 6, v2
	v_lshl_add_u32 v2, v16, 1, v2
	v_mov_b32_e32 v3, v139
	s_waitcnt vmcnt(6)
	v_lshl_add_u64 v[2:3], s[6:7], 0, v[2:3]
	v_lshl_add_u64 v[166:167], v[160:161], 0, v[2:3]
	v_mov_b32_e32 v2, 0
	s_mov_b32 s6, -2
	s_mov_b64 s[4:5], 0
	v_add_u32_e32 v174, 0, v15
	v_mov_b32_e32 v3, v2
	v_mov_b32_e32 v4, v2
	v_mov_b32_e32 v5, v2
	v_mov_b32_e32 v6, v2
	v_mov_b32_e32 v7, v2
	v_mov_b32_e32 v8, v2
	v_mov_b32_e32 v9, v2
	v_mov_b32_e32 v10, v2
	v_mov_b32_e32 v11, v2
	v_mov_b32_e32 v12, v2
	v_mov_b32_e32 v13, v2
	v_mov_b32_e32 v14, v2
	v_mov_b32_e32 v15, v2
	v_mov_b32_e32 v16, v2
	v_mov_b32_e32 v17, v2
	v_mov_b32_e32 v18, v2
	v_mov_b32_e32 v19, v2
	v_mov_b32_e32 v20, v2
	v_mov_b32_e32 v21, v2
	v_mov_b32_e32 v22, v2
	v_mov_b32_e32 v23, v2
	v_mov_b32_e32 v24, v2
	v_mov_b32_e32 v25, v2
	v_mov_b32_e32 v26, v2
	v_mov_b32_e32 v27, v2
	v_mov_b32_e32 v28, v2
	v_mov_b32_e32 v29, v2
	v_mov_b32_e32 v30, v2
	v_mov_b32_e32 v31, v2
	v_mov_b32_e32 v32, v2
	v_mov_b32_e32 v33, v2
	v_mov_b32_e32 v34, v2
	v_mov_b32_e32 v35, v2
	v_mov_b32_e32 v36, v2
	v_mov_b32_e32 v37, v2
	v_mov_b32_e32 v38, v2
	v_mov_b32_e32 v39, v2
	v_mov_b32_e32 v40, v2
	v_mov_b32_e32 v41, v2
	v_mov_b32_e32 v42, v2
	v_mov_b32_e32 v43, v2
	v_mov_b32_e32 v44, v2
	v_mov_b32_e32 v45, v2
	v_mov_b32_e32 v46, v2
	v_mov_b32_e32 v47, v2
	v_mov_b32_e32 v48, v2
	v_mov_b32_e32 v49, v2
	v_mov_b32_e32 v50, v2
	v_mov_b32_e32 v51, v2
	v_mov_b32_e32 v52, v2
	v_mov_b32_e32 v53, v2
	v_mov_b32_e32 v54, v2
	v_mov_b32_e32 v55, v2
	v_mov_b32_e32 v56, v2
	v_mov_b32_e32 v57, v2
	v_mov_b32_e32 v58, v2
	v_mov_b32_e32 v59, v2
	v_mov_b32_e32 v60, v2
	v_mov_b32_e32 v61, v2
	v_mov_b32_e32 v62, v2
	v_mov_b32_e32 v63, v2
	v_mov_b32_e32 v64, v2
	v_mov_b32_e32 v65, v2
	v_mov_b32_e32 v66, v2
	v_mov_b32_e32 v67, v2
	v_mov_b32_e32 v68, v2
	v_mov_b32_e32 v69, v2
	v_mov_b32_e32 v70, v2
	v_mov_b32_e32 v71, v2
	v_mov_b32_e32 v72, v2
	v_mov_b32_e32 v73, v2
	v_mov_b32_e32 v74, v2
	v_mov_b32_e32 v75, v2
	v_mov_b32_e32 v76, v2
	v_mov_b32_e32 v77, v2
	v_mov_b32_e32 v78, v2
	v_mov_b32_e32 v79, v2
	v_mov_b32_e32 v80, v2
	v_mov_b32_e32 v81, v2
	v_mov_b32_e32 v82, v2
	v_mov_b32_e32 v83, v2
	v_mov_b32_e32 v84, v2
	v_mov_b32_e32 v85, v2
	v_mov_b32_e32 v86, v2
	v_mov_b32_e32 v87, v2
	v_mov_b32_e32 v88, v2
	v_mov_b32_e32 v89, v2
	v_mov_b32_e32 v90, v2
	v_mov_b32_e32 v91, v2
	v_mov_b32_e32 v92, v2
	v_mov_b32_e32 v93, v2
	v_mov_b32_e32 v94, v2
	v_mov_b32_e32 v95, v2
	v_mov_b32_e32 v96, v2
	v_mov_b32_e32 v97, v2
	v_mov_b32_e32 v98, v2
	v_mov_b32_e32 v99, v2
	v_mov_b32_e32 v100, v2
	v_mov_b32_e32 v101, v2
	v_mov_b32_e32 v102, v2
	v_mov_b32_e32 v103, v2
	v_mov_b32_e32 v104, v2
	v_mov_b32_e32 v105, v2
	v_mov_b32_e32 v106, v2
	v_mov_b32_e32 v107, v2
	v_mov_b32_e32 v108, v2
	v_mov_b32_e32 v109, v2
	v_mov_b32_e32 v110, v2
	v_mov_b32_e32 v111, v2
	v_mov_b32_e32 v112, v2
	v_mov_b32_e32 v113, v2
	v_mov_b32_e32 v114, v2
	v_mov_b32_e32 v115, v2
	v_mov_b32_e32 v116, v2
	v_mov_b32_e32 v117, v2
	v_mov_b32_e32 v118, v2
	v_mov_b32_e32 v119, v2
	v_mov_b32_e32 v120, v2
	v_mov_b32_e32 v121, v2
	v_mov_b32_e32 v122, v2
	v_mov_b32_e32 v123, v2
	v_mov_b32_e32 v124, v2
	v_mov_b32_e32 v125, v2
	v_mov_b32_e32 v126, v2
	v_mov_b32_e32 v127, v2
	v_mov_b32_e32 v128, v2
	v_mov_b32_e32 v129, v2
	s_barrier
	v_readfirstlane_b32 s98, v0
	s_bitcmp1_b32 s98, 8
	s_cbranch_scc0 .Lkprio_6
	s_setprio 1
.Lkprio_6:
.LBB0_1788:
	s_cmpk_eq_i32 s4, 0x700
	v_lshl_add_u64 v[170:171], v[162:163], 0, s[4:5]
	v_lshl_add_u64 v[170:171], v[170:171], 0, s[22:23]
	s_cselect_b64 vcc, -1, 0
	s_add_i32 s7, 0, 0x10000
	v_cndmask_b32_e32 v245, v171, v153, vcc
	v_add_u32_e32 v171, s7, v173
	ds_read_b128 v[176:179], v171
	ds_read_b128 v[180:183], v171 offset:1024
	ds_read_b128 v[184:187], v171 offset:2048
	ds_read_b128 v[188:191], v171 offset:3072
	v_cndmask_b32_e32 v244, v170, v152, vcc
	v_lshl_add_u64 v[170:171], v[168:169], 0, s[4:5]
	v_cndmask_b32_e32 v171, v171, v151, vcc
	v_cndmask_b32_e32 v170, v170, v150, vcc
	v_lshl_add_u64 v[228:229], v[164:165], 0, s[4:5]
	s_add_i32 m0, s34, 0xc000
	ds_read_b128 v[192:195], v174
	ds_read_b128 v[196:199], v174 offset:1024
	ds_read_b128 v[200:203], v174 offset:2048
	ds_read_b128 v[204:207], v174 offset:3072
	ds_read_b128 v[210:213], v174 offset:4096
	ds_read_b128 v[214:217], v174 offset:5120
	ds_read_b128 v[218:221], v174 offset:6144
	ds_read_b128 v[222:225], v174 offset:7168
	global_load_lds_dwordx4 v[228:229], off
	v_lshl_add_u64 v[228:229], v[166:167], 0, s[4:5]
	s_add_i32 m0, s34, 0xe000
	s_nop 0
	global_load_lds_dwordx4 v[228:229], off
	s_waitcnt lgkmcnt(8)
	s_barrier
	s_waitcnt lgkmcnt(7)
	v_mfma_f32_16x16x32_bf16 v[126:129], v[176:179], v[192:195], v[126:129]
	v_mfma_f32_16x16x32_bf16 v[122:125], v[184:187], v[192:195], v[122:125]
	s_waitcnt lgkmcnt(5)
	v_mfma_f32_16x16x32_bf16 v[118:121], v[176:179], v[200:203], v[118:121]
	v_mfma_f32_16x16x32_bf16 v[114:117], v[184:187], v[200:203], v[114:117]
	s_waitcnt lgkmcnt(3)
	v_mfma_f32_16x16x32_bf16 v[110:113], v[176:179], v[210:213], v[110:113]
	v_mfma_f32_16x16x32_bf16 v[106:109], v[184:187], v[210:213], v[106:109]
	s_waitcnt lgkmcnt(1)
	v_mfma_f32_16x16x32_bf16 v[102:105], v[176:179], v[218:221], v[102:105]
	v_mfma_f32_16x16x32_bf16 v[98:101], v[184:187], v[218:221], v[98:101]
	v_mfma_f32_16x16x32_bf16 v[126:129], v[180:183], v[196:199], v[126:129]
	v_mfma_f32_16x16x32_bf16 v[122:125], v[188:191], v[196:199], v[122:125]
	v_mfma_f32_16x16x32_bf16 v[118:121], v[180:183], v[204:207], v[118:121]
	v_mfma_f32_16x16x32_bf16 v[114:117], v[188:191], v[204:207], v[114:117]
	v_mfma_f32_16x16x32_bf16 v[110:113], v[180:183], v[214:217], v[110:113]
	v_mfma_f32_16x16x32_bf16 v[106:109], v[188:191], v[214:217], v[106:109]
	s_waitcnt lgkmcnt(0)
	v_mfma_f32_16x16x32_bf16 v[102:105], v[180:183], v[222:225], v[102:105]
	v_mfma_f32_16x16x32_bf16 v[98:101], v[188:191], v[222:225], v[98:101]
	s_barrier
	s_add_i32 s57, 0, 0x14000
	s_add_i32 s7, s7, s39
	v_add_u32_e32 v175, s57, v173
	v_lshl_add_u64 v[246:247], v[170:171], 0, v[138:139]
	s_mov_b32 m0, s7
	ds_read_b128 v[228:231], v175
	ds_read_b128 v[232:235], v175 offset:1024
	ds_read_b128 v[236:239], v175 offset:2048
	ds_read_b128 v[240:243], v175 offset:3072
	global_load_lds_dwordx4 v[246:247], off
	v_lshl_add_u64 v[248:249], v[170:171], 0, v[148:149]
	s_add_i32 m0, s7, 0x2000
	s_nop 0
	global_load_lds_dwordx4 v[248:249], off
	s_barrier
	s_waitcnt lgkmcnt(3)
	v_mfma_f32_16x16x32_bf16 v[94:97], v[228:231], v[192:195], v[94:97]
	s_waitcnt lgkmcnt(1)
	v_mfma_f32_16x16x32_bf16 v[90:93], v[236:239], v[192:195], v[90:93]
	v_mfma_f32_16x16x32_bf16 v[86:89], v[228:231], v[200:203], v[86:89]
	v_mfma_f32_16x16x32_bf16 v[82:85], v[236:239], v[200:203], v[82:85]
	v_mfma_f32_16x16x32_bf16 v[78:81], v[228:231], v[210:213], v[78:81]
	v_mfma_f32_16x16x32_bf16 v[74:77], v[236:239], v[210:213], v[74:77]
	v_mfma_f32_16x16x32_bf16 v[70:73], v[228:231], v[218:221], v[70:73]
	v_mfma_f32_16x16x32_bf16 v[66:69], v[236:239], v[218:221], v[66:69]
	v_mfma_f32_16x16x32_bf16 v[94:97], v[232:235], v[196:199], v[94:97]
	s_waitcnt lgkmcnt(0)
	v_mfma_f32_16x16x32_bf16 v[90:93], v[240:243], v[196:199], v[90:93]
	v_mfma_f32_16x16x32_bf16 v[86:89], v[232:235], v[204:207], v[86:89]
	v_mfma_f32_16x16x32_bf16 v[82:85], v[240:243], v[204:207], v[82:85]
	v_mfma_f32_16x16x32_bf16 v[78:81], v[232:235], v[214:217], v[78:81]
	v_mfma_f32_16x16x32_bf16 v[74:77], v[240:243], v[214:217], v[74:77]
	v_mfma_f32_16x16x32_bf16 v[70:73], v[232:235], v[222:225], v[70:73]
	v_mfma_f32_16x16x32_bf16 v[66:69], v[240:243], v[222:225], v[66:69]
	s_mov_b32 m0, s34
	v_lshl_add_u64 v[250:251], v[244:245], 0, v[138:139]
	s_barrier
	ds_read_b128 v[192:195], v174 offset:16384
	ds_read_b128 v[196:199], v174 offset:17408
	ds_read_b128 v[200:203], v174 offset:18432
	ds_read_b128 v[204:207], v174 offset:19456
	ds_read_b128 v[210:213], v174 offset:20480
	ds_read_b128 v[214:217], v174 offset:21504
	ds_read_b128 v[218:221], v174 offset:22528
	ds_read_b128 v[222:225], v174 offset:23552
	global_load_lds_dwordx4 v[250:251], off
	v_lshl_add_u64 v[252:253], v[244:245], 0, v[148:149]
	s_mov_b32 m0, s41
	s_nop 0
	global_load_lds_dwordx4 v[252:253], off
	s_barrier
	s_waitcnt lgkmcnt(7)
	v_mfma_f32_16x16x32_bf16 v[62:65], v[176:179], v[192:195], v[62:65]
	v_mfma_f32_16x16x32_bf16 v[58:61], v[184:187], v[192:195], v[58:61]
	s_waitcnt lgkmcnt(5)
	v_mfma_f32_16x16x32_bf16 v[54:57], v[176:179], v[200:203], v[54:57]
	v_mfma_f32_16x16x32_bf16 v[50:53], v[184:187], v[200:203], v[50:53]
	s_waitcnt lgkmcnt(3)
	v_mfma_f32_16x16x32_bf16 v[46:49], v[176:179], v[210:213], v[46:49]
	v_mfma_f32_16x16x32_bf16 v[42:45], v[184:187], v[210:213], v[42:45]
	s_waitcnt lgkmcnt(1)
	v_mfma_f32_16x16x32_bf16 v[38:41], v[176:179], v[218:221], v[38:41]
	v_mfma_f32_16x16x32_bf16 v[34:37], v[184:187], v[218:221], v[34:37]
	v_mfma_f32_16x16x32_bf16 v[62:65], v[180:183], v[196:199], v[62:65]
	v_mfma_f32_16x16x32_bf16 v[58:61], v[188:191], v[196:199], v[58:61]
	v_mfma_f32_16x16x32_bf16 v[54:57], v[180:183], v[204:207], v[54:57]
	v_mfma_f32_16x16x32_bf16 v[50:53], v[188:191], v[204:207], v[50:53]
	v_mfma_f32_16x16x32_bf16 v[46:49], v[180:183], v[214:217], v[46:49]
	v_mfma_f32_16x16x32_bf16 v[42:45], v[188:191], v[214:217], v[42:45]
	s_waitcnt lgkmcnt(0)
	v_mfma_f32_16x16x32_bf16 v[38:41], v[180:183], v[222:225], v[38:41]
	v_mfma_f32_16x16x32_bf16 v[34:37], v[188:191], v[222:225], v[34:37]
	s_barrier
	v_lshl_add_u64 v[176:177], v[170:171], 0, s[16:17]
	s_add_i32 s7, s57, s39
	v_lshl_add_u64 v[178:179], v[176:177], 0, v[138:139]
	s_mov_b32 m0, s7
	v_lshl_add_u64 v[176:177], v[176:177], 0, v[148:149]
	global_load_lds_dwordx4 v[178:179], off
	s_add_i32 m0, s7, 0x2000
	s_nop 0
	global_load_lds_dwordx4 v[176:177], off
	s_waitcnt vmcnt(6)
	s_barrier
	v_mfma_f32_16x16x32_bf16 v[30:33], v[228:231], v[192:195], v[30:33]
	v_mfma_f32_16x16x32_bf16 v[26:29], v[236:239], v[192:195], v[26:29]
	v_mfma_f32_16x16x32_bf16 v[22:25], v[228:231], v[200:203], v[22:25]
	v_mfma_f32_16x16x32_bf16 v[18:21], v[236:239], v[200:203], v[18:21]
	v_mfma_f32_16x16x32_bf16 v[14:17], v[228:231], v[210:213], v[14:17]
	v_mfma_f32_16x16x32_bf16 v[10:13], v[236:239], v[210:213], v[10:13]
	v_mfma_f32_16x16x32_bf16 v[6:9], v[228:231], v[218:221], v[6:9]
	v_mfma_f32_16x16x32_bf16 v[2:5], v[236:239], v[218:221], v[2:5]
	v_mfma_f32_16x16x32_bf16 v[30:33], v[232:235], v[196:199], v[30:33]
	v_mfma_f32_16x16x32_bf16 v[26:29], v[240:243], v[196:199], v[26:29]
	v_mfma_f32_16x16x32_bf16 v[22:25], v[232:235], v[204:207], v[22:25]
	v_mfma_f32_16x16x32_bf16 v[18:21], v[240:243], v[204:207], v[18:21]
	v_mfma_f32_16x16x32_bf16 v[14:17], v[232:235], v[214:217], v[14:17]
	v_mfma_f32_16x16x32_bf16 v[10:13], v[240:243], v[214:217], v[10:13]
	v_mfma_f32_16x16x32_bf16 v[6:9], v[232:235], v[222:225], v[6:9]
	v_mfma_f32_16x16x32_bf16 v[2:5], v[240:243], v[222:225], v[2:5]
	s_add_i32 s7, 0, 0x18000
	v_add_u32_e32 v175, s7, v173
	s_barrier
	ds_read_b128 v[176:179], v175
	ds_read_b128 v[180:183], v175 offset:1024
	ds_read_b128 v[184:187], v175 offset:2048
	ds_read_b128 v[188:191], v175 offset:3072
	v_lshl_add_u64 v[228:229], v[244:245], 0, s[16:17]
	s_mov_b32 m0, s42
	v_lshl_add_u64 v[230:231], v[228:229], 0, v[138:139]
	ds_read_b128 v[192:195], v174 offset:32768
	ds_read_b128 v[196:199], v174 offset:33792
	ds_read_b128 v[200:203], v174 offset:34816
	ds_read_b128 v[204:207], v174 offset:35840
	ds_read_b128 v[210:213], v174 offset:36864
	ds_read_b128 v[214:217], v174 offset:37888
	ds_read_b128 v[218:221], v174 offset:38912
	ds_read_b128 v[222:225], v174 offset:39936
	global_load_lds_dwordx4 v[230:231], off
	v_lshl_add_u64 v[228:229], v[228:229], 0, v[148:149]
	s_mov_b32 m0, s43
	s_nop 0
	global_load_lds_dwordx4 v[228:229], off
	s_waitcnt lgkmcnt(8)
	s_barrier
	s_waitcnt lgkmcnt(7)
	v_mfma_f32_16x16x32_bf16 v[126:129], v[176:179], v[192:195], v[126:129]
	v_mfma_f32_16x16x32_bf16 v[122:125], v[184:187], v[192:195], v[122:125]
	s_waitcnt lgkmcnt(5)
	v_mfma_f32_16x16x32_bf16 v[118:121], v[176:179], v[200:203], v[118:121]
	v_mfma_f32_16x16x32_bf16 v[114:117], v[184:187], v[200:203], v[114:117]
	s_waitcnt lgkmcnt(3)
	v_mfma_f32_16x16x32_bf16 v[110:113], v[176:179], v[210:213], v[110:113]
	v_mfma_f32_16x16x32_bf16 v[106:109], v[184:187], v[210:213], v[106:109]
	s_waitcnt lgkmcnt(1)
	v_mfma_f32_16x16x32_bf16 v[102:105], v[176:179], v[218:221], v[102:105]
	v_mfma_f32_16x16x32_bf16 v[98:101], v[184:187], v[218:221], v[98:101]
	v_mfma_f32_16x16x32_bf16 v[126:129], v[180:183], v[196:199], v[126:129]
	v_mfma_f32_16x16x32_bf16 v[122:125], v[188:191], v[196:199], v[122:125]
	v_mfma_f32_16x16x32_bf16 v[118:121], v[180:183], v[204:207], v[118:121]
	v_mfma_f32_16x16x32_bf16 v[114:117], v[188:191], v[204:207], v[114:117]
	v_mfma_f32_16x16x32_bf16 v[110:113], v[180:183], v[214:217], v[110:113]
	v_mfma_f32_16x16x32_bf16 v[106:109], v[188:191], v[214:217], v[106:109]
	s_waitcnt lgkmcnt(0)
	v_mfma_f32_16x16x32_bf16 v[102:105], v[180:183], v[222:225], v[102:105]
	v_mfma_f32_16x16x32_bf16 v[98:101], v[188:191], v[222:225], v[98:101]
	s_barrier
	s_add_i32 s57, 0, 0x1c000
	s_add_i32 s7, s7, s39
	v_add_u32_e32 v175, s57, v173
	v_lshl_add_u64 v[244:245], v[246:247], 0, s[18:19]
	s_mov_b32 m0, s7
	ds_read_b128 v[228:231], v175
	ds_read_b128 v[232:235], v175 offset:1024
	ds_read_b128 v[236:239], v175 offset:2048
	ds_read_b128 v[240:243], v175 offset:3072
	global_load_lds_dwordx4 v[244:245], off
	v_lshl_add_u64 v[244:245], v[248:249], 0, s[18:19]
	s_add_i32 m0, s7, 0x2000
	s_nop 0
	global_load_lds_dwordx4 v[244:245], off
	s_barrier
	s_waitcnt lgkmcnt(3)
	v_mfma_f32_16x16x32_bf16 v[94:97], v[228:231], v[192:195], v[94:97]
	s_waitcnt lgkmcnt(1)
	v_mfma_f32_16x16x32_bf16 v[90:93], v[236:239], v[192:195], v[90:93]
	v_mfma_f32_16x16x32_bf16 v[86:89], v[228:231], v[200:203], v[86:89]
	v_mfma_f32_16x16x32_bf16 v[82:85], v[236:239], v[200:203], v[82:85]
	v_mfma_f32_16x16x32_bf16 v[78:81], v[228:231], v[210:213], v[78:81]
	v_mfma_f32_16x16x32_bf16 v[74:77], v[236:239], v[210:213], v[74:77]
	v_mfma_f32_16x16x32_bf16 v[70:73], v[228:231], v[218:221], v[70:73]
	v_mfma_f32_16x16x32_bf16 v[66:69], v[236:239], v[218:221], v[66:69]
	v_mfma_f32_16x16x32_bf16 v[94:97], v[232:235], v[196:199], v[94:97]
	s_waitcnt lgkmcnt(0)
	v_mfma_f32_16x16x32_bf16 v[90:93], v[240:243], v[196:199], v[90:93]
	v_mfma_f32_16x16x32_bf16 v[86:89], v[232:235], v[204:207], v[86:89]
	v_mfma_f32_16x16x32_bf16 v[82:85], v[240:243], v[204:207], v[82:85]
	v_mfma_f32_16x16x32_bf16 v[78:81], v[232:235], v[214:217], v[78:81]
	v_mfma_f32_16x16x32_bf16 v[74:77], v[240:243], v[214:217], v[74:77]
	v_mfma_f32_16x16x32_bf16 v[70:73], v[232:235], v[222:225], v[70:73]
	v_mfma_f32_16x16x32_bf16 v[66:69], v[240:243], v[222:225], v[66:69]
	s_mov_b32 m0, s55
	v_lshl_add_u64 v[244:245], v[250:251], 0, s[18:19]
	s_barrier
	ds_read_b128 v[192:195], v174 offset:49152
	ds_read_b128 v[196:199], v174 offset:50176
	ds_read_b128 v[200:203], v174 offset:51200
	ds_read_b128 v[204:207], v174 offset:52224
	ds_read_b128 v[210:213], v174 offset:53248
	ds_read_b128 v[214:217], v174 offset:54272
	ds_read_b128 v[218:221], v174 offset:55296
	ds_read_b128 v[222:225], v174 offset:56320
	global_load_lds_dwordx4 v[244:245], off
	v_lshl_add_u64 v[244:245], v[252:253], 0, s[18:19]
	s_mov_b32 m0, s56
	s_nop 0
	global_load_lds_dwordx4 v[244:245], off
	s_barrier
	s_waitcnt lgkmcnt(7)
	v_mfma_f32_16x16x32_bf16 v[62:65], v[176:179], v[192:195], v[62:65]
	v_mfma_f32_16x16x32_bf16 v[58:61], v[184:187], v[192:195], v[58:61]
	s_waitcnt lgkmcnt(5)
	v_mfma_f32_16x16x32_bf16 v[54:57], v[176:179], v[200:203], v[54:57]
	v_mfma_f32_16x16x32_bf16 v[50:53], v[184:187], v[200:203], v[50:53]
	s_waitcnt lgkmcnt(3)
	v_mfma_f32_16x16x32_bf16 v[46:49], v[176:179], v[210:213], v[46:49]
	v_mfma_f32_16x16x32_bf16 v[42:45], v[184:187], v[210:213], v[42:45]
	s_waitcnt lgkmcnt(1)
	v_mfma_f32_16x16x32_bf16 v[38:41], v[176:179], v[218:221], v[38:41]
	v_mfma_f32_16x16x32_bf16 v[34:37], v[184:187], v[218:221], v[34:37]
	v_mfma_f32_16x16x32_bf16 v[62:65], v[180:183], v[196:199], v[62:65]
	v_mfma_f32_16x16x32_bf16 v[58:61], v[188:191], v[196:199], v[58:61]
	v_mfma_f32_16x16x32_bf16 v[54:57], v[180:183], v[204:207], v[54:57]
	v_mfma_f32_16x16x32_bf16 v[50:53], v[188:191], v[204:207], v[50:53]
	v_mfma_f32_16x16x32_bf16 v[46:49], v[180:183], v[214:217], v[46:49]
	v_mfma_f32_16x16x32_bf16 v[42:45], v[188:191], v[214:217], v[42:45]
	s_waitcnt lgkmcnt(0)
	v_mfma_f32_16x16x32_bf16 v[38:41], v[180:183], v[222:225], v[38:41]
	v_mfma_f32_16x16x32_bf16 v[34:37], v[188:191], v[222:225], v[34:37]
	s_barrier
	v_lshl_add_u64 v[170:171], v[170:171], 0, s[20:21]
	s_add_i32 s7, s57, s39
	v_lshl_add_u64 v[176:177], v[170:171], 0, v[138:139]
	s_mov_b32 m0, s7
	v_lshl_add_u64 v[170:171], v[170:171], 0, v[148:149]
	global_load_lds_dwordx4 v[176:177], off
	s_add_i32 m0, s7, 0x2000
	s_nop 0
	global_load_lds_dwordx4 v[170:171], off
	s_waitcnt vmcnt(6)
	s_barrier
	v_mfma_f32_16x16x32_bf16 v[30:33], v[228:231], v[192:195], v[30:33]
	v_mfma_f32_16x16x32_bf16 v[26:29], v[236:239], v[192:195], v[26:29]
	v_mfma_f32_16x16x32_bf16 v[22:25], v[228:231], v[200:203], v[22:25]
	v_mfma_f32_16x16x32_bf16 v[18:21], v[236:239], v[200:203], v[18:21]
	v_mfma_f32_16x16x32_bf16 v[14:17], v[228:231], v[210:213], v[14:17]
	v_mfma_f32_16x16x32_bf16 v[10:13], v[236:239], v[210:213], v[10:13]
	v_mfma_f32_16x16x32_bf16 v[6:9], v[228:231], v[218:221], v[6:9]
	v_mfma_f32_16x16x32_bf16 v[2:5], v[236:239], v[218:221], v[2:5]
	v_mfma_f32_16x16x32_bf16 v[30:33], v[232:235], v[196:199], v[30:33]
	v_mfma_f32_16x16x32_bf16 v[26:29], v[240:243], v[196:199], v[26:29]
	v_mfma_f32_16x16x32_bf16 v[22:25], v[232:235], v[204:207], v[22:25]
	v_mfma_f32_16x16x32_bf16 v[18:21], v[240:243], v[204:207], v[18:21]
	v_mfma_f32_16x16x32_bf16 v[14:17], v[232:235], v[214:217], v[14:17]
	v_mfma_f32_16x16x32_bf16 v[10:13], v[240:243], v[214:217], v[10:13]
	v_mfma_f32_16x16x32_bf16 v[6:9], v[232:235], v[222:225], v[6:9]
	v_mfma_f32_16x16x32_bf16 v[2:5], v[240:243], v[222:225], v[2:5]
	s_add_i32 s6, s6, 2
	s_add_u32 s4, s4, 0x100
	s_addc_u32 s5, s5, 0
	s_cmp_lt_u32 s6, 14
	s_barrier
	s_cbranch_scc1 .LBB0_1788
	s_setprio 0
	s_waitcnt vmcnt(0)
	s_cmpk_gt_u32 s38, 0xff
	s_cbranch_scc1 .LBB0_1791
	s_barrier

.LBB0_1913:
	s_add_i32 m0, s28, 0x18000
	v_lshl_add_u64 v[2:3], v[2:3], 0, s[18:19]
	s_waitcnt vmcnt(4)
	s_barrier
	global_load_lds_dwordx4 v[2:3], off
	v_lshl_add_u64 v[2:3], v[4:5], 0, s[18:19]
	s_add_i32 m0, s28, 0x1a000
	s_add_i32 s35, s28, 0x8000
	global_load_lds_dwordx4 v[2:3], off
	v_lshl_add_u64 v[2:3], v[8:9], 0, s[18:19]
	s_mov_b32 m0, s35
	s_add_i32 s36, s28, 0xa000
	global_load_lds_dwordx4 v[2:3], off
	v_lshl_add_u64 v[2:3], v[6:7], 0, s[18:19]
	s_mov_b32 m0, s36
	v_bfe_u32 v160, v15, 4, 2
	global_load_lds_dwordx4 v[2:3], off
	v_lshl_add_u64 v[2:3], v[146:147], 0, s[20:21]
	s_add_i32 m0, s28, 0x1c000
	v_lshl_add_u64 v[4:5], v[2:3], 0, v[130:131]
	global_load_lds_dwordx4 v[4:5], off
	v_lshl_add_u64 v[2:3], v[2:3], 0, v[144:145]
	s_add_i32 m0, s28, 0x1e000
	s_lshl_b32 s4, s4, 5
	global_load_lds_dwordx4 v[2:3], off
	v_and_b32_e32 v19, 15, v15
	v_lshlrev_b32_e32 v20, 4, v160
	s_and_b32 s30, s4, 0x60
	v_lshlrev_b32_e32 v15, 2, v15
	v_lshl_or_b32 v161, s5, 6, v19
	v_lshl_or_b32 v19, v19, 6, v20
	s_lshl_b32 s4, s30, 7
	v_and_b32_e32 v15, 32, v15
	v_bitop3_b32 v162, v19, s4, v15 bitop3:0xde
	s_lshl_b32 s4, s5, 13
	v_lshrrev_b32_e32 v3, 1, v10
	v_mul_lo_u32 v2, v11, s46
	v_bitop3_b32 v15, v19, s4, v15 bitop3:0xde
	v_mad_u64_u32 v[2:3], s[4:5], v3, s51, v[2:3]
	v_or_b32_e32 v2, v2, v12
	s_mul_hi_i32 s39, s56, 0x160000
	s_mul_i32 s38, s56, 0x160000
	v_add_lshl_u32 v2, v2, v13, 1
	v_mov_b32_e32 v3, v131
	v_lshl_add_u64 v[2:3], s[38:39], 0, v[2:3]
	v_lshl_add_u64 v[150:151], v[154:155], 0, v[2:3]
	v_lshrrev_b32_e32 v3, 1, v14
	v_mul_lo_u32 v2, v16, s46
	v_mad_u64_u32 v[2:3], s[4:5], v3, s51, v[2:3]
	v_or_b32_e32 v2, v2, v17
	v_add_lshl_u32 v2, v2, v18, 1
	v_mov_b32_e32 v3, v131
	s_waitcnt vmcnt(6)
	v_lshl_add_u64 v[2:3], s[38:39], 0, v[2:3]
	v_lshl_add_u64 v[152:153], v[154:155], 0, v[2:3]
	v_mov_b32_e32 v2, 0
	s_mov_b32 s37, -2
	s_mov_b64 s[4:5], 0x7330080
	v_add_u32_e32 v163, 0, v15
	v_mov_b32_e32 v3, v2
	v_mov_b32_e32 v4, v2
	v_mov_b32_e32 v5, v2
	v_mov_b32_e32 v6, v2
	v_mov_b32_e32 v7, v2
	v_mov_b32_e32 v8, v2
	v_mov_b32_e32 v9, v2
	v_mov_b32_e32 v10, v2
	v_mov_b32_e32 v11, v2
	v_mov_b32_e32 v12, v2
	v_mov_b32_e32 v13, v2
	v_mov_b32_e32 v14, v2
	v_mov_b32_e32 v15, v2
	v_mov_b32_e32 v16, v2
	v_mov_b32_e32 v17, v2
	v_mov_b32_e32 v18, v2
	v_mov_b32_e32 v19, v2
	v_mov_b32_e32 v20, v2
	v_mov_b32_e32 v21, v2
	v_mov_b32_e32 v22, v2
	v_mov_b32_e32 v23, v2
	v_mov_b32_e32 v24, v2
	v_mov_b32_e32 v25, v2
	v_mov_b32_e32 v26, v2
	v_mov_b32_e32 v27, v2
	v_mov_b32_e32 v28, v2
	v_mov_b32_e32 v29, v2
	v_mov_b32_e32 v30, v2
	v_mov_b32_e32 v31, v2
	v_mov_b32_e32 v32, v2
	v_mov_b32_e32 v33, v2
	v_mov_b32_e32 v34, v2
	v_mov_b32_e32 v35, v2
	v_mov_b32_e32 v36, v2
	v_mov_b32_e32 v37, v2
	v_mov_b32_e32 v38, v2
	v_mov_b32_e32 v39, v2
	v_mov_b32_e32 v40, v2
	v_mov_b32_e32 v41, v2
	v_mov_b32_e32 v42, v2
	v_mov_b32_e32 v43, v2
	v_mov_b32_e32 v44, v2
	v_mov_b32_e32 v45, v2
	v_mov_b32_e32 v46, v2
	v_mov_b32_e32 v47, v2
	v_mov_b32_e32 v48, v2
	v_mov_b32_e32 v49, v2
	v_mov_b32_e32 v50, v2
	v_mov_b32_e32 v51, v2
	v_mov_b32_e32 v52, v2
	v_mov_b32_e32 v53, v2
	v_mov_b32_e32 v54, v2
	v_mov_b32_e32 v55, v2
	v_mov_b32_e32 v56, v2
	v_mov_b32_e32 v57, v2
	v_mov_b32_e32 v58, v2
	v_mov_b32_e32 v59, v2
	v_mov_b32_e32 v60, v2
	v_mov_b32_e32 v61, v2
	v_mov_b32_e32 v62, v2
	v_mov_b32_e32 v63, v2
	v_mov_b32_e32 v64, v2
	v_mov_b32_e32 v65, v2
	v_mov_b32_e32 v66, v2
	v_mov_b32_e32 v67, v2
	v_mov_b32_e32 v68, v2
	v_mov_b32_e32 v69, v2
	v_mov_b32_e32 v70, v2
	v_mov_b32_e32 v71, v2
	v_mov_b32_e32 v72, v2
	v_mov_b32_e32 v73, v2
	v_mov_b32_e32 v74, v2
	v_mov_b32_e32 v75, v2
	v_mov_b32_e32 v76, v2
	v_mov_b32_e32 v77, v2
	v_mov_b32_e32 v78, v2
	v_mov_b32_e32 v79, v2
	v_mov_b32_e32 v80, v2
	v_mov_b32_e32 v81, v2
	v_mov_b32_e32 v82, v2
	v_mov_b32_e32 v83, v2
	v_mov_b32_e32 v84, v2
	v_mov_b32_e32 v85, v2
	v_mov_b32_e32 v86, v2
	v_mov_b32_e32 v87, v2
	v_mov_b32_e32 v88, v2
	v_mov_b32_e32 v89, v2
	v_mov_b32_e32 v90, v2
	v_mov_b32_e32 v91, v2
	v_mov_b32_e32 v92, v2
	v_mov_b32_e32 v93, v2
	v_mov_b32_e32 v94, v2
	v_mov_b32_e32 v95, v2
	v_mov_b32_e32 v96, v2
	v_mov_b32_e32 v97, v2
	v_mov_b32_e32 v98, v2
	v_mov_b32_e32 v99, v2
	v_mov_b32_e32 v100, v2
	v_mov_b32_e32 v101, v2
	v_mov_b32_e32 v102, v2
	v_mov_b32_e32 v103, v2
	v_mov_b32_e32 v104, v2
	v_mov_b32_e32 v105, v2
	v_mov_b32_e32 v106, v2
	v_mov_b32_e32 v107, v2
	v_mov_b32_e32 v108, v2
	v_mov_b32_e32 v109, v2
	v_mov_b32_e32 v110, v2
	v_mov_b32_e32 v111, v2
	v_mov_b32_e32 v112, v2
	v_mov_b32_e32 v113, v2
	v_mov_b32_e32 v114, v2
	v_mov_b32_e32 v115, v2
	v_mov_b32_e32 v116, v2
	v_mov_b32_e32 v117, v2
	v_mov_b32_e32 v118, v2
	v_mov_b32_e32 v119, v2
	v_mov_b32_e32 v120, v2
	v_mov_b32_e32 v121, v2
	v_mov_b32_e32 v122, v2
	v_mov_b32_e32 v123, v2
	v_mov_b32_e32 v124, v2
	v_mov_b32_e32 v125, v2
	v_mov_b32_e32 v126, v2
	v_mov_b32_e32 v127, v2
	v_mov_b32_e32 v128, v2
	v_mov_b32_e32 v129, v2
	s_barrier
	v_readfirstlane_b32 s98, v0
	s_bitcmp1_b32 s98, 8
	s_cbranch_scc0 .Lkprio_7
	s_setprio 1
.Lkprio_7:
.LBB0_1914:
	s_add_u32 s38, s4, 0xf8cd0080
	s_addc_u32 s39, s5, -1
	s_cmp_lg_u32 s37, 40
	s_cselect_b32 s39, s39, 0
	s_cselect_b32 s38, s38, 0
	s_add_i32 s40, 0, 0x10000
	v_add_u32_e32 v156, s40, v162
	ds_read_b128 v[164:167], v156
	ds_read_b128 v[168:171], v156 offset:1024
	ds_read_b128 v[172:175], v156 offset:2048
	ds_read_b128 v[176:179], v156 offset:3072
	v_lshl_add_u64 v[232:233], v[148:149], 0, s[38:39]
	v_lshl_add_u64 v[156:157], v[146:147], 0, s[38:39]
	v_lshl_add_u64 v[214:215], v[150:151], 0, s[4:5]
	s_add_i32 m0, s28, 0xc000
	ds_read_b128 v[180:183], v163
	ds_read_b128 v[184:187], v163 offset:1024
	ds_read_b128 v[188:191], v163 offset:2048
	ds_read_b128 v[192:195], v163 offset:3072
	ds_read_b128 v[196:199], v163 offset:4096
	ds_read_b128 v[200:203], v163 offset:5120
	ds_read_b128 v[204:207], v163 offset:6144
	ds_read_b128 v[210:213], v163 offset:7168
	global_load_lds_dwordx4 v[214:215], off
	v_lshl_add_u64 v[214:215], v[152:153], 0, s[4:5]
	s_add_i32 m0, s28, 0xe000
	s_nop 0
	global_load_lds_dwordx4 v[214:215], off
	s_waitcnt lgkmcnt(8)
	s_barrier
	s_waitcnt lgkmcnt(7)
	v_mfma_f32_16x16x32_bf16 v[126:129], v[164:167], v[180:183], v[126:129]
	v_mfma_f32_16x16x32_bf16 v[122:125], v[172:175], v[180:183], v[122:125]
	s_waitcnt lgkmcnt(5)
	v_mfma_f32_16x16x32_bf16 v[118:121], v[164:167], v[188:191], v[118:121]
	v_mfma_f32_16x16x32_bf16 v[114:117], v[172:175], v[188:191], v[114:117]
	s_waitcnt lgkmcnt(3)
	v_mfma_f32_16x16x32_bf16 v[110:113], v[164:167], v[196:199], v[110:113]
	v_mfma_f32_16x16x32_bf16 v[106:109], v[172:175], v[196:199], v[106:109]
	s_waitcnt lgkmcnt(1)
	v_mfma_f32_16x16x32_bf16 v[102:105], v[164:167], v[204:207], v[102:105]
	v_mfma_f32_16x16x32_bf16 v[98:101], v[172:175], v[204:207], v[98:101]
	v_mfma_f32_16x16x32_bf16 v[126:129], v[168:171], v[184:187], v[126:129]
	v_mfma_f32_16x16x32_bf16 v[122:125], v[176:179], v[184:187], v[122:125]
	v_mfma_f32_16x16x32_bf16 v[118:121], v[168:171], v[192:195], v[118:121]
	v_mfma_f32_16x16x32_bf16 v[114:117], v[176:179], v[192:195], v[114:117]
	v_mfma_f32_16x16x32_bf16 v[110:113], v[168:171], v[200:203], v[110:113]
	v_mfma_f32_16x16x32_bf16 v[106:109], v[176:179], v[200:203], v[106:109]
	s_waitcnt lgkmcnt(0)
	v_mfma_f32_16x16x32_bf16 v[102:105], v[168:171], v[210:213], v[102:105]
	v_mfma_f32_16x16x32_bf16 v[98:101], v[176:179], v[210:213], v[98:101]
	s_barrier
	s_add_i32 s38, 0, 0x14000
	s_add_i32 s39, s40, s27
	v_add_u32_e32 v208, s38, v162
	v_lshl_add_u64 v[234:235], v[156:157], 0, v[130:131]
	s_mov_b32 m0, s39
	ds_read_b128 v[214:217], v208
	ds_read_b128 v[218:221], v208 offset:1024
	ds_read_b128 v[222:225], v208 offset:2048
	ds_read_b128 v[228:231], v208 offset:3072
	global_load_lds_dwordx4 v[234:235], off
	v_lshl_add_u64 v[236:237], v[156:157], 0, v[144:145]
	s_add_i32 m0, s39, 0x2000
	s_nop 0
	global_load_lds_dwordx4 v[236:237], off
	s_barrier
	s_waitcnt lgkmcnt(3)
	v_mfma_f32_16x16x32_bf16 v[94:97], v[214:217], v[180:183], v[94:97]
	s_waitcnt lgkmcnt(1)
	v_mfma_f32_16x16x32_bf16 v[90:93], v[222:225], v[180:183], v[90:93]
	v_mfma_f32_16x16x32_bf16 v[86:89], v[214:217], v[188:191], v[86:89]
	v_mfma_f32_16x16x32_bf16 v[82:85], v[222:225], v[188:191], v[82:85]
	v_mfma_f32_16x16x32_bf16 v[78:81], v[214:217], v[196:199], v[78:81]
	v_mfma_f32_16x16x32_bf16 v[74:77], v[222:225], v[196:199], v[74:77]
	v_mfma_f32_16x16x32_bf16 v[70:73], v[214:217], v[204:207], v[70:73]
	v_mfma_f32_16x16x32_bf16 v[66:69], v[222:225], v[204:207], v[66:69]
	v_mfma_f32_16x16x32_bf16 v[94:97], v[218:221], v[184:187], v[94:97]
	s_waitcnt lgkmcnt(0)
	v_mfma_f32_16x16x32_bf16 v[90:93], v[228:231], v[184:187], v[90:93]
	v_mfma_f32_16x16x32_bf16 v[86:89], v[218:221], v[192:195], v[86:89]
	v_mfma_f32_16x16x32_bf16 v[82:85], v[228:231], v[192:195], v[82:85]
	v_mfma_f32_16x16x32_bf16 v[78:81], v[218:221], v[200:203], v[78:81]
	v_mfma_f32_16x16x32_bf16 v[74:77], v[228:231], v[200:203], v[74:77]
	v_mfma_f32_16x16x32_bf16 v[70:73], v[218:221], v[210:213], v[70:73]
	v_mfma_f32_16x16x32_bf16 v[66:69], v[228:231], v[210:213], v[66:69]
	s_mov_b32 m0, s28
	v_lshl_add_u64 v[238:239], v[232:233], 0, v[130:131]
	s_barrier
	ds_read_b128 v[180:183], v163 offset:16384
	ds_read_b128 v[184:187], v163 offset:17408
	ds_read_b128 v[188:191], v163 offset:18432
	ds_read_b128 v[192:195], v163 offset:19456
	ds_read_b128 v[196:199], v163 offset:20480
	ds_read_b128 v[200:203], v163 offset:21504
	ds_read_b128 v[204:207], v163 offset:22528
	ds_read_b128 v[210:213], v163 offset:23552
	global_load_lds_dwordx4 v[238:239], off
	v_lshl_add_u64 v[240:241], v[232:233], 0, v[144:145]
	s_mov_b32 m0, s29
	s_nop 0
	global_load_lds_dwordx4 v[240:241], off
	s_barrier
	s_waitcnt lgkmcnt(7)
	v_mfma_f32_16x16x32_bf16 v[62:65], v[164:167], v[180:183], v[62:65]
	v_mfma_f32_16x16x32_bf16 v[58:61], v[172:175], v[180:183], v[58:61]
	s_waitcnt lgkmcnt(5)
	v_mfma_f32_16x16x32_bf16 v[54:57], v[164:167], v[188:191], v[54:57]
	v_mfma_f32_16x16x32_bf16 v[50:53], v[172:175], v[188:191], v[50:53]
	s_waitcnt lgkmcnt(3)
	v_mfma_f32_16x16x32_bf16 v[46:49], v[164:167], v[196:199], v[46:49]
	v_mfma_f32_16x16x32_bf16 v[42:45], v[172:175], v[196:199], v[42:45]
	s_waitcnt lgkmcnt(1)
	v_mfma_f32_16x16x32_bf16 v[38:41], v[164:167], v[204:207], v[38:41]
	v_mfma_f32_16x16x32_bf16 v[34:37], v[172:175], v[204:207], v[34:37]
	v_mfma_f32_16x16x32_bf16 v[62:65], v[168:171], v[184:187], v[62:65]
	v_mfma_f32_16x16x32_bf16 v[58:61], v[176:179], v[184:187], v[58:61]
	v_mfma_f32_16x16x32_bf16 v[54:57], v[168:171], v[192:195], v[54:57]
	v_mfma_f32_16x16x32_bf16 v[50:53], v[176:179], v[192:195], v[50:53]
	v_mfma_f32_16x16x32_bf16 v[46:49], v[168:171], v[200:203], v[46:49]
	v_mfma_f32_16x16x32_bf16 v[42:45], v[176:179], v[200:203], v[42:45]
	s_waitcnt lgkmcnt(0)
	v_mfma_f32_16x16x32_bf16 v[38:41], v[168:171], v[210:213], v[38:41]
	v_mfma_f32_16x16x32_bf16 v[34:37], v[176:179], v[210:213], v[34:37]
	s_barrier
	v_lshl_add_u64 v[164:165], v[156:157], 0, s[16:17]
	s_add_i32 s38, s38, s27
	v_lshl_add_u64 v[166:167], v[164:165], 0, v[130:131]
	s_mov_b32 m0, s38
	v_lshl_add_u64 v[164:165], v[164:165], 0, v[144:145]
	global_load_lds_dwordx4 v[166:167], off
	s_add_i32 m0, s38, 0x2000
	s_nop 0
	global_load_lds_dwordx4 v[164:165], off
	s_waitcnt vmcnt(6)
	s_barrier
	v_mfma_f32_16x16x32_bf16 v[30:33], v[214:217], v[180:183], v[30:33]
	v_mfma_f32_16x16x32_bf16 v[26:29], v[222:225], v[180:183], v[26:29]
	v_mfma_f32_16x16x32_bf16 v[22:25], v[214:217], v[188:191], v[22:25]
	v_mfma_f32_16x16x32_bf16 v[18:21], v[222:225], v[188:191], v[18:21]
	v_mfma_f32_16x16x32_bf16 v[14:17], v[214:217], v[196:199], v[14:17]
	v_mfma_f32_16x16x32_bf16 v[10:13], v[222:225], v[196:199], v[10:13]
	v_mfma_f32_16x16x32_bf16 v[6:9], v[214:217], v[204:207], v[6:9]
	v_mfma_f32_16x16x32_bf16 v[2:5], v[222:225], v[204:207], v[2:5]
	v_mfma_f32_16x16x32_bf16 v[30:33], v[218:221], v[184:187], v[30:33]
	v_mfma_f32_16x16x32_bf16 v[26:29], v[228:231], v[184:187], v[26:29]
	v_mfma_f32_16x16x32_bf16 v[22:25], v[218:221], v[192:195], v[22:25]
	v_mfma_f32_16x16x32_bf16 v[18:21], v[228:231], v[192:195], v[18:21]
	v_mfma_f32_16x16x32_bf16 v[14:17], v[218:221], v[200:203], v[14:17]
	v_mfma_f32_16x16x32_bf16 v[10:13], v[228:231], v[200:203], v[10:13]
	v_mfma_f32_16x16x32_bf16 v[6:9], v[218:221], v[210:213], v[6:9]
	v_mfma_f32_16x16x32_bf16 v[2:5], v[228:231], v[210:213], v[2:5]
	s_add_i32 s38, 0, 0x18000
	v_add_u32_e32 v176, s38, v162
	s_barrier
	ds_read_b128 v[164:167], v176
	ds_read_b128 v[168:171], v176 offset:1024
	ds_read_b128 v[172:175], v176 offset:2048
	ds_read_b128 v[176:179], v176 offset:3072
	v_lshl_add_u64 v[214:215], v[232:233], 0, s[16:17]
	s_mov_b32 m0, s31
	v_lshl_add_u64 v[216:217], v[214:215], 0, v[130:131]
	ds_read_b128 v[180:183], v163 offset:32768
	ds_read_b128 v[184:187], v163 offset:33792
	ds_read_b128 v[188:191], v163 offset:34816
	ds_read_b128 v[192:195], v163 offset:35840
	ds_read_b128 v[196:199], v163 offset:36864
	ds_read_b128 v[200:203], v163 offset:37888
	ds_read_b128 v[204:207], v163 offset:38912
	ds_read_b128 v[210:213], v163 offset:39936
	global_load_lds_dwordx4 v[216:217], off
	v_lshl_add_u64 v[214:215], v[214:215], 0, v[144:145]
	s_mov_b32 m0, s34
	s_nop 0
	global_load_lds_dwordx4 v[214:215], off
	s_waitcnt lgkmcnt(8)
	s_barrier
	s_waitcnt lgkmcnt(7)
	v_mfma_f32_16x16x32_bf16 v[126:129], v[164:167], v[180:183], v[126:129]
	v_mfma_f32_16x16x32_bf16 v[122:125], v[172:175], v[180:183], v[122:125]
	s_waitcnt lgkmcnt(5)
	v_mfma_f32_16x16x32_bf16 v[118:121], v[164:167], v[188:191], v[118:121]
	v_mfma_f32_16x16x32_bf16 v[114:117], v[172:175], v[188:191], v[114:117]
	s_waitcnt lgkmcnt(3)
	v_mfma_f32_16x16x32_bf16 v[110:113], v[164:167], v[196:199], v[110:113]
	v_mfma_f32_16x16x32_bf16 v[106:109], v[172:175], v[196:199], v[106:109]
	s_waitcnt lgkmcnt(1)
	v_mfma_f32_16x16x32_bf16 v[102:105], v[164:167], v[204:207], v[102:105]
	v_mfma_f32_16x16x32_bf16 v[98:101], v[172:175], v[204:207], v[98:101]
	v_mfma_f32_16x16x32_bf16 v[126:129], v[168:171], v[184:187], v[126:129]
	v_mfma_f32_16x16x32_bf16 v[122:125], v[176:179], v[184:187], v[122:125]
	v_mfma_f32_16x16x32_bf16 v[118:121], v[168:171], v[192:195], v[118:121]
	v_mfma_f32_16x16x32_bf16 v[114:117], v[176:179], v[192:195], v[114:117]
	v_mfma_f32_16x16x32_bf16 v[110:113], v[168:171], v[200:203], v[110:113]
	v_mfma_f32_16x16x32_bf16 v[106:109], v[176:179], v[200:203], v[106:109]
	s_waitcnt lgkmcnt(0)
	v_mfma_f32_16x16x32_bf16 v[102:105], v[168:171], v[210:213], v[102:105]
	v_mfma_f32_16x16x32_bf16 v[98:101], v[176:179], v[210:213], v[98:101]
	s_barrier
	s_add_i32 s39, 0, 0x1c000
	s_add_i32 s38, s38, s27
	v_add_u32_e32 v208, s39, v162
	v_lshl_add_u64 v[232:233], v[234:235], 0, s[18:19]
	s_mov_b32 m0, s38
	ds_read_b128 v[214:217], v208
	ds_read_b128 v[218:221], v208 offset:1024
	ds_read_b128 v[222:225], v208 offset:2048
	ds_read_b128 v[228:231], v208 offset:3072
	global_load_lds_dwordx4 v[232:233], off
	v_lshl_add_u64 v[232:233], v[236:237], 0, s[18:19]
	s_add_i32 m0, s38, 0x2000
	s_nop 0
	global_load_lds_dwordx4 v[232:233], off
	s_barrier
	s_waitcnt lgkmcnt(3)
	v_mfma_f32_16x16x32_bf16 v[94:97], v[214:217], v[180:183], v[94:97]
	s_waitcnt lgkmcnt(1)
	v_mfma_f32_16x16x32_bf16 v[90:93], v[222:225], v[180:183], v[90:93]
	v_mfma_f32_16x16x32_bf16 v[86:89], v[214:217], v[188:191], v[86:89]
	v_mfma_f32_16x16x32_bf16 v[82:85], v[222:225], v[188:191], v[82:85]
	v_mfma_f32_16x16x32_bf16 v[78:81], v[214:217], v[196:199], v[78:81]
	v_mfma_f32_16x16x32_bf16 v[74:77], v[222:225], v[196:199], v[74:77]
	v_mfma_f32_16x16x32_bf16 v[70:73], v[214:217], v[204:207], v[70:73]
	v_mfma_f32_16x16x32_bf16 v[66:69], v[222:225], v[204:207], v[66:69]
	v_mfma_f32_16x16x32_bf16 v[94:97], v[218:221], v[184:187], v[94:97]
	s_waitcnt lgkmcnt(0)
	v_mfma_f32_16x16x32_bf16 v[90:93], v[228:231], v[184:187], v[90:93]
	v_mfma_f32_16x16x32_bf16 v[86:89], v[218:221], v[192:195], v[86:89]
	v_mfma_f32_16x16x32_bf16 v[82:85], v[228:231], v[192:195], v[82:85]
	v_mfma_f32_16x16x32_bf16 v[78:81], v[218:221], v[200:203], v[78:81]
	v_mfma_f32_16x16x32_bf16 v[74:77], v[228:231], v[200:203], v[74:77]
	v_mfma_f32_16x16x32_bf16 v[70:73], v[218:221], v[210:213], v[70:73]
	v_mfma_f32_16x16x32_bf16 v[66:69], v[228:231], v[210:213], v[66:69]
	s_mov_b32 m0, s35
	v_lshl_add_u64 v[232:233], v[238:239], 0, s[18:19]
	s_barrier
	ds_read_b128 v[180:183], v163 offset:49152
	ds_read_b128 v[184:187], v163 offset:50176
	ds_read_b128 v[188:191], v163 offset:51200
	ds_read_b128 v[192:195], v163 offset:52224
	ds_read_b128 v[196:199], v163 offset:53248
	ds_read_b128 v[200:203], v163 offset:54272
	ds_read_b128 v[204:207], v163 offset:55296
	ds_read_b128 v[210:213], v163 offset:56320
	global_load_lds_dwordx4 v[232:233], off
	v_lshl_add_u64 v[232:233], v[240:241], 0, s[18:19]
	s_mov_b32 m0, s36
	s_nop 0
	global_load_lds_dwordx4 v[232:233], off
	s_barrier
	s_waitcnt lgkmcnt(7)
	v_mfma_f32_16x16x32_bf16 v[62:65], v[164:167], v[180:183], v[62:65]
	v_mfma_f32_16x16x32_bf16 v[58:61], v[172:175], v[180:183], v[58:61]
	s_waitcnt lgkmcnt(5)
	v_mfma_f32_16x16x32_bf16 v[54:57], v[164:167], v[188:191], v[54:57]
	v_mfma_f32_16x16x32_bf16 v[50:53], v[172:175], v[188:191], v[50:53]
	s_waitcnt lgkmcnt(3)
	v_mfma_f32_16x16x32_bf16 v[46:49], v[164:167], v[196:199], v[46:49]
	v_mfma_f32_16x16x32_bf16 v[42:45], v[172:175], v[196:199], v[42:45]
	s_waitcnt lgkmcnt(1)
	v_mfma_f32_16x16x32_bf16 v[38:41], v[164:167], v[204:207], v[38:41]
	v_mfma_f32_16x16x32_bf16 v[34:37], v[172:175], v[204:207], v[34:37]
	v_mfma_f32_16x16x32_bf16 v[62:65], v[168:171], v[184:187], v[62:65]
	v_mfma_f32_16x16x32_bf16 v[58:61], v[176:179], v[184:187], v[58:61]
	v_mfma_f32_16x16x32_bf16 v[54:57], v[168:171], v[192:195], v[54:57]
	v_mfma_f32_16x16x32_bf16 v[50:53], v[176:179], v[192:195], v[50:53]
	v_mfma_f32_16x16x32_bf16 v[46:49], v[168:171], v[200:203], v[46:49]
	v_mfma_f32_16x16x32_bf16 v[42:45], v[176:179], v[200:203], v[42:45]
	s_waitcnt lgkmcnt(0)
	v_mfma_f32_16x16x32_bf16 v[38:41], v[168:171], v[210:213], v[38:41]
	v_mfma_f32_16x16x32_bf16 v[34:37], v[176:179], v[210:213], v[34:37]
	s_barrier
	v_lshl_add_u64 v[156:157], v[156:157], 0, s[20:21]
	s_add_i32 s38, s39, s27
	v_lshl_add_u64 v[164:165], v[156:157], 0, v[130:131]
	s_mov_b32 m0, s38
	v_lshl_add_u64 v[156:157], v[156:157], 0, v[144:145]
	global_load_lds_dwordx4 v[164:165], off
	s_add_i32 m0, s38, 0x2000
	s_nop 0
	global_load_lds_dwordx4 v[156:157], off
	s_waitcnt vmcnt(6)
	s_barrier
	v_mfma_f32_16x16x32_bf16 v[30:33], v[214:217], v[180:183], v[30:33]
	v_mfma_f32_16x16x32_bf16 v[26:29], v[222:225], v[180:183], v[26:29]
	v_mfma_f32_16x16x32_bf16 v[22:25], v[214:217], v[188:191], v[22:25]
	v_mfma_f32_16x16x32_bf16 v[18:21], v[222:225], v[188:191], v[18:21]
	v_mfma_f32_16x16x32_bf16 v[14:17], v[214:217], v[196:199], v[14:17]
	v_mfma_f32_16x16x32_bf16 v[10:13], v[222:225], v[196:199], v[10:13]
	v_mfma_f32_16x16x32_bf16 v[6:9], v[214:217], v[204:207], v[6:9]
	v_mfma_f32_16x16x32_bf16 v[2:5], v[222:225], v[204:207], v[2:5]
	v_mfma_f32_16x16x32_bf16 v[30:33], v[218:221], v[184:187], v[30:33]
	v_mfma_f32_16x16x32_bf16 v[26:29], v[228:231], v[184:187], v[26:29]
	v_mfma_f32_16x16x32_bf16 v[22:25], v[218:221], v[192:195], v[22:25]
	v_mfma_f32_16x16x32_bf16 v[18:21], v[228:231], v[192:195], v[18:21]
	v_mfma_f32_16x16x32_bf16 v[14:17], v[218:221], v[200:203], v[14:17]
	v_mfma_f32_16x16x32_bf16 v[10:13], v[228:231], v[200:203], v[10:13]
	v_mfma_f32_16x16x32_bf16 v[6:9], v[218:221], v[210:213], v[6:9]
	v_mfma_f32_16x16x32_bf16 v[2:5], v[228:231], v[210:213], v[2:5]
	s_add_i32 s37, s37, 2
	s_add_u32 s4, s4, 0x100
	s_addc_u32 s5, s5, 0
	s_cmp_lt_u32 s37, 42
	s_barrier
	s_cbranch_scc1 .LBB0_1914
	s_setprio 0
	s_waitcnt vmcnt(0)
	s_cmpk_gt_u32 s26, 0xff
	s_cbranch_scc1 .LBB0_1917
	s_barrier
